# GEMM2/5 skew applied after the first tile's loads are issued (4 us): the late half's first-tile load latency is covered by its sleep
# speedup vs baseline: 1.0004x; 1.0004x over previous
.LBB0_623:
	s_cmp_lt_i32 s64, 5
	s_cselect_b64 s[8:9], -1, 0
	s_and_b64 s[0:1], s[8:9], s[0:1]
	s_cmpk_lt_i32 s2, 0x300
	s_cselect_b64 s[6:7], -1, 0
	s_and_b64 s[0:1], s[0:1], s[6:7]
	s_andn2_b64 vcc, exec, s[0:1]
	s_cbranch_vccnz .LBB0_632
	s_and_b32 s0, s62, 7
	s_cmp_lg_u32 s0, 0
	s_cselect_b64 s[0:1], -1, 0
	s_ashr_i32 s18, s62, 3
	s_add_u32 s19, s96, 0x720000
	s_addc_u32 s20, s97, 0
	s_add_u32 s21, s96, 0x13a0000
	s_addc_u32 s22, s97, 0
	s_add_u32 s10, s96, 0x43a0000
	s_addc_u32 s11, s97, 0
	s_add_u32 s23, s96, 0xecc4000
	s_addc_u32 s24, s97, 0
	s_abs_i32 s25, s62
	v_cvt_f32_u32_e32 v2, s25
	v_cndmask_b32_e64 v1, 0, 1, s[0:1]
	s_sub_i32 s0, 0, s25
	s_mov_b64 s[12:13], s[36:37]
	v_rcp_iflag_f32_e32 v2, v2
	v_mbcnt_hi_u32_b32 v89, -1, v213
	s_lshl_b32 s28, s62, 3
	s_mov_b64 s[14:15], s[38:39]
	v_mul_f32_e32 v2, 0x4f7ffffe, v2
	v_cvt_u32_f32_e32 v2, v2
	s_ashr_i32 s26, s62, 31
	s_sub_i32 s27, 0, s62
	s_lshl_b32 s29, s2, 3
	v_readfirstlane_b32 s1, v2
	s_mul_i32 s0, s0, s1
	s_mul_hi_u32 s0, s1, s0
	v_and_b32_e32 v2, 64, v89
	s_sub_i32 s30, 0, s28
	s_add_i32 s31, s1, s0
	v_cmp_ne_u32_e64 s[0:1], 1, v1
	v_mov_b32_e32 v67, 0
	s_movk_i32 s34, 0x90
	s_mov_b32 s35, 0xfffffc0
	s_mov_b32 s36, 0x20000
	s_mov_b32 s37, 0x40000
	s_mov_b32 s38, 0x60000
	s_movk_i32 s39, 0xff00
	s_movk_i32 s40, 0x410
	s_movk_i32 s41, 0x2000
	v_mov_b32_e32 v1, s15
	v_mov_b32_e32 v86, s13
	v_mov_b32_e32 v87, s14
	v_mov_b32_e32 v88, s12
	s_movk_i32 s42, 0x1000
	v_add_u32_e32 v90, 64, v2
	v_xor_b32_e32 v91, 32, v89
	v_xor_b32_e32 v92, 16, v89
	v_xor_b32_e32 v93, 8, v89
	v_xor_b32_e32 v94, 4, v89
	v_xor_b32_e32 v95, 2, v89
	v_xor_b32_e32 v96, 1, v89
	s_mov_b32 s101, 1
	s_mov_b32 s43, s2
	s_branch .LBB0_626

.LBB0_629:
	s_ashr_i32 s4, s3, 31
	s_lshr_b32 s4, s4, 30
	s_add_i32 s4, s3, s4
	s_and_b32 s4, s4, 0xfffffc
	s_sub_i32 s3, s3, s4
	s_lshl_b32 s4, s3, 8
	s_ashr_i32 s5, s4, 31
	v_mov_b32_e32 v50, v212
	s_lshl_b32 s12, s14, 7
	s_lshl_b64 s[16:17], s[4:5], 11
	s_add_u32 s16, s19, s16
	v_ashrrev_i32_e32 v26, 3, v50
	v_ashrrev_i32_e32 v27, 31, v26
	s_addc_u32 s17, s20, s17
	v_lshlrev_b64 v[2:3], 11, v[26:27]
	v_lshlrev_b32_e32 v6, 4, v50
	v_lshl_add_u64 v[4:5], s[16:17], 0, v[2:3]
	v_and_b32_e32 v66, 0x70, v6
	v_lshl_add_u64 v[74:75], v[4:5], 0, v[66:67]
	v_add_co_u32_e32 v78, vcc, s36, v74
	s_ashr_i32 s13, s12, 31
	s_nop 0
	v_addc_co_u32_e32 v79, vcc, 0, v75, vcc
	s_lshl_b64 s[44:45], s[12:13], 11
	v_add_co_u32_e32 v80, vcc, s37, v74
	s_add_u32 s44, s21, s44
	s_nop 0
	v_addc_co_u32_e32 v81, vcc, 0, v75, vcc
	s_addc_u32 s45, s22, s45
	v_add_co_u32_e32 v82, vcc, s38, v74
	v_lshl_add_u64 v[2:3], s[44:45], 0, v[2:3]
	s_nop 0
	v_addc_co_u32_e32 v83, vcc, 0, v75, vcc
	v_lshl_add_u64 v[76:77], v[2:3], 0, v[66:67]
	global_load_dwordx4 v[2:5], v[74:75], off
	global_load_dwordx4 v[6:9], v[78:79], off
	global_load_dwordx4 v[10:13], v[80:81], off
	global_load_dwordx4 v[14:17], v[82:83], off
	global_load_dwordx4 v[18:21], v[76:77], off
	v_add_co_u32_e32 v84, vcc, s36, v76
	v_mad_u64_u32 v[72:73], s[16:17], v26, s34, v[66:67]
	s_nop 0
	v_addc_co_u32_e32 v85, vcc, 0, v77, vcc
	global_load_dwordx4 v[22:25], v[84:85], off
	global_load_dwordx4 v[26:29], v[74:75], off offset:128
	global_load_dwordx4 v[30:33], v[78:79], off offset:128
	global_load_dwordx4 v[34:37], v[82:83], off offset:128
	global_load_dwordx4 v[98:101], v[78:79], off offset:256
	global_load_dwordx4 v[38:41], v[80:81], off offset:128
	global_load_dwordx4 v[102:105], v[80:81], off offset:256
	global_load_dwordx4 v[106:109], v[74:75], off offset:256
	global_load_dwordx4 v[42:45], v[76:77], off offset:128
	global_load_dwordx4 v[110:113], v[76:77], off offset:256
	global_load_dwordx4 v[114:117], v[82:83], off offset:256
	global_load_dwordx4 v[46:49], v[84:85], off offset:128
	global_load_dwordx4 v[118:121], v[84:85], off offset:256
	s_cmp_eq_u32 s101, 0
	s_cbranch_scc1 .Lskew_done_g2
	s_mov_b32 s101, 0
	s_bitcmp1_b32 s2, 3
	s_cbranch_scc0 .Lskew_done_g2
	s_memrealtime s[98:99]
	s_waitcnt lgkmcnt(0)
	s_add_u32 s100, s98, 400

.Lskew_done_g2:
	v_and_b32_e32 v68, 63, v69
	v_add_u32_e32 v97, 0x12000, v72
	s_waitcnt vmcnt(17)
	ds_write_b128 v72, v[2:5]
	s_waitcnt vmcnt(16)
	ds_write_b128 v72, v[6:9] offset:9216
	s_waitcnt vmcnt(15)
	ds_write_b128 v72, v[10:13] offset:18432
	s_waitcnt vmcnt(14)
	ds_write_b128 v72, v[14:17] offset:27648
	s_waitcnt vmcnt(13)
	ds_write_b128 v72, v[18:21] offset:36864
	s_waitcnt vmcnt(12)
	ds_write_b128 v72, v[22:25] offset:46080
	s_waitcnt lgkmcnt(0)
	s_barrier
	global_load_dwordx4 v[122:125], v[78:79], off offset:384
	global_load_dwordx4 v[126:129], v[80:81], off offset:384
	global_load_dwordx4 v[130:133], v[74:75], off offset:384
	global_load_dwordx4 v[134:137], v[76:77], off offset:384
	global_load_dwordx4 v[138:141], v[82:83], off offset:384
	global_load_dwordx4 v[142:145], v[84:85], off offset:384
	v_and_b32_e32 v2, 31, v50
	v_lshrrev_b32_e32 v3, 1, v50
	v_and_or_b32 v4, v3, s35, v2
	v_and_b32_e32 v2, 16, v3
	v_and_b32_e32 v3, 0x5f, v50
	v_mad_u32_u24 v73, v3, s34, v2
	v_add_u32_e32 v66, 0x12000, v73
	s_waitcnt vmcnt(17)
	ds_write_b128 v97, v[26:29]
	s_waitcnt vmcnt(16)
	ds_write_b128 v97, v[30:33] offset:9216
	s_waitcnt vmcnt(13)
	ds_write_b128 v97, v[38:41] offset:18432
	ds_write_b128 v97, v[34:37] offset:27648
	s_waitcnt vmcnt(10)
	ds_write_b128 v97, v[42:45] offset:36864
	s_waitcnt vmcnt(7)
	ds_write_b128 v97, v[46:49] offset:46080
	v_mad_u64_u32 v[70:71], s[16:17], v4, s34, v[2:3]
	ds_read_b128 v[2:5], v73 offset:36864
	ds_read_b128 v[146:149], v73 offset:36896
	ds_read_b128 v[6:9], v73 offset:41472
	ds_read_b128 v[150:153], v73 offset:41504
	ds_read_b128 v[10:13], v70
	ds_read_b128 v[154:157], v70 offset:32
	ds_read_b128 v[14:17], v70 offset:4608
	ds_read_b128 v[158:161], v70 offset:4640
	s_setprio 1
	s_waitcnt lgkmcnt(3)
	v_mfma_f32_32x32x16_bf16 v[50:65], v[10:13], v[2:5], 0
	v_mfma_f32_32x32x16_bf16 v[18:33], v[10:13], v[6:9], 0
	s_waitcnt lgkmcnt(1)
	v_mfma_f32_32x32x16_bf16 v[34:49], v[14:17], v[2:5], 0
	v_mfma_f32_32x32x16_bf16 v[2:17], v[14:17], v[6:9], 0
	s_setprio 0
	ds_read_b128 v[162:165], v73 offset:36928
	ds_read_b128 v[166:169], v73 offset:41536
	ds_read_b128 v[170:173], v70 offset:64
	ds_read_b128 v[174:177], v70 offset:4672
	s_setprio 1
	v_mfma_f32_32x32x16_bf16 v[50:65], v[154:157], v[146:149], v[50:65]
	s_waitcnt lgkmcnt(4)
	v_mfma_f32_32x32x16_bf16 v[2:17], v[158:161], v[150:153], v[2:17]
	v_mfma_f32_32x32x16_bf16 v[18:33], v[154:157], v[150:153], v[18:33]
	v_mfma_f32_32x32x16_bf16 v[34:49], v[158:161], v[146:149], v[34:49]
	s_setprio 0
	ds_read_b128 v[146:149], v73 offset:36960
	ds_read_b128 v[150:153], v73 offset:41568
	ds_read_b128 v[154:157], v70 offset:96
	ds_read_b128 v[158:161], v70 offset:4704
	s_setprio 1
	s_waitcnt lgkmcnt(5)
	v_mfma_f32_32x32x16_bf16 v[50:65], v[170:173], v[162:165], v[50:65]
	s_waitcnt lgkmcnt(4)
	v_mfma_f32_32x32x16_bf16 v[2:17], v[174:177], v[166:169], v[2:17]
	v_mfma_f32_32x32x16_bf16 v[18:33], v[170:173], v[166:169], v[18:33]
	v_mfma_f32_32x32x16_bf16 v[34:49], v[174:177], v[162:165], v[34:49]
	s_setprio 0
	s_setprio 1
	s_waitcnt lgkmcnt(1)
	v_mfma_f32_32x32x16_bf16 v[50:65], v[154:157], v[146:149], v[50:65]
	s_waitcnt lgkmcnt(0)
	v_mfma_f32_32x32x16_bf16 v[2:17], v[158:161], v[150:153], v[2:17]
	v_mfma_f32_32x32x16_bf16 v[18:33], v[154:157], v[150:153], v[18:33]
	v_mfma_f32_32x32x16_bf16 v[34:49], v[158:161], v[146:149], v[34:49]
	s_setprio 0
	s_barrier
	global_load_dwordx4 v[146:149], v[78:79], off offset:512
	global_load_dwordx4 v[150:153], v[80:81], off offset:512
	global_load_dwordx4 v[154:157], v[74:75], off offset:512
	global_load_dwordx4 v[158:161], v[76:77], off offset:512
	global_load_dwordx4 v[162:165], v[82:83], off offset:512
	global_load_dwordx4 v[166:169], v[84:85], off offset:512
	ds_write_b128 v72, v[106:109]
	ds_write_b128 v72, v[98:101] offset:9216
	ds_write_b128 v72, v[102:105] offset:18432
	ds_write_b128 v72, v[114:117] offset:27648
	ds_write_b128 v72, v[110:113] offset:36864
	s_waitcnt vmcnt(12)
	ds_write_b128 v72, v[118:121] offset:46080
	v_add_u32_e32 v71, 0x12000, v70
	ds_read_b128 v[98:101], v66 offset:36864
	ds_read_b128 v[102:105], v66 offset:36896
	ds_read_b128 v[106:109], v66 offset:41472
	ds_read_b128 v[110:113], v66 offset:41504
	ds_read_b128 v[114:117], v71
	ds_read_b128 v[118:121], v71 offset:32
	ds_read_b128 v[170:173], v71 offset:4608
	ds_read_b128 v[174:177], v71 offset:4640
	s_setprio 1
	s_waitcnt lgkmcnt(3)
	v_mfma_f32_32x32x16_bf16 v[50:65], v[114:117], v[98:101], v[50:65]
	s_waitcnt lgkmcnt(1)
	v_mfma_f32_32x32x16_bf16 v[2:17], v[170:173], v[106:109], v[2:17]
	v_mfma_f32_32x32x16_bf16 v[18:33], v[114:117], v[106:109], v[18:33]
	v_mfma_f32_32x32x16_bf16 v[34:49], v[170:173], v[98:101], v[34:49]
	s_setprio 0
	ds_read_b128 v[98:101], v66 offset:36928
	ds_read_b128 v[106:109], v66 offset:41536
	ds_read_b128 v[114:117], v71 offset:64
	ds_read_b128 v[170:173], v71 offset:4672
	s_setprio 1
	v_mfma_f32_32x32x16_bf16 v[50:65], v[118:121], v[102:105], v[50:65]
	s_waitcnt lgkmcnt(4)
	v_mfma_f32_32x32x16_bf16 v[2:17], v[174:177], v[110:113], v[2:17]
	v_mfma_f32_32x32x16_bf16 v[18:33], v[118:121], v[110:113], v[18:33]
	v_mfma_f32_32x32x16_bf16 v[34:49], v[174:177], v[102:105], v[34:49]
	s_setprio 0
	ds_read_b128 v[102:105], v66 offset:36960
	ds_read_b128 v[110:113], v66 offset:41568
	ds_read_b128 v[118:121], v71 offset:96
	ds_read_b128 v[174:177], v71 offset:4704
	s_setprio 1
	s_waitcnt lgkmcnt(5)
	v_mfma_f32_32x32x16_bf16 v[50:65], v[114:117], v[98:101], v[50:65]
	s_waitcnt lgkmcnt(4)
	v_mfma_f32_32x32x16_bf16 v[2:17], v[170:173], v[106:109], v[2:17]
	v_mfma_f32_32x32x16_bf16 v[18:33], v[114:117], v[106:109], v[18:33]
	v_mfma_f32_32x32x16_bf16 v[34:49], v[170:173], v[98:101], v[34:49]
	s_setprio 0
	s_setprio 1
	s_waitcnt lgkmcnt(1)
	v_mfma_f32_32x32x16_bf16 v[50:65], v[118:121], v[102:105], v[50:65]
	s_waitcnt lgkmcnt(0)
	v_mfma_f32_32x32x16_bf16 v[2:17], v[174:177], v[110:113], v[2:17]
	v_mfma_f32_32x32x16_bf16 v[18:33], v[118:121], v[110:113], v[18:33]
	v_mfma_f32_32x32x16_bf16 v[34:49], v[174:177], v[102:105], v[34:49]
	s_setprio 0
	s_barrier
	global_load_dwordx4 v[98:101], v[78:79], off offset:640
	global_load_dwordx4 v[102:105], v[80:81], off offset:640
	global_load_dwordx4 v[106:109], v[74:75], off offset:640
	global_load_dwordx4 v[110:113], v[76:77], off offset:640
	global_load_dwordx4 v[114:117], v[82:83], off offset:640
	global_load_dwordx4 v[118:121], v[84:85], off offset:640
	s_waitcnt vmcnt(15)
	ds_write_b128 v97, v[130:133]
	ds_write_b128 v97, v[122:125] offset:9216
	ds_write_b128 v97, v[126:129] offset:18432
	s_waitcnt vmcnt(13)
	ds_write_b128 v97, v[138:141] offset:27648
	ds_write_b128 v97, v[134:137] offset:36864
	s_waitcnt vmcnt(12)
	ds_write_b128 v97, v[142:145] offset:46080
	ds_read_b128 v[122:125], v73 offset:36864
	ds_read_b128 v[126:129], v73 offset:36896
	ds_read_b128 v[130:133], v73 offset:41472
	ds_read_b128 v[134:137], v73 offset:41504
	ds_read_b128 v[138:141], v70
	ds_read_b128 v[142:145], v70 offset:32
	ds_read_b128 v[170:173], v70 offset:4608
	ds_read_b128 v[174:177], v70 offset:4640
	s_setprio 1
	s_waitcnt lgkmcnt(3)
	v_mfma_f32_32x32x16_bf16 v[50:65], v[138:141], v[122:125], v[50:65]
	s_waitcnt lgkmcnt(1)
	v_mfma_f32_32x32x16_bf16 v[2:17], v[170:173], v[130:133], v[2:17]
	v_mfma_f32_32x32x16_bf16 v[18:33], v[138:141], v[130:133], v[18:33]
	v_mfma_f32_32x32x16_bf16 v[34:49], v[170:173], v[122:125], v[34:49]
	s_setprio 0
	ds_read_b128 v[122:125], v73 offset:36928
	ds_read_b128 v[130:133], v73 offset:41536
	ds_read_b128 v[138:141], v70 offset:64
	ds_read_b128 v[170:173], v70 offset:4672
	s_setprio 1
	v_mfma_f32_32x32x16_bf16 v[50:65], v[142:145], v[126:129], v[50:65]
	s_waitcnt lgkmcnt(4)
	v_mfma_f32_32x32x16_bf16 v[2:17], v[174:177], v[134:137], v[2:17]
	v_mfma_f32_32x32x16_bf16 v[18:33], v[142:145], v[134:137], v[18:33]
	v_mfma_f32_32x32x16_bf16 v[34:49], v[174:177], v[126:129], v[34:49]
	s_setprio 0
	ds_read_b128 v[126:129], v73 offset:36960
	ds_read_b128 v[134:137], v73 offset:41568
	ds_read_b128 v[142:145], v70 offset:96
	ds_read_b128 v[174:177], v70 offset:4704
	s_setprio 1
	s_waitcnt lgkmcnt(5)
	v_mfma_f32_32x32x16_bf16 v[50:65], v[138:141], v[122:125], v[50:65]
	s_waitcnt lgkmcnt(4)
	v_mfma_f32_32x32x16_bf16 v[2:17], v[170:173], v[130:133], v[2:17]
	v_mfma_f32_32x32x16_bf16 v[18:33], v[138:141], v[130:133], v[18:33]
	v_mfma_f32_32x32x16_bf16 v[34:49], v[170:173], v[122:125], v[34:49]
	s_setprio 0
	s_setprio 1
	s_waitcnt lgkmcnt(1)
	v_mfma_f32_32x32x16_bf16 v[50:65], v[142:145], v[126:129], v[50:65]
	s_waitcnt lgkmcnt(0)
	v_mfma_f32_32x32x16_bf16 v[2:17], v[174:177], v[134:137], v[2:17]
	v_mfma_f32_32x32x16_bf16 v[18:33], v[142:145], v[134:137], v[18:33]
	v_mfma_f32_32x32x16_bf16 v[34:49], v[174:177], v[126:129], v[34:49]
	s_setprio 0
	s_barrier
	global_load_dwordx4 v[122:125], v[78:79], off offset:768
	global_load_dwordx4 v[126:129], v[80:81], off offset:768
	global_load_dwordx4 v[130:133], v[74:75], off offset:768
	global_load_dwordx4 v[134:137], v[76:77], off offset:768
	global_load_dwordx4 v[138:141], v[82:83], off offset:768
	global_load_dwordx4 v[142:145], v[84:85], off offset:768
	s_waitcnt vmcnt(15)
	ds_write_b128 v72, v[154:157]
	ds_write_b128 v72, v[146:149] offset:9216
	ds_write_b128 v72, v[150:153] offset:18432
	s_waitcnt vmcnt(13)
	ds_write_b128 v72, v[162:165] offset:27648
	ds_write_b128 v72, v[158:161] offset:36864
	s_waitcnt vmcnt(12)
	ds_write_b128 v72, v[166:169] offset:46080
	ds_read_b128 v[146:149], v66 offset:36864
	ds_read_b128 v[150:153], v66 offset:36896
	ds_read_b128 v[154:157], v66 offset:41472
	ds_read_b128 v[158:161], v66 offset:41504
	ds_read_b128 v[162:165], v71
	ds_read_b128 v[166:169], v71 offset:32
	ds_read_b128 v[170:173], v71 offset:4608
	ds_read_b128 v[174:177], v71 offset:4640
	s_setprio 1
	s_waitcnt lgkmcnt(3)
	v_mfma_f32_32x32x16_bf16 v[50:65], v[162:165], v[146:149], v[50:65]
	s_waitcnt lgkmcnt(1)
	v_mfma_f32_32x32x16_bf16 v[2:17], v[170:173], v[154:157], v[2:17]
	v_mfma_f32_32x32x16_bf16 v[18:33], v[162:165], v[154:157], v[18:33]
	v_mfma_f32_32x32x16_bf16 v[34:49], v[170:173], v[146:149], v[34:49]
	s_setprio 0
	ds_read_b128 v[146:149], v66 offset:36928
	ds_read_b128 v[154:157], v66 offset:41536
	ds_read_b128 v[162:165], v71 offset:64
	ds_read_b128 v[170:173], v71 offset:4672
	s_setprio 1
	v_mfma_f32_32x32x16_bf16 v[50:65], v[166:169], v[150:153], v[50:65]
	s_waitcnt lgkmcnt(4)
	v_mfma_f32_32x32x16_bf16 v[2:17], v[174:177], v[158:161], v[2:17]
	v_mfma_f32_32x32x16_bf16 v[18:33], v[166:169], v[158:161], v[18:33]
	v_mfma_f32_32x32x16_bf16 v[34:49], v[174:177], v[150:153], v[34:49]
	s_setprio 0
	ds_read_b128 v[150:153], v66 offset:36960
	ds_read_b128 v[158:161], v66 offset:41568
	ds_read_b128 v[166:169], v71 offset:96
	ds_read_b128 v[174:177], v71 offset:4704
	s_setprio 1
	s_waitcnt lgkmcnt(5)
	v_mfma_f32_32x32x16_bf16 v[50:65], v[162:165], v[146:149], v[50:65]
	s_waitcnt lgkmcnt(4)
	v_mfma_f32_32x32x16_bf16 v[2:17], v[170:173], v[154:157], v[2:17]
	v_mfma_f32_32x32x16_bf16 v[18:33], v[162:165], v[154:157], v[18:33]
	v_mfma_f32_32x32x16_bf16 v[34:49], v[170:173], v[146:149], v[34:49]
	s_setprio 0
	s_setprio 1
	s_waitcnt lgkmcnt(1)
	v_mfma_f32_32x32x16_bf16 v[50:65], v[166:169], v[150:153], v[50:65]
	s_waitcnt lgkmcnt(0)
	v_mfma_f32_32x32x16_bf16 v[2:17], v[174:177], v[158:161], v[2:17]
	v_mfma_f32_32x32x16_bf16 v[18:33], v[166:169], v[158:161], v[18:33]
	v_mfma_f32_32x32x16_bf16 v[34:49], v[174:177], v[150:153], v[34:49]
	s_setprio 0
	s_barrier
	global_load_dwordx4 v[146:149], v[78:79], off offset:896
	global_load_dwordx4 v[150:153], v[80:81], off offset:896
	global_load_dwordx4 v[154:157], v[74:75], off offset:896
	global_load_dwordx4 v[158:161], v[76:77], off offset:896
	global_load_dwordx4 v[162:165], v[82:83], off offset:896
	global_load_dwordx4 v[166:169], v[84:85], off offset:896
	s_waitcnt vmcnt(15)
	ds_write_b128 v97, v[106:109]
	ds_write_b128 v97, v[98:101] offset:9216
	ds_write_b128 v97, v[102:105] offset:18432
	s_waitcnt vmcnt(13)
	ds_write_b128 v97, v[114:117] offset:27648
	ds_write_b128 v97, v[110:113] offset:36864
	s_waitcnt vmcnt(12)
	ds_write_b128 v97, v[118:121] offset:46080
	ds_read_b128 v[98:101], v73 offset:36864
	ds_read_b128 v[102:105], v73 offset:36896
	ds_read_b128 v[106:109], v73 offset:41472
	ds_read_b128 v[110:113], v73 offset:41504
	ds_read_b128 v[114:117], v70
	ds_read_b128 v[118:121], v70 offset:32
	ds_read_b128 v[170:173], v70 offset:4608
	ds_read_b128 v[174:177], v70 offset:4640
	s_setprio 1
	s_waitcnt lgkmcnt(3)
	v_mfma_f32_32x32x16_bf16 v[50:65], v[114:117], v[98:101], v[50:65]
	s_waitcnt lgkmcnt(1)
	v_mfma_f32_32x32x16_bf16 v[2:17], v[170:173], v[106:109], v[2:17]
	v_mfma_f32_32x32x16_bf16 v[18:33], v[114:117], v[106:109], v[18:33]
	v_mfma_f32_32x32x16_bf16 v[34:49], v[170:173], v[98:101], v[34:49]
	s_setprio 0
	ds_read_b128 v[98:101], v73 offset:36928
	ds_read_b128 v[106:109], v73 offset:41536
	ds_read_b128 v[114:117], v70 offset:64
	ds_read_b128 v[170:173], v70 offset:4672
	s_setprio 1
	v_mfma_f32_32x32x16_bf16 v[50:65], v[118:121], v[102:105], v[50:65]
	s_waitcnt lgkmcnt(4)
	v_mfma_f32_32x32x16_bf16 v[2:17], v[174:177], v[110:113], v[2:17]
	v_mfma_f32_32x32x16_bf16 v[18:33], v[118:121], v[110:113], v[18:33]
	v_mfma_f32_32x32x16_bf16 v[34:49], v[174:177], v[102:105], v[34:49]
	s_setprio 0
	ds_read_b128 v[102:105], v73 offset:36960
	ds_read_b128 v[110:113], v73 offset:41568
	ds_read_b128 v[118:121], v70 offset:96
	ds_read_b128 v[174:177], v70 offset:4704
	s_setprio 1
	s_waitcnt lgkmcnt(5)
	v_mfma_f32_32x32x16_bf16 v[50:65], v[114:117], v[98:101], v[50:65]
	s_waitcnt lgkmcnt(4)
	v_mfma_f32_32x32x16_bf16 v[2:17], v[170:173], v[106:109], v[2:17]
	v_mfma_f32_32x32x16_bf16 v[18:33], v[114:117], v[106:109], v[18:33]
	v_mfma_f32_32x32x16_bf16 v[34:49], v[170:173], v[98:101], v[34:49]
	s_setprio 0
	s_setprio 1
	s_waitcnt lgkmcnt(1)
	v_mfma_f32_32x32x16_bf16 v[50:65], v[118:121], v[102:105], v[50:65]
	s_waitcnt lgkmcnt(0)
	v_mfma_f32_32x32x16_bf16 v[2:17], v[174:177], v[110:113], v[2:17]
	v_mfma_f32_32x32x16_bf16 v[18:33], v[118:121], v[110:113], v[18:33]
	v_mfma_f32_32x32x16_bf16 v[34:49], v[174:177], v[102:105], v[34:49]
	s_setprio 0
	s_barrier
	global_load_dwordx4 v[98:101], v[78:79], off offset:1024
	global_load_dwordx4 v[102:105], v[80:81], off offset:1024
	global_load_dwordx4 v[106:109], v[74:75], off offset:1024
	global_load_dwordx4 v[110:113], v[76:77], off offset:1024
	global_load_dwordx4 v[114:117], v[82:83], off offset:1024
	global_load_dwordx4 v[118:121], v[84:85], off offset:1024
	s_waitcnt vmcnt(15)
	ds_write_b128 v72, v[130:133]
	ds_write_b128 v72, v[122:125] offset:9216
	ds_write_b128 v72, v[126:129] offset:18432
	s_waitcnt vmcnt(13)
	ds_write_b128 v72, v[138:141] offset:27648
	ds_write_b128 v72, v[134:137] offset:36864
	s_waitcnt vmcnt(12)
	ds_write_b128 v72, v[142:145] offset:46080
	ds_read_b128 v[122:125], v66 offset:36864
	ds_read_b128 v[126:129], v66 offset:36896
	ds_read_b128 v[130:133], v66 offset:41472
	ds_read_b128 v[134:137], v66 offset:41504
	ds_read_b128 v[138:141], v71
	ds_read_b128 v[142:145], v71 offset:32
	ds_read_b128 v[170:173], v71 offset:4608
	ds_read_b128 v[174:177], v71 offset:4640
	s_setprio 1
	s_waitcnt lgkmcnt(3)
	v_mfma_f32_32x32x16_bf16 v[50:65], v[138:141], v[122:125], v[50:65]
	s_waitcnt lgkmcnt(1)
	v_mfma_f32_32x32x16_bf16 v[2:17], v[170:173], v[130:133], v[2:17]
	v_mfma_f32_32x32x16_bf16 v[18:33], v[138:141], v[130:133], v[18:33]
	v_mfma_f32_32x32x16_bf16 v[34:49], v[170:173], v[122:125], v[34:49]
	s_setprio 0
	ds_read_b128 v[122:125], v66 offset:36928
	ds_read_b128 v[130:133], v66 offset:41536
	ds_read_b128 v[138:141], v71 offset:64
	ds_read_b128 v[170:173], v71 offset:4672
	s_setprio 1
	v_mfma_f32_32x32x16_bf16 v[50:65], v[142:145], v[126:129], v[50:65]
	s_waitcnt lgkmcnt(4)
	v_mfma_f32_32x32x16_bf16 v[2:17], v[174:177], v[134:137], v[2:17]
	v_mfma_f32_32x32x16_bf16 v[18:33], v[142:145], v[134:137], v[18:33]
	v_mfma_f32_32x32x16_bf16 v[34:49], v[174:177], v[126:129], v[34:49]
	s_setprio 0
	ds_read_b128 v[126:129], v66 offset:36960
	ds_read_b128 v[134:137], v66 offset:41568
	ds_read_b128 v[142:145], v71 offset:96
	ds_read_b128 v[174:177], v71 offset:4704
	s_setprio 1
	s_waitcnt lgkmcnt(5)
	v_mfma_f32_32x32x16_bf16 v[50:65], v[138:141], v[122:125], v[50:65]
	s_waitcnt lgkmcnt(4)
	v_mfma_f32_32x32x16_bf16 v[2:17], v[170:173], v[130:133], v[2:17]
	v_mfma_f32_32x32x16_bf16 v[18:33], v[138:141], v[130:133], v[18:33]
	v_mfma_f32_32x32x16_bf16 v[34:49], v[170:173], v[122:125], v[34:49]
	s_setprio 0
	s_setprio 1
	s_waitcnt lgkmcnt(1)
	v_mfma_f32_32x32x16_bf16 v[50:65], v[142:145], v[126:129], v[50:65]
	s_waitcnt lgkmcnt(0)
	v_mfma_f32_32x32x16_bf16 v[2:17], v[174:177], v[134:137], v[2:17]
	v_mfma_f32_32x32x16_bf16 v[18:33], v[142:145], v[134:137], v[18:33]
	v_mfma_f32_32x32x16_bf16 v[34:49], v[174:177], v[126:129], v[34:49]
	s_setprio 0
	s_barrier
	global_load_dwordx4 v[122:125], v[78:79], off offset:1152
	global_load_dwordx4 v[126:129], v[80:81], off offset:1152
	global_load_dwordx4 v[130:133], v[74:75], off offset:1152
	global_load_dwordx4 v[134:137], v[76:77], off offset:1152
	global_load_dwordx4 v[138:141], v[82:83], off offset:1152
	global_load_dwordx4 v[142:145], v[84:85], off offset:1152
	s_waitcnt vmcnt(15)
	ds_write_b128 v97, v[154:157]
	ds_write_b128 v97, v[146:149] offset:9216
	ds_write_b128 v97, v[150:153] offset:18432
	s_waitcnt vmcnt(13)
	ds_write_b128 v97, v[162:165] offset:27648
	ds_write_b128 v97, v[158:161] offset:36864
	s_waitcnt vmcnt(12)
	ds_write_b128 v97, v[166:169] offset:46080
	ds_read_b128 v[146:149], v73 offset:36864
	ds_read_b128 v[150:153], v73 offset:36896
	ds_read_b128 v[154:157], v73 offset:41472
	ds_read_b128 v[158:161], v73 offset:41504
	ds_read_b128 v[162:165], v70
	ds_read_b128 v[166:169], v70 offset:32
	ds_read_b128 v[170:173], v70 offset:4608
	ds_read_b128 v[174:177], v70 offset:4640
	s_setprio 1
	s_waitcnt lgkmcnt(3)
	v_mfma_f32_32x32x16_bf16 v[50:65], v[162:165], v[146:149], v[50:65]
	s_waitcnt lgkmcnt(1)
	v_mfma_f32_32x32x16_bf16 v[2:17], v[170:173], v[154:157], v[2:17]
	v_mfma_f32_32x32x16_bf16 v[18:33], v[162:165], v[154:157], v[18:33]
	v_mfma_f32_32x32x16_bf16 v[34:49], v[170:173], v[146:149], v[34:49]
	s_setprio 0
	ds_read_b128 v[146:149], v73 offset:36928
	ds_read_b128 v[154:157], v73 offset:41536
	ds_read_b128 v[162:165], v70 offset:64
	ds_read_b128 v[170:173], v70 offset:4672
	s_setprio 1
	v_mfma_f32_32x32x16_bf16 v[50:65], v[166:169], v[150:153], v[50:65]
	s_waitcnt lgkmcnt(4)
	v_mfma_f32_32x32x16_bf16 v[2:17], v[174:177], v[158:161], v[2:17]
	v_mfma_f32_32x32x16_bf16 v[18:33], v[166:169], v[158:161], v[18:33]
	v_mfma_f32_32x32x16_bf16 v[34:49], v[174:177], v[150:153], v[34:49]
	s_setprio 0
	ds_read_b128 v[150:153], v73 offset:36960
	ds_read_b128 v[158:161], v73 offset:41568
	ds_read_b128 v[166:169], v70 offset:96
	ds_read_b128 v[174:177], v70 offset:4704
	s_setprio 1
	s_waitcnt lgkmcnt(5)
	v_mfma_f32_32x32x16_bf16 v[50:65], v[162:165], v[146:149], v[50:65]
	s_waitcnt lgkmcnt(4)
	v_mfma_f32_32x32x16_bf16 v[2:17], v[170:173], v[154:157], v[2:17]
	v_mfma_f32_32x32x16_bf16 v[18:33], v[162:165], v[154:157], v[18:33]
	v_mfma_f32_32x32x16_bf16 v[34:49], v[170:173], v[146:149], v[34:49]
	s_setprio 0
	s_setprio 1
	s_waitcnt lgkmcnt(1)
	v_mfma_f32_32x32x16_bf16 v[50:65], v[166:169], v[150:153], v[50:65]
	s_waitcnt lgkmcnt(0)
	v_mfma_f32_32x32x16_bf16 v[2:17], v[174:177], v[158:161], v[2:17]
	v_mfma_f32_32x32x16_bf16 v[18:33], v[166:169], v[158:161], v[18:33]
	v_mfma_f32_32x32x16_bf16 v[34:49], v[174:177], v[150:153], v[34:49]
	s_setprio 0
	s_barrier
	global_load_dwordx4 v[146:149], v[78:79], off offset:1280
	global_load_dwordx4 v[150:153], v[80:81], off offset:1280
	global_load_dwordx4 v[154:157], v[74:75], off offset:1280
	global_load_dwordx4 v[158:161], v[76:77], off offset:1280
	global_load_dwordx4 v[162:165], v[82:83], off offset:1280
	global_load_dwordx4 v[166:169], v[84:85], off offset:1280
	s_waitcnt vmcnt(15)
	ds_write_b128 v72, v[106:109]
	ds_write_b128 v72, v[98:101] offset:9216
	ds_write_b128 v72, v[102:105] offset:18432
	s_waitcnt vmcnt(13)
	ds_write_b128 v72, v[114:117] offset:27648
	ds_write_b128 v72, v[110:113] offset:36864
	s_waitcnt vmcnt(12)
	ds_write_b128 v72, v[118:121] offset:46080
	ds_read_b128 v[98:101], v66 offset:36864
	ds_read_b128 v[102:105], v66 offset:36896
	ds_read_b128 v[106:109], v66 offset:41472
	ds_read_b128 v[110:113], v66 offset:41504
	ds_read_b128 v[114:117], v71
	ds_read_b128 v[118:121], v71 offset:32
	ds_read_b128 v[170:173], v71 offset:4608
	ds_read_b128 v[174:177], v71 offset:4640
	s_setprio 1
	s_waitcnt lgkmcnt(3)
	v_mfma_f32_32x32x16_bf16 v[50:65], v[114:117], v[98:101], v[50:65]
	s_waitcnt lgkmcnt(1)
	v_mfma_f32_32x32x16_bf16 v[2:17], v[170:173], v[106:109], v[2:17]
	v_mfma_f32_32x32x16_bf16 v[18:33], v[114:117], v[106:109], v[18:33]
	v_mfma_f32_32x32x16_bf16 v[34:49], v[170:173], v[98:101], v[34:49]
	s_setprio 0
	ds_read_b128 v[98:101], v66 offset:36928
	ds_read_b128 v[106:109], v66 offset:41536
	ds_read_b128 v[114:117], v71 offset:64
	ds_read_b128 v[170:173], v71 offset:4672
	s_setprio 1
	v_mfma_f32_32x32x16_bf16 v[50:65], v[118:121], v[102:105], v[50:65]
	s_waitcnt lgkmcnt(4)
	v_mfma_f32_32x32x16_bf16 v[2:17], v[174:177], v[110:113], v[2:17]
	v_mfma_f32_32x32x16_bf16 v[18:33], v[118:121], v[110:113], v[18:33]
	v_mfma_f32_32x32x16_bf16 v[34:49], v[174:177], v[102:105], v[34:49]
	s_setprio 0
	ds_read_b128 v[102:105], v66 offset:36960
	ds_read_b128 v[110:113], v66 offset:41568
	ds_read_b128 v[118:121], v71 offset:96
	ds_read_b128 v[174:177], v71 offset:4704
	s_setprio 1
	s_waitcnt lgkmcnt(5)
	v_mfma_f32_32x32x16_bf16 v[50:65], v[114:117], v[98:101], v[50:65]
	s_waitcnt lgkmcnt(4)
	v_mfma_f32_32x32x16_bf16 v[2:17], v[170:173], v[106:109], v[2:17]
	v_mfma_f32_32x32x16_bf16 v[18:33], v[114:117], v[106:109], v[18:33]
	v_mfma_f32_32x32x16_bf16 v[34:49], v[170:173], v[98:101], v[34:49]
	s_setprio 0
	s_setprio 1
	s_waitcnt lgkmcnt(1)
	v_mfma_f32_32x32x16_bf16 v[50:65], v[118:121], v[102:105], v[50:65]
	s_waitcnt lgkmcnt(0)
	v_mfma_f32_32x32x16_bf16 v[2:17], v[174:177], v[110:113], v[2:17]
	v_mfma_f32_32x32x16_bf16 v[18:33], v[118:121], v[110:113], v[18:33]
	v_mfma_f32_32x32x16_bf16 v[34:49], v[174:177], v[102:105], v[34:49]
	s_setprio 0
	s_barrier
	global_load_dwordx4 v[98:101], v[78:79], off offset:1408
	global_load_dwordx4 v[102:105], v[80:81], off offset:1408
	global_load_dwordx4 v[106:109], v[74:75], off offset:1408
	global_load_dwordx4 v[110:113], v[76:77], off offset:1408
	global_load_dwordx4 v[114:117], v[82:83], off offset:1408
	global_load_dwordx4 v[118:121], v[84:85], off offset:1408
	s_waitcnt vmcnt(15)
	ds_write_b128 v97, v[130:133]
	ds_write_b128 v97, v[122:125] offset:9216
	ds_write_b128 v97, v[126:129] offset:18432
	s_waitcnt vmcnt(13)
	ds_write_b128 v97, v[138:141] offset:27648
	ds_write_b128 v97, v[134:137] offset:36864
	s_waitcnt vmcnt(12)
	ds_write_b128 v97, v[142:145] offset:46080
	ds_read_b128 v[122:125], v73 offset:36864
	ds_read_b128 v[126:129], v73 offset:36896
	ds_read_b128 v[130:133], v73 offset:41472
	ds_read_b128 v[134:137], v73 offset:41504
	ds_read_b128 v[138:141], v70
	ds_read_b128 v[142:145], v70 offset:32
	ds_read_b128 v[170:173], v70 offset:4608
	ds_read_b128 v[174:177], v70 offset:4640
	s_setprio 1
	s_waitcnt lgkmcnt(3)
	v_mfma_f32_32x32x16_bf16 v[50:65], v[138:141], v[122:125], v[50:65]
	s_waitcnt lgkmcnt(1)
	v_mfma_f32_32x32x16_bf16 v[2:17], v[170:173], v[130:133], v[2:17]
	v_mfma_f32_32x32x16_bf16 v[18:33], v[138:141], v[130:133], v[18:33]
	v_mfma_f32_32x32x16_bf16 v[34:49], v[170:173], v[122:125], v[34:49]
	s_setprio 0
	ds_read_b128 v[122:125], v73 offset:36928
	ds_read_b128 v[130:133], v73 offset:41536
	ds_read_b128 v[138:141], v70 offset:64
	ds_read_b128 v[170:173], v70 offset:4672
	s_setprio 1
	v_mfma_f32_32x32x16_bf16 v[50:65], v[142:145], v[126:129], v[50:65]
	s_waitcnt lgkmcnt(4)
	v_mfma_f32_32x32x16_bf16 v[2:17], v[174:177], v[134:137], v[2:17]
	v_mfma_f32_32x32x16_bf16 v[18:33], v[142:145], v[134:137], v[18:33]
	v_mfma_f32_32x32x16_bf16 v[34:49], v[174:177], v[126:129], v[34:49]
	s_setprio 0
	ds_read_b128 v[126:129], v73 offset:36960
	ds_read_b128 v[134:137], v73 offset:41568
	ds_read_b128 v[142:145], v70 offset:96
	ds_read_b128 v[174:177], v70 offset:4704
	s_setprio 1
	s_waitcnt lgkmcnt(5)
	v_mfma_f32_32x32x16_bf16 v[50:65], v[138:141], v[122:125], v[50:65]
	s_waitcnt lgkmcnt(4)
	v_mfma_f32_32x32x16_bf16 v[2:17], v[170:173], v[130:133], v[2:17]
	v_mfma_f32_32x32x16_bf16 v[18:33], v[138:141], v[130:133], v[18:33]
	v_mfma_f32_32x32x16_bf16 v[34:49], v[170:173], v[122:125], v[34:49]
	s_setprio 0
	s_setprio 1
	s_waitcnt lgkmcnt(1)
	v_mfma_f32_32x32x16_bf16 v[50:65], v[142:145], v[126:129], v[50:65]
	s_waitcnt lgkmcnt(0)
	v_mfma_f32_32x32x16_bf16 v[2:17], v[174:177], v[134:137], v[2:17]
	v_mfma_f32_32x32x16_bf16 v[18:33], v[142:145], v[134:137], v[18:33]
	v_mfma_f32_32x32x16_bf16 v[34:49], v[174:177], v[126:129], v[34:49]
	s_setprio 0
	s_barrier
	global_load_dwordx4 v[122:125], v[78:79], off offset:1536
	global_load_dwordx4 v[126:129], v[80:81], off offset:1536
	global_load_dwordx4 v[130:133], v[74:75], off offset:1536
	global_load_dwordx4 v[134:137], v[76:77], off offset:1536
	global_load_dwordx4 v[138:141], v[82:83], off offset:1536
	global_load_dwordx4 v[142:145], v[84:85], off offset:1536
	s_waitcnt vmcnt(15)
	ds_write_b128 v72, v[154:157]
	ds_write_b128 v72, v[146:149] offset:9216
	ds_write_b128 v72, v[150:153] offset:18432
	s_waitcnt vmcnt(13)
	ds_write_b128 v72, v[162:165] offset:27648
	ds_write_b128 v72, v[158:161] offset:36864
	s_waitcnt vmcnt(12)
	ds_write_b128 v72, v[166:169] offset:46080
	ds_read_b128 v[146:149], v66 offset:36864
	ds_read_b128 v[150:153], v66 offset:36896
	ds_read_b128 v[154:157], v66 offset:41472
	ds_read_b128 v[158:161], v66 offset:41504
	ds_read_b128 v[162:165], v71
	ds_read_b128 v[166:169], v71 offset:32
	ds_read_b128 v[170:173], v71 offset:4608
	ds_read_b128 v[174:177], v71 offset:4640
	s_setprio 1
	s_waitcnt lgkmcnt(3)
	v_mfma_f32_32x32x16_bf16 v[50:65], v[162:165], v[146:149], v[50:65]
	s_waitcnt lgkmcnt(1)
	v_mfma_f32_32x32x16_bf16 v[2:17], v[170:173], v[154:157], v[2:17]
	v_mfma_f32_32x32x16_bf16 v[18:33], v[162:165], v[154:157], v[18:33]
	v_mfma_f32_32x32x16_bf16 v[34:49], v[170:173], v[146:149], v[34:49]
	s_setprio 0
	ds_read_b128 v[146:149], v66 offset:36928
	ds_read_b128 v[154:157], v66 offset:41536
	ds_read_b128 v[162:165], v71 offset:64
	ds_read_b128 v[170:173], v71 offset:4672
	s_setprio 1
	v_mfma_f32_32x32x16_bf16 v[50:65], v[166:169], v[150:153], v[50:65]
	s_waitcnt lgkmcnt(4)
	v_mfma_f32_32x32x16_bf16 v[2:17], v[174:177], v[158:161], v[2:17]
	v_mfma_f32_32x32x16_bf16 v[18:33], v[166:169], v[158:161], v[18:33]
	v_mfma_f32_32x32x16_bf16 v[34:49], v[174:177], v[150:153], v[34:49]
	s_setprio 0
	ds_read_b128 v[150:153], v66 offset:36960
	ds_read_b128 v[158:161], v66 offset:41568
	ds_read_b128 v[166:169], v71 offset:96
	ds_read_b128 v[174:177], v71 offset:4704
	s_setprio 1
	s_waitcnt lgkmcnt(5)
	v_mfma_f32_32x32x16_bf16 v[50:65], v[162:165], v[146:149], v[50:65]
	s_waitcnt lgkmcnt(4)
	v_mfma_f32_32x32x16_bf16 v[2:17], v[170:173], v[154:157], v[2:17]
	v_mfma_f32_32x32x16_bf16 v[18:33], v[162:165], v[154:157], v[18:33]
	v_mfma_f32_32x32x16_bf16 v[34:49], v[170:173], v[146:149], v[34:49]
	s_setprio 0
	s_setprio 1
	s_waitcnt lgkmcnt(1)
	v_mfma_f32_32x32x16_bf16 v[50:65], v[166:169], v[150:153], v[50:65]
	s_waitcnt lgkmcnt(0)
	v_mfma_f32_32x32x16_bf16 v[2:17], v[174:177], v[158:161], v[2:17]
	v_mfma_f32_32x32x16_bf16 v[18:33], v[166:169], v[158:161], v[18:33]
	v_mfma_f32_32x32x16_bf16 v[34:49], v[174:177], v[150:153], v[34:49]
	s_setprio 0
	s_barrier
	global_load_dwordx4 v[146:149], v[78:79], off offset:1664
	global_load_dwordx4 v[150:153], v[80:81], off offset:1664
	global_load_dwordx4 v[154:157], v[74:75], off offset:1664
	global_load_dwordx4 v[158:161], v[76:77], off offset:1664
	global_load_dwordx4 v[162:165], v[82:83], off offset:1664
	global_load_dwordx4 v[166:169], v[84:85], off offset:1664
	s_waitcnt vmcnt(15)
	ds_write_b128 v97, v[106:109]
	ds_write_b128 v97, v[98:101] offset:9216
	ds_write_b128 v97, v[102:105] offset:18432
	s_waitcnt vmcnt(13)
	ds_write_b128 v97, v[114:117] offset:27648
	ds_write_b128 v97, v[110:113] offset:36864
	s_waitcnt vmcnt(12)
	ds_write_b128 v97, v[118:121] offset:46080
	ds_read_b128 v[98:101], v73 offset:36864
	ds_read_b128 v[102:105], v73 offset:36896
	ds_read_b128 v[106:109], v73 offset:41472
	ds_read_b128 v[110:113], v73 offset:41504
	ds_read_b128 v[114:117], v70
	ds_read_b128 v[118:121], v70 offset:32
	ds_read_b128 v[170:173], v70 offset:4608
	ds_read_b128 v[174:177], v70 offset:4640
	s_setprio 1
	s_waitcnt lgkmcnt(3)
	v_mfma_f32_32x32x16_bf16 v[50:65], v[114:117], v[98:101], v[50:65]
	s_waitcnt lgkmcnt(1)
	v_mfma_f32_32x32x16_bf16 v[2:17], v[170:173], v[106:109], v[2:17]
	v_mfma_f32_32x32x16_bf16 v[18:33], v[114:117], v[106:109], v[18:33]
	v_mfma_f32_32x32x16_bf16 v[34:49], v[170:173], v[98:101], v[34:49]
	s_setprio 0
	ds_read_b128 v[98:101], v73 offset:36928
	ds_read_b128 v[106:109], v73 offset:41536
	ds_read_b128 v[114:117], v70 offset:64
	ds_read_b128 v[170:173], v70 offset:4672
	s_setprio 1
	v_mfma_f32_32x32x16_bf16 v[50:65], v[118:121], v[102:105], v[50:65]
	s_waitcnt lgkmcnt(4)
	v_mfma_f32_32x32x16_bf16 v[2:17], v[174:177], v[110:113], v[2:17]
	v_mfma_f32_32x32x16_bf16 v[18:33], v[118:121], v[110:113], v[18:33]
	v_mfma_f32_32x32x16_bf16 v[34:49], v[174:177], v[102:105], v[34:49]
	s_setprio 0
	ds_read_b128 v[102:105], v73 offset:36960
	ds_read_b128 v[110:113], v73 offset:41568
	ds_read_b128 v[118:121], v70 offset:96
	ds_read_b128 v[174:177], v70 offset:4704
	s_setprio 1
	s_waitcnt lgkmcnt(5)
	v_mfma_f32_32x32x16_bf16 v[50:65], v[114:117], v[98:101], v[50:65]
	s_waitcnt lgkmcnt(4)
	v_mfma_f32_32x32x16_bf16 v[2:17], v[170:173], v[106:109], v[2:17]
	v_mfma_f32_32x32x16_bf16 v[18:33], v[114:117], v[106:109], v[18:33]
	v_mfma_f32_32x32x16_bf16 v[34:49], v[170:173], v[98:101], v[34:49]
	s_setprio 0
	s_setprio 1
	s_waitcnt lgkmcnt(1)
	v_mfma_f32_32x32x16_bf16 v[50:65], v[118:121], v[102:105], v[50:65]
	s_waitcnt lgkmcnt(0)
	v_mfma_f32_32x32x16_bf16 v[2:17], v[174:177], v[110:113], v[2:17]
	v_mfma_f32_32x32x16_bf16 v[18:33], v[118:121], v[110:113], v[18:33]
	v_mfma_f32_32x32x16_bf16 v[34:49], v[174:177], v[102:105], v[34:49]
	s_setprio 0
	s_barrier
	global_load_dwordx4 v[98:101], v[78:79], off offset:1792
	global_load_dwordx4 v[102:105], v[80:81], off offset:1792
	global_load_dwordx4 v[106:109], v[74:75], off offset:1792
	global_load_dwordx4 v[110:113], v[76:77], off offset:1792
	global_load_dwordx4 v[114:117], v[82:83], off offset:1792
	global_load_dwordx4 v[118:121], v[84:85], off offset:1792
	s_waitcnt vmcnt(15)
	ds_write_b128 v72, v[130:133]
	ds_write_b128 v72, v[122:125] offset:9216
	ds_write_b128 v72, v[126:129] offset:18432
	s_waitcnt vmcnt(13)
	ds_write_b128 v72, v[138:141] offset:27648
	ds_write_b128 v72, v[134:137] offset:36864
	s_waitcnt vmcnt(12)
	ds_write_b128 v72, v[142:145] offset:46080
	ds_read_b128 v[122:125], v66 offset:36864
	ds_read_b128 v[126:129], v66 offset:36896
	ds_read_b128 v[130:133], v66 offset:41472
	ds_read_b128 v[134:137], v66 offset:41504
	ds_read_b128 v[138:141], v71
	ds_read_b128 v[142:145], v71 offset:32
	ds_read_b128 v[170:173], v71 offset:4608
	ds_read_b128 v[174:177], v71 offset:4640
	s_setprio 1
	s_waitcnt lgkmcnt(3)
	v_mfma_f32_32x32x16_bf16 v[50:65], v[138:141], v[122:125], v[50:65]
	s_waitcnt lgkmcnt(1)
	v_mfma_f32_32x32x16_bf16 v[2:17], v[170:173], v[130:133], v[2:17]
	v_mfma_f32_32x32x16_bf16 v[18:33], v[138:141], v[130:133], v[18:33]
	v_mfma_f32_32x32x16_bf16 v[34:49], v[170:173], v[122:125], v[34:49]
	s_setprio 0
	ds_read_b128 v[122:125], v66 offset:36928
	ds_read_b128 v[130:133], v66 offset:41536
	ds_read_b128 v[138:141], v71 offset:64
	ds_read_b128 v[170:173], v71 offset:4672
	s_setprio 1
	v_mfma_f32_32x32x16_bf16 v[50:65], v[142:145], v[126:129], v[50:65]
	s_waitcnt lgkmcnt(4)
	v_mfma_f32_32x32x16_bf16 v[2:17], v[174:177], v[134:137], v[2:17]
	v_mfma_f32_32x32x16_bf16 v[18:33], v[142:145], v[134:137], v[18:33]
	v_mfma_f32_32x32x16_bf16 v[34:49], v[174:177], v[126:129], v[34:49]
	s_setprio 0
	ds_read_b128 v[126:129], v66 offset:36960
	ds_read_b128 v[134:137], v66 offset:41568
	ds_read_b128 v[142:145], v71 offset:96
	ds_read_b128 v[174:177], v71 offset:4704
	s_setprio 1
	s_waitcnt lgkmcnt(5)
	v_mfma_f32_32x32x16_bf16 v[50:65], v[138:141], v[122:125], v[50:65]
	s_waitcnt lgkmcnt(4)
	v_mfma_f32_32x32x16_bf16 v[2:17], v[170:173], v[130:133], v[2:17]
	v_mfma_f32_32x32x16_bf16 v[18:33], v[138:141], v[130:133], v[18:33]
	v_mfma_f32_32x32x16_bf16 v[34:49], v[170:173], v[122:125], v[34:49]
	s_setprio 0
	s_setprio 1
	s_waitcnt lgkmcnt(1)
	v_mfma_f32_32x32x16_bf16 v[50:65], v[142:145], v[126:129], v[50:65]
	s_waitcnt lgkmcnt(0)
	v_mfma_f32_32x32x16_bf16 v[2:17], v[174:177], v[134:137], v[2:17]
	v_mfma_f32_32x32x16_bf16 v[18:33], v[142:145], v[134:137], v[18:33]
	v_mfma_f32_32x32x16_bf16 v[34:49], v[174:177], v[126:129], v[34:49]
	s_setprio 0
	s_barrier
	global_load_dwordx4 v[122:125], v[78:79], off offset:1920
	s_nop 0
	global_load_dwordx4 v[78:81], v[80:81], off offset:1920
	s_nop 0
	global_load_dwordx4 v[126:129], v[74:75], off offset:1920
	s_nop 0
	global_load_dwordx4 v[74:77], v[76:77], off offset:1920
	s_nop 0
	global_load_dwordx4 v[130:133], v[82:83], off offset:1920
	s_nop 0
	global_load_dwordx4 v[82:85], v[84:85], off offset:1920
	s_waitcnt vmcnt(15)
	ds_write_b128 v97, v[154:157]
	ds_write_b128 v97, v[146:149] offset:9216
	ds_write_b128 v97, v[150:153] offset:18432
	s_waitcnt vmcnt(13)
	ds_write_b128 v97, v[162:165] offset:27648
	ds_write_b128 v97, v[158:161] offset:36864
	s_waitcnt vmcnt(12)
	ds_write_b128 v97, v[166:169] offset:46080
	ds_read_b128 v[134:137], v73 offset:36864
	ds_read_b128 v[138:141], v73 offset:36896
	ds_read_b128 v[142:145], v73 offset:41472
	ds_read_b128 v[146:149], v73 offset:41504
	ds_read_b128 v[150:153], v70
	ds_read_b128 v[154:157], v70 offset:32
	ds_read_b128 v[158:161], v70 offset:4608
	ds_read_b128 v[162:165], v70 offset:4640
	s_setprio 1
	s_waitcnt lgkmcnt(3)
	v_mfma_f32_32x32x16_bf16 v[50:65], v[150:153], v[134:137], v[50:65]
	s_waitcnt lgkmcnt(1)
	v_mfma_f32_32x32x16_bf16 v[2:17], v[158:161], v[142:145], v[2:17]
	v_mfma_f32_32x32x16_bf16 v[18:33], v[150:153], v[142:145], v[18:33]
	v_mfma_f32_32x32x16_bf16 v[34:49], v[158:161], v[134:137], v[34:49]
	s_setprio 0
	ds_read_b128 v[134:137], v73 offset:36928
	ds_read_b128 v[142:145], v73 offset:41536
	ds_read_b128 v[150:153], v70 offset:64
	ds_read_b128 v[158:161], v70 offset:4672
	s_setprio 1
	v_mfma_f32_32x32x16_bf16 v[50:65], v[154:157], v[138:141], v[50:65]
	s_waitcnt lgkmcnt(4)
	v_mfma_f32_32x32x16_bf16 v[2:17], v[162:165], v[146:149], v[2:17]
	v_mfma_f32_32x32x16_bf16 v[18:33], v[154:157], v[146:149], v[18:33]
	v_mfma_f32_32x32x16_bf16 v[34:49], v[162:165], v[138:141], v[34:49]
	s_setprio 0
	ds_read_b128 v[138:141], v73 offset:36960
	ds_read_b128 v[146:149], v73 offset:41568
	ds_read_b128 v[154:157], v70 offset:96
	ds_read_b128 v[162:165], v70 offset:4704
	s_setprio 1
	s_waitcnt lgkmcnt(5)
	v_mfma_f32_32x32x16_bf16 v[50:65], v[150:153], v[134:137], v[50:65]
	s_waitcnt lgkmcnt(4)
	v_mfma_f32_32x32x16_bf16 v[2:17], v[158:161], v[142:145], v[2:17]
	v_mfma_f32_32x32x16_bf16 v[18:33], v[150:153], v[142:145], v[18:33]
	v_mfma_f32_32x32x16_bf16 v[34:49], v[158:161], v[134:137], v[34:49]
	s_setprio 0
	s_setprio 1
	s_waitcnt lgkmcnt(1)
	v_mfma_f32_32x32x16_bf16 v[50:65], v[154:157], v[138:141], v[50:65]
	s_waitcnt lgkmcnt(0)
	v_mfma_f32_32x32x16_bf16 v[2:17], v[162:165], v[146:149], v[2:17]
	v_mfma_f32_32x32x16_bf16 v[18:33], v[154:157], v[146:149], v[18:33]
	v_mfma_f32_32x32x16_bf16 v[34:49], v[162:165], v[138:141], v[34:49]
	s_setprio 0
	s_barrier
	s_waitcnt vmcnt(9)
	ds_write_b128 v72, v[106:109]
	ds_write_b128 v72, v[98:101] offset:9216
	ds_write_b128 v72, v[102:105] offset:18432
	s_waitcnt vmcnt(7)
	ds_write_b128 v72, v[114:117] offset:27648
	ds_write_b128 v72, v[110:113] offset:36864
	s_waitcnt vmcnt(6)
	ds_write_b128 v72, v[118:121] offset:46080
	ds_read_b128 v[98:101], v66 offset:36864
	ds_read_b128 v[102:105], v66 offset:36896
	ds_read_b128 v[106:109], v66 offset:41472
	ds_read_b128 v[110:113], v66 offset:41504
	ds_read_b128 v[114:117], v71
	ds_read_b128 v[118:121], v71 offset:32
	ds_read_b128 v[134:137], v71 offset:4608
	ds_read_b128 v[138:141], v71 offset:4640
	s_setprio 1
	s_waitcnt lgkmcnt(3)
	v_mfma_f32_32x32x16_bf16 v[50:65], v[114:117], v[98:101], v[50:65]
	s_waitcnt lgkmcnt(1)
	v_mfma_f32_32x32x16_bf16 v[2:17], v[134:137], v[106:109], v[2:17]
	v_mfma_f32_32x32x16_bf16 v[18:33], v[114:117], v[106:109], v[18:33]
	v_mfma_f32_32x32x16_bf16 v[34:49], v[134:137], v[98:101], v[34:49]
	s_setprio 0
	ds_read_b128 v[98:101], v66 offset:36928
	ds_read_b128 v[106:109], v66 offset:41536
	ds_read_b128 v[114:117], v71 offset:64
	ds_read_b128 v[134:137], v71 offset:4672
	s_setprio 1
	v_mfma_f32_32x32x16_bf16 v[50:65], v[118:121], v[102:105], v[50:65]
	s_waitcnt lgkmcnt(4)
	v_mfma_f32_32x32x16_bf16 v[2:17], v[138:141], v[110:113], v[2:17]
	v_mfma_f32_32x32x16_bf16 v[18:33], v[118:121], v[110:113], v[18:33]
	v_mfma_f32_32x32x16_bf16 v[34:49], v[138:141], v[102:105], v[34:49]
	s_setprio 0
	ds_read_b128 v[102:105], v66 offset:36960
	ds_read_b128 v[110:113], v66 offset:41568
	ds_read_b128 v[118:121], v71 offset:96
	ds_read_b128 v[138:141], v71 offset:4704
	s_setprio 1
	s_waitcnt lgkmcnt(5)
	v_mfma_f32_32x32x16_bf16 v[50:65], v[114:117], v[98:101], v[50:65]
	s_waitcnt lgkmcnt(4)
	v_mfma_f32_32x32x16_bf16 v[2:17], v[134:137], v[106:109], v[2:17]
	v_mfma_f32_32x32x16_bf16 v[18:33], v[114:117], v[106:109], v[18:33]
	v_mfma_f32_32x32x16_bf16 v[34:49], v[134:137], v[98:101], v[34:49]
	s_setprio 0
	s_setprio 1
	s_waitcnt lgkmcnt(1)
	v_mfma_f32_32x32x16_bf16 v[50:65], v[118:121], v[102:105], v[50:65]
	s_waitcnt lgkmcnt(0)
	v_mfma_f32_32x32x16_bf16 v[2:17], v[138:141], v[110:113], v[2:17]
	v_mfma_f32_32x32x16_bf16 v[18:33], v[118:121], v[110:113], v[18:33]
	v_mfma_f32_32x32x16_bf16 v[34:49], v[138:141], v[102:105], v[34:49]
	s_setprio 0
	s_barrier
	s_waitcnt vmcnt(3)
	ds_write_b128 v97, v[126:129]
	ds_write_b128 v97, v[122:125] offset:9216
	ds_write_b128 v97, v[78:81] offset:18432
	s_waitcnt vmcnt(1)
	ds_write_b128 v97, v[130:133] offset:27648
	ds_write_b128 v97, v[74:77] offset:36864
	s_waitcnt vmcnt(0)
	ds_write_b128 v97, v[82:85] offset:46080
	ds_read_b128 v[74:77], v73 offset:36864
	ds_read_b128 v[78:81], v73 offset:36896
	ds_read_b128 v[82:85], v73 offset:41472
	ds_read_b128 v[98:101], v73 offset:41504
	ds_read_b128 v[102:105], v70
	ds_read_b128 v[106:109], v70 offset:32
	ds_read_b128 v[110:113], v70 offset:4608
	ds_read_b128 v[114:117], v70 offset:4640
	s_setprio 1
	s_waitcnt lgkmcnt(3)
	v_mfma_f32_32x32x16_bf16 v[50:65], v[102:105], v[74:77], v[50:65]
	s_waitcnt lgkmcnt(1)
	v_mfma_f32_32x32x16_bf16 v[2:17], v[110:113], v[82:85], v[2:17]
	v_mfma_f32_32x32x16_bf16 v[18:33], v[102:105], v[82:85], v[18:33]
	v_mfma_f32_32x32x16_bf16 v[34:49], v[110:113], v[74:77], v[34:49]
	s_setprio 0
	ds_read_b128 v[74:77], v73 offset:36928
	ds_read_b128 v[82:85], v73 offset:41536
	ds_read_b128 v[102:105], v70 offset:64
	ds_read_b128 v[110:113], v70 offset:4672
	s_setprio 1
	v_mfma_f32_32x32x16_bf16 v[50:65], v[106:109], v[78:81], v[50:65]
	s_waitcnt lgkmcnt(4)
	v_mfma_f32_32x32x16_bf16 v[2:17], v[114:117], v[98:101], v[2:17]
	v_mfma_f32_32x32x16_bf16 v[18:33], v[106:109], v[98:101], v[18:33]
	v_mfma_f32_32x32x16_bf16 v[34:49], v[114:117], v[78:81], v[34:49]
	s_setprio 0
	ds_read_b128 v[78:81], v73 offset:36960
	ds_read_b128 v[98:101], v73 offset:41568
	ds_read_b128 v[106:109], v70 offset:96
	ds_read_b128 v[114:117], v70 offset:4704
	s_setprio 1
	s_waitcnt lgkmcnt(5)
	v_mfma_f32_32x32x16_bf16 v[50:65], v[102:105], v[74:77], v[50:65]
	s_waitcnt lgkmcnt(4)
	v_mfma_f32_32x32x16_bf16 v[2:17], v[110:113], v[82:85], v[2:17]
	v_mfma_f32_32x32x16_bf16 v[18:33], v[102:105], v[82:85], v[18:33]
	v_mfma_f32_32x32x16_bf16 v[34:49], v[110:113], v[74:77], v[34:49]
	s_setprio 0
	s_setprio 1
	s_waitcnt lgkmcnt(1)
	v_mfma_f32_32x32x16_bf16 v[50:65], v[106:109], v[78:81], v[50:65]
	s_waitcnt lgkmcnt(0)
	v_mfma_f32_32x32x16_bf16 v[2:17], v[114:117], v[98:101], v[2:17]
	v_mfma_f32_32x32x16_bf16 v[18:33], v[106:109], v[98:101], v[18:33]
	v_mfma_f32_32x32x16_bf16 v[34:49], v[114:117], v[78:81], v[34:49]
	s_setprio 0
	s_barrier
	ds_read_b128 v[72:75], v66 offset:36864
	ds_read_b128 v[76:79], v66 offset:36896
	ds_read_b128 v[80:83], v66 offset:41472
	ds_read_b128 v[98:101], v66 offset:41504
	ds_read_b128 v[102:105], v71
	ds_read_b128 v[106:109], v71 offset:32
	ds_read_b128 v[110:113], v71 offset:4608
	ds_read_b128 v[114:117], v71 offset:4640
	s_setprio 1
	s_waitcnt lgkmcnt(3)
	v_mfma_f32_32x32x16_bf16 v[50:65], v[102:105], v[72:75], v[50:65]
	s_waitcnt lgkmcnt(1)
	v_mfma_f32_32x32x16_bf16 v[2:17], v[110:113], v[80:83], v[2:17]
	v_mfma_f32_32x32x16_bf16 v[18:33], v[102:105], v[80:83], v[18:33]
	v_mfma_f32_32x32x16_bf16 v[34:49], v[110:113], v[72:75], v[34:49]
	s_setprio 0
	ds_read_b128 v[72:75], v66 offset:36928
	ds_read_b128 v[80:83], v66 offset:41536
	ds_read_b128 v[102:105], v71 offset:64
	ds_read_b128 v[110:113], v71 offset:4672
	s_setprio 1
	v_mfma_f32_32x32x16_bf16 v[50:65], v[106:109], v[76:79], v[50:65]
	s_waitcnt lgkmcnt(4)
	v_mfma_f32_32x32x16_bf16 v[2:17], v[114:117], v[98:101], v[2:17]
	v_mfma_f32_32x32x16_bf16 v[18:33], v[106:109], v[98:101], v[18:33]
	v_mfma_f32_32x32x16_bf16 v[34:49], v[114:117], v[76:79], v[34:49]
	s_setprio 0
	ds_read_b128 v[76:79], v66 offset:36960
	ds_read_b128 v[98:101], v66 offset:41568
	ds_read_b128 v[106:109], v71 offset:96
	ds_read_b128 v[114:117], v71 offset:4704
	s_setprio 1
	s_waitcnt lgkmcnt(5)
	v_mfma_f32_32x32x16_bf16 v[50:65], v[102:105], v[72:75], v[50:65]
	s_waitcnt lgkmcnt(4)
	v_mfma_f32_32x32x16_bf16 v[2:17], v[110:113], v[80:83], v[2:17]
	v_mfma_f32_32x32x16_bf16 v[18:33], v[102:105], v[80:83], v[18:33]
	v_mfma_f32_32x32x16_bf16 v[34:49], v[110:113], v[72:75], v[34:49]
	s_setprio 0
	s_setprio 1
	s_waitcnt lgkmcnt(1)
	v_mfma_f32_32x32x16_bf16 v[50:65], v[106:109], v[76:79], v[50:65]
	s_waitcnt lgkmcnt(0)
	v_mfma_f32_32x32x16_bf16 v[2:17], v[114:117], v[98:101], v[2:17]
	v_mfma_f32_32x32x16_bf16 v[18:33], v[106:109], v[98:101], v[18:33]
	v_mfma_f32_32x32x16_bf16 v[34:49], v[114:117], v[76:79], v[34:49]
	s_setprio 0
	s_add_i32 s3, s12, 0xffffe000
	s_lshr_b32 s3, s3, 12
	s_add_i32 s3, s3, 1
	s_cmp_gt_i32 s14, 63
	s_cselect_b32 s3, s3, 0
	v_lshrrev_b32_e32 v70, 1, v69
	s_mul_i32 s33, s3, 0x3000
	v_lshlrev_b32_e32 v71, 1, v69
	v_and_b32_e32 v70, 16, v70
	s_mul_hi_u32 s14, s3, 0x3000
	s_add_u32 s16, s96, s33
	v_and_b32_e32 v66, 0x5f, v69
	v_and_or_b32 v70, v71, s39, v70
	s_addc_u32 s17, s97, s14
	s_lshl_b64 s[14:15], s[4:5], 2
	v_readlane_b32 s44, v245, 0
	v_mad_u32_u24 v66, v66, s40, v70
	s_add_u32 s16, s16, s14
	v_readlane_b32 s45, v245, 1
	v_readlane_b32 s48, v245, 4
	v_readlane_b32 s49, v245, 5
	s_barrier
	ds_write_b128 v66, v[50:53]
	ds_write_b128 v66, v[54:57] offset:32
	ds_write_b128 v66, v[58:61] offset:64
	ds_write_b128 v66, v[62:65] offset:96
	ds_write_b128 v66, v[34:37] offset:128
	ds_write_b128 v66, v[38:41] offset:160
	ds_write_b128 v66, v[42:45] offset:192
	ds_write_b128 v66, v[46:49] offset:224
	ds_write_b128 v66, v[18:21] offset:33280
	ds_write_b128 v66, v[22:25] offset:33312
	ds_write_b128 v66, v[26:29] offset:33344
	ds_write_b128 v66, v[30:33] offset:33376
	ds_write_b128 v66, v[2:5] offset:33408
	ds_write_b128 v66, v[6:9] offset:33440
	ds_write_b128 v66, v[10:13] offset:33472
	ds_write_b128 v66, v[14:17] offset:33504
	s_addc_u32 s17, s17, s15
	v_lshlrev_b32_e32 v66, 4, v68
	s_mov_b64 s[44:45], s[48:49]
	v_lshl_add_u64 v[2:3], s[16:17], 0, v[66:67]
	s_add_u32 s16, s44, s14
	v_ashrrev_i32_e32 v59, 2, v69
	s_addc_u32 s17, s45, s15
	s_add_i32 s3, s3, 5
	s_add_i32 s33, s33, 0xf000
	v_and_b32_e32 v58, -16, v59
	s_mul_hi_u32 s3, s3, 0x3000
	s_add_u32 s33, s96, s33
	v_add_u32_e32 v60, s12, v58
	s_addc_u32 s3, s97, s3
	v_add_u32_e32 v6, 0xffffe000, v60
	v_ashrrev_i32_e32 v61, 31, v60
	v_cmp_gt_i32_e32 vcc, s41, v60
	s_add_u32 s44, s33, s14
	s_addc_u32 s45, s3, s15
	v_cndmask_b32_e32 v7, 0, v61, vcc
	v_cndmask_b32_e32 v6, v6, v60, vcc
	v_cndmask_b32_e32 v9, v1, v86, vcc
	v_cndmask_b32_e32 v8, v87, v88, vcc
	v_lshlrev_b64 v[6:7], 12, v[6:7]
	v_add_co_u32_e32 v2, vcc, s41, v2
	v_lshl_add_u64 v[4:5], s[44:45], 0, v[66:67]
	v_lshl_add_u64 v[6:7], v[8:9], 0, v[6:7]
	v_addc_co_u32_e32 v3, vcc, 0, v3, vcc
	v_lshl_add_u64 v[6:7], v[6:7], 0, s[14:15]
	v_add_co_u32_e32 v10, vcc, s42, v4
	v_lshl_add_u64 v[6:7], v[6:7], 0, v[66:67]
	s_nop 0
	v_addc_co_u32_e32 v11, vcc, 0, v5, vcc
	s_waitcnt lgkmcnt(0)
	s_barrier
	s_mov_b64 s[98:99], 0x2000
	v_lshl_add_u64 v[246:247], v[6:7], 0, s[98:99]
	global_load_dwordx4 v[6:9], v[6:7], off
	s_nop 0
	global_load_dwordx4 v[2:5], v[2:3], off
	s_nop 0
	global_load_dwordx4 v[10:13], v[10:11], off
	s_nop 0
	global_load_dwordx4 v[14:17], v66, s[16:17]
	global_load_dwordx4 v[120:123], v[246:247], off offset:-4096
	global_load_dwordx4 v[124:127], v[246:247], off
	v_lshl_add_u64 v[246:247], v[246:247], 0, s[98:99]
	global_load_dwordx4 v[128:131], v[246:247], off offset:-4096
	global_load_dwordx4 v[132:135], v[246:247], off
	v_lshl_add_u64 v[246:247], v[246:247], 0, s[98:99]
	global_load_dwordx4 v[136:139], v[246:247], off offset:-4096
	global_load_dwordx4 v[140:143], v[246:247], off
	v_lshl_add_u64 v[246:247], v[246:247], 0, s[98:99]
	global_load_dwordx4 v[144:147], v[246:247], off offset:-4096
	global_load_dwordx4 v[148:151], v[246:247], off
	v_lshl_add_u64 v[246:247], v[246:247], 0, s[98:99]
	global_load_dwordx4 v[152:155], v[246:247], off offset:-4096
	global_load_dwordx4 v[156:159], v[246:247], off
	v_lshl_add_u64 v[246:247], v[246:247], 0, s[98:99]
	global_load_dwordx4 v[160:163], v[246:247], off offset:-4096
	global_load_dwordx4 v[164:167], v[246:247], off
	v_lshl_add_u64 v[246:247], v[246:247], 0, s[98:99]
	global_load_dwordx4 v[168:171], v[246:247], off offset:-4096
	global_load_dwordx4 v[172:175], v[246:247], off
	v_lshl_add_u64 v[246:247], v[246:247], 0, s[98:99]
	v_lshlrev_b64 v[18:19], 12, v[60:61]
	v_lshl_add_u64 v[18:19], s[74:75], 0, v[18:19]
	v_lshl_add_u64 v[18:19], v[18:19], 0, s[14:15]
	v_mad_u64_u32 v[72:73], s[16:17], v58, s40, v[66:67]
	v_lshl_add_u64 v[26:27], v[18:19], 0, v[66:67]
	v_lshlrev_b64 v[18:19], 11, v[60:61]
	v_lshl_add_u64 v[18:19], s[10:11], 0, v[18:19]
	s_lshl_b64 s[16:17], s[4:5], 1
	v_lshl_add_u64 v[18:19], v[18:19], 0, s[16:17]
	v_lshlrev_b32_e32 v62, 3, v68
	v_mov_b32_e32 v63, v67
	v_or_b32_e32 v30, 1, v60
	v_lshl_add_u64 v[28:29], v[18:19], 0, v[62:63]
	v_add_u32_e32 v18, 0xffffe001, v60
	v_ashrrev_i32_e32 v31, 31, v30
	v_cmp_gt_i32_e32 vcc, s41, v30
	v_or_b32_e32 v36, 5, v60
	v_add_u32_e32 v40, 0xffffe005, v60
	v_cndmask_b32_e32 v19, 0, v31, vcc
	v_cndmask_b32_e32 v18, v18, v30, vcc
	v_lshlrev_b64 v[24:25], 12, v[18:19]
	ds_read_b128 v[18:21], v72
	v_cndmask_b32_e32 v23, v1, v86, vcc
	v_cndmask_b32_e32 v22, v87, v88, vcc
	v_lshl_add_u64 v[22:23], v[22:23], 0, v[24:25]
	v_lshl_add_u64 v[22:23], v[22:23], 0, s[14:15]
	v_lshl_add_u64 v[32:33], v[22:23], 0, v[66:67]
	ds_read_b128 v[22:25], v72 offset:1040
	v_ashrrev_i32_e32 v37, 31, v36
	v_or_b32_e32 v44, 7, v60
	v_add_u32_e32 v48, 0xffffe007, v60
	v_ashrrev_i32_e32 v45, 31, v44
	v_or_b32_e32 v52, 9, v60
	v_add_u32_e32 v56, 0xffffe009, v60
	v_ashrrev_i32_e32 v53, 31, v52
	v_or_b32_e32 v76, 11, v60
	v_add_u32_e32 v61, 0xffffe00b, v60
	v_ashrrev_i32_e32 v77, 31, v76
	v_or_b32_e32 v84, 13, v60
	v_ashrrev_i32_e32 v85, 31, v84
	v_or_b32_e32 v59, 15, v59
	v_and_b32_e32 v97, 32, v69
	v_and_b32_e32 v110, 16, v69
	v_and_b32_e32 v111, 8, v69
	v_and_b32_e32 v112, 4, v69
	v_readlane_b32 s46, v245, 2
	v_readlane_b32 s47, v245, 3
	v_readlane_b32 s50, v245, 6
	v_readlane_b32 s51, v245, 7
	v_readlane_b32 s52, v245, 8
	v_readlane_b32 s53, v245, 9
	v_readlane_b32 s54, v245, 10
	v_readlane_b32 s55, v245, 11
	v_readlane_b32 s56, v245, 12
	v_readlane_b32 s57, v245, 13
	v_readlane_b32 s58, v245, 14
	v_readlane_b32 s59, v245, 15
	s_waitcnt vmcnt(15)
	v_pk_add_f32 v[10:11], v[10:11], 1.0 op_sel_hi:[1,0]
	v_pk_add_f32 v[12:13], v[12:13], 1.0 op_sel_hi:[1,0]
	s_waitcnt lgkmcnt(1)
	v_pk_fma_f32 v[6:7], v[2:3], v[18:19], v[6:7]
	s_waitcnt vmcnt(14)
	v_pk_mul_f32 v[64:65], v[14:15], v[10:11]
	v_pk_fma_f32 v[8:9], v[4:5], v[20:21], v[8:9]
	v_pk_mul_f32 v[70:71], v[16:17], v[12:13]
	v_pk_mul_f32 v[10:11], v[64:65], v[6:7]
	v_pk_mul_f32 v[12:13], v[70:71], v[8:9]
	v_cvt_pk_bf16_f32 v10, v10, v11
	v_cvt_pk_bf16_f32 v11, v12, v13
	global_store_dwordx4 v[26:27], v[6:9], off
	global_store_dwordx2 v[28:29], v[10:11], off
	v_or_b32_e32 v26, 2, v60
	v_lshlrev_b64 v[14:15], 12, v[30:31]
	v_add_u32_e32 v18, 0xffffe002, v60
	v_ashrrev_i32_e32 v27, 31, v26
	v_cmp_gt_i32_e32 vcc, s41, v26
	v_lshl_add_u64 v[14:15], s[74:75], 0, v[14:15]
	v_lshlrev_b64 v[16:17], 11, v[30:31]
	v_cndmask_b32_e32 v19, 0, v27, vcc
	v_cndmask_b32_e32 v18, v18, v26, vcc
	v_lshl_add_u64 v[14:15], v[14:15], 0, s[14:15]
	v_cndmask_b32_e32 v21, v1, v86, vcc
	v_cndmask_b32_e32 v20, v87, v88, vcc
	v_lshl_add_u64 v[16:17], s[10:11], 0, v[16:17]
	v_lshlrev_b64 v[18:19], 12, v[18:19]
	v_lshl_add_u64 v[14:15], v[14:15], 0, v[66:67]
	v_lshl_add_u64 v[18:19], v[20:21], 0, v[18:19]
	v_lshl_add_u64 v[16:17], v[16:17], 0, s[16:17]
	v_lshl_add_u64 v[18:19], v[18:19], 0, s[14:15]
	v_lshl_add_u64 v[16:17], v[16:17], 0, v[62:63]
	v_lshl_add_u64 v[18:19], v[18:19], 0, v[66:67]
	v_or_b32_e32 v28, 3, v60
	v_add_u32_e32 v32, 0xffffe003, v60
	v_ashrrev_i32_e32 v29, 31, v28
	v_cmp_gt_i32_e32 vcc, s41, v28
	v_lshlrev_b64 v[30:31], 12, v[26:27]
	v_lshlrev_b64 v[26:27], 11, v[26:27]
	v_cndmask_b32_e32 v33, 0, v29, vcc
	v_cndmask_b32_e32 v32, v32, v28, vcc
	v_cndmask_b32_e32 v35, v1, v86, vcc
	v_cndmask_b32_e32 v34, v87, v88, vcc
	v_lshl_add_u64 v[30:31], s[74:75], 0, v[30:31]
	v_lshl_add_u64 v[26:27], s[10:11], 0, v[26:27]
	v_lshlrev_b64 v[32:33], 12, v[32:33]
	v_lshl_add_u64 v[32:33], v[34:35], 0, v[32:33]
	v_lshl_add_u64 v[30:31], v[30:31], 0, s[14:15]
	v_lshl_add_u64 v[26:27], v[26:27], 0, s[16:17]
	v_lshl_add_u64 v[32:33], v[32:33], 0, s[14:15]
	v_lshl_add_u64 v[30:31], v[30:31], 0, v[66:67]
	v_lshl_add_u64 v[26:27], v[26:27], 0, v[62:63]
	v_lshl_add_u64 v[32:33], v[32:33], 0, v[66:67]
	v_or_b32_e32 v34, 4, v60
	v_ashrrev_i32_e32 v35, 31, v34
	v_cmp_gt_i32_e32 vcc, s41, v34
	v_lshlrev_b64 v[38:39], 12, v[34:35]
	v_lshl_add_u64 v[38:39], s[74:75], 0, v[38:39]
	v_lshl_add_u64 v[38:39], v[38:39], 0, s[14:15]
	v_lshl_add_u64 v[38:39], v[38:39], 0, v[66:67]
	v_pk_mul_f32 v[6:7], v[6:7], v[6:7]
	v_pk_mul_f32 v[8:9], v[8:9], v[8:9]
	v_add_f32_e32 v6, v6, v7
	v_add_f32_e32 v6, v6, v8
	s_waitcnt vmcnt(15) lgkmcnt(0)
	v_pk_fma_f32 v[10:11], v[2:3], v[22:23], v[120:121]
	v_pk_fma_f32 v[12:13], v[4:5], v[24:25], v[122:123]
	global_store_dwordx4 v[14:15], v[10:13], off
	v_pk_mul_f32 v[14:15], v[64:65], v[10:11]
	v_pk_mul_f32 v[20:21], v[70:71], v[12:13]
	v_cvt_pk_bf16_f32 v14, v14, v15
	v_cvt_pk_bf16_f32 v15, v20, v21
	global_store_dwordx2 v[16:17], v[14:15], off
	global_load_dwordx4 v[120:123], v[246:247], off offset:-4096
	ds_read_b128 v[18:21], v72 offset:2080
	ds_read_b128 v[22:25], v72 offset:3120
	s_waitcnt vmcnt(17) lgkmcnt(1)
	v_pk_fma_f32 v[14:15], v[2:3], v[18:19], v[124:125]
	v_pk_fma_f32 v[16:17], v[4:5], v[20:21], v[126:127]
	v_pk_mul_f32 v[18:19], v[64:65], v[14:15]
	v_pk_mul_f32 v[20:21], v[70:71], v[16:17]
	v_cvt_pk_bf16_f32 v18, v18, v19
	v_cvt_pk_bf16_f32 v19, v20, v21
	global_store_dwordx4 v[30:31], v[14:17], off
	global_store_dwordx2 v[26:27], v[18:19], off
	v_add_u32_e32 v30, 0xffffe004, v60
	v_lshlrev_b64 v[26:27], 12, v[28:29]
	v_lshlrev_b64 v[28:29], 11, v[28:29]
	v_cndmask_b32_e32 v31, 0, v35, vcc
	v_cndmask_b32_e32 v30, v30, v34, vcc
	v_cndmask_b32_e32 v33, v1, v86, vcc
	v_cndmask_b32_e32 v32, v87, v88, vcc
	v_lshl_add_u64 v[26:27], s[74:75], 0, v[26:27]
	v_lshl_add_u64 v[28:29], s[10:11], 0, v[28:29]
	v_lshlrev_b64 v[30:31], 12, v[30:31]
	v_lshl_add_u64 v[30:31], v[32:33], 0, v[30:31]
	v_lshl_add_u64 v[26:27], v[26:27], 0, s[14:15]
	v_lshl_add_u64 v[28:29], v[28:29], 0, s[16:17]
	v_lshl_add_u64 v[30:31], v[30:31], 0, s[14:15]
	v_lshl_add_u64 v[26:27], v[26:27], 0, v[66:67]
	v_lshl_add_u64 v[28:29], v[28:29], 0, v[62:63]
	v_lshl_add_u64 v[30:31], v[30:31], 0, v[66:67]
	v_cmp_gt_i32_e32 vcc, s41, v36
	v_lshlrev_b64 v[34:35], 11, v[34:35]
	v_lshl_add_u64 v[34:35], s[10:11], 0, v[34:35]
	v_cndmask_b32_e32 v41, 0, v37, vcc
	v_cndmask_b32_e32 v40, v40, v36, vcc
	v_cndmask_b32_e32 v43, v1, v86, vcc
	v_cndmask_b32_e32 v42, v87, v88, vcc
	v_lshlrev_b64 v[40:41], 12, v[40:41]
	v_lshl_add_u64 v[40:41], v[42:43], 0, v[40:41]
	v_lshl_add_u64 v[34:35], v[34:35], 0, s[16:17]
	v_lshl_add_u64 v[40:41], v[40:41], 0, s[14:15]
	v_lshl_add_u64 v[34:35], v[34:35], 0, v[62:63]
	v_lshl_add_u64 v[40:41], v[40:41], 0, v[66:67]
	v_or_b32_e32 v42, 6, v60
	v_ashrrev_i32_e32 v43, 31, v42
	v_cmp_gt_i32_e32 vcc, s41, v42
	v_lshlrev_b64 v[46:47], 12, v[42:43]
	v_lshl_add_u64 v[46:47], s[74:75], 0, v[46:47]
	v_lshl_add_u64 v[46:47], v[46:47], 0, s[14:15]
	v_lshl_add_u64 v[46:47], v[46:47], 0, v[66:67]
	s_waitcnt vmcnt(18) lgkmcnt(0)
	v_pk_fma_f32 v[18:19], v[2:3], v[22:23], v[128:129]
	v_pk_fma_f32 v[20:21], v[4:5], v[24:25], v[130:131]
	v_pk_mul_f32 v[22:23], v[64:65], v[18:19]
	v_pk_mul_f32 v[24:25], v[70:71], v[20:21]
	v_cvt_pk_bf16_f32 v22, v22, v23
	v_cvt_pk_bf16_f32 v23, v24, v25
	global_store_dwordx4 v[26:27], v[18:21], off
	global_store_dwordx2 v[28:29], v[22:23], off
	ds_read_b128 v[26:29], v72 offset:4160
	ds_read_b128 v[30:33], v72 offset:5200
	s_waitcnt vmcnt(19) lgkmcnt(1)
	v_pk_fma_f32 v[22:23], v[2:3], v[26:27], v[132:133]
	v_pk_fma_f32 v[24:25], v[4:5], v[28:29], v[134:135]
	v_pk_mul_f32 v[26:27], v[64:65], v[22:23]
	v_pk_mul_f32 v[28:29], v[70:71], v[24:25]
	v_cvt_pk_bf16_f32 v26, v26, v27
	v_cvt_pk_bf16_f32 v27, v28, v29
	global_store_dwordx4 v[38:39], v[22:25], off
	global_store_dwordx2 v[34:35], v[26:27], off
	v_add_u32_e32 v38, 0xffffe006, v60
	v_lshlrev_b64 v[34:35], 12, v[36:37]
	v_lshlrev_b64 v[36:37], 11, v[36:37]
	v_cndmask_b32_e32 v39, 0, v43, vcc
	v_cndmask_b32_e32 v38, v38, v42, vcc
	v_cndmask_b32_e32 v41, v1, v86, vcc
	v_cndmask_b32_e32 v40, v87, v88, vcc
	v_lshl_add_u64 v[34:35], s[74:75], 0, v[34:35]
	v_lshl_add_u64 v[36:37], s[10:11], 0, v[36:37]
	v_lshlrev_b64 v[38:39], 12, v[38:39]
	v_lshl_add_u64 v[38:39], v[40:41], 0, v[38:39]
	v_lshl_add_u64 v[34:35], v[34:35], 0, s[14:15]
	v_lshl_add_u64 v[36:37], v[36:37], 0, s[16:17]
	v_lshl_add_u64 v[38:39], v[38:39], 0, s[14:15]
	v_lshl_add_u64 v[34:35], v[34:35], 0, v[66:67]
	v_lshl_add_u64 v[36:37], v[36:37], 0, v[62:63]
	v_lshl_add_u64 v[38:39], v[38:39], 0, v[66:67]
	v_cmp_gt_i32_e32 vcc, s41, v44
	v_lshlrev_b64 v[42:43], 11, v[42:43]
	v_lshl_add_u64 v[42:43], s[10:11], 0, v[42:43]
	v_cndmask_b32_e32 v49, 0, v45, vcc
	v_cndmask_b32_e32 v48, v48, v44, vcc
	v_cndmask_b32_e32 v51, v1, v86, vcc
	v_cndmask_b32_e32 v50, v87, v88, vcc
	v_lshlrev_b64 v[48:49], 12, v[48:49]
	v_lshl_add_u64 v[48:49], v[50:51], 0, v[48:49]
	v_lshl_add_u64 v[42:43], v[42:43], 0, s[16:17]
	v_lshl_add_u64 v[48:49], v[48:49], 0, s[14:15]
	v_lshl_add_u64 v[42:43], v[42:43], 0, v[62:63]
	v_lshl_add_u64 v[48:49], v[48:49], 0, v[66:67]
	v_or_b32_e32 v50, 8, v60
	v_ashrrev_i32_e32 v51, 31, v50
	v_cmp_gt_i32_e32 vcc, s41, v50
	v_lshlrev_b64 v[54:55], 12, v[50:51]
	v_lshl_add_u64 v[54:55], s[74:75], 0, v[54:55]
	v_lshl_add_u64 v[54:55], v[54:55], 0, s[14:15]
	v_lshl_add_u64 v[54:55], v[54:55], 0, v[66:67]
	s_waitcnt vmcnt(20) lgkmcnt(0)
	v_pk_fma_f32 v[26:27], v[2:3], v[30:31], v[136:137]
	v_pk_fma_f32 v[28:29], v[4:5], v[32:33], v[138:139]
	v_pk_mul_f32 v[30:31], v[64:65], v[26:27]
	v_pk_mul_f32 v[32:33], v[70:71], v[28:29]
	v_cvt_pk_bf16_f32 v30, v30, v31
	v_cvt_pk_bf16_f32 v31, v32, v33
	global_store_dwordx4 v[34:35], v[26:29], off
	global_store_dwordx2 v[36:37], v[30:31], off
	ds_read_b128 v[34:37], v72 offset:6240
	ds_read_b128 v[38:41], v72 offset:7280
	s_waitcnt vmcnt(21) lgkmcnt(1)
	v_pk_fma_f32 v[30:31], v[2:3], v[34:35], v[140:141]
	v_pk_fma_f32 v[32:33], v[4:5], v[36:37], v[142:143]
	v_pk_mul_f32 v[34:35], v[64:65], v[30:31]
	v_pk_mul_f32 v[36:37], v[70:71], v[32:33]
	v_cvt_pk_bf16_f32 v34, v34, v35
	v_cvt_pk_bf16_f32 v35, v36, v37
	global_store_dwordx4 v[46:47], v[30:33], off
	global_store_dwordx2 v[42:43], v[34:35], off
	v_add_u32_e32 v46, 0xffffe008, v60
	v_lshlrev_b64 v[42:43], 12, v[44:45]
	v_lshlrev_b64 v[44:45], 11, v[44:45]
	v_cndmask_b32_e32 v47, 0, v51, vcc
	v_cndmask_b32_e32 v46, v46, v50, vcc
	v_cndmask_b32_e32 v49, v1, v86, vcc
	v_cndmask_b32_e32 v48, v87, v88, vcc
	v_lshl_add_u64 v[42:43], s[74:75], 0, v[42:43]
	v_lshl_add_u64 v[44:45], s[10:11], 0, v[44:45]
	v_lshlrev_b64 v[46:47], 12, v[46:47]
	v_lshl_add_u64 v[46:47], v[48:49], 0, v[46:47]
	v_lshl_add_u64 v[42:43], v[42:43], 0, s[14:15]
	v_lshl_add_u64 v[44:45], v[44:45], 0, s[16:17]
	v_lshl_add_u64 v[46:47], v[46:47], 0, s[14:15]
	v_lshl_add_u64 v[42:43], v[42:43], 0, v[66:67]
	v_lshl_add_u64 v[44:45], v[44:45], 0, v[62:63]
	v_lshl_add_u64 v[46:47], v[46:47], 0, v[66:67]
	v_cmp_gt_i32_e32 vcc, s41, v52
	v_lshlrev_b64 v[50:51], 11, v[50:51]
	v_lshl_add_u64 v[50:51], s[10:11], 0, v[50:51]
	v_cndmask_b32_e32 v57, 0, v53, vcc
	v_cndmask_b32_e32 v56, v56, v52, vcc
	v_cndmask_b32_e32 v75, v1, v86, vcc
	v_cndmask_b32_e32 v74, v87, v88, vcc
	v_lshlrev_b64 v[56:57], 12, v[56:57]
	v_lshl_add_u64 v[56:57], v[74:75], 0, v[56:57]
	v_lshl_add_u64 v[50:51], v[50:51], 0, s[16:17]
	v_lshl_add_u64 v[56:57], v[56:57], 0, s[14:15]
	v_lshl_add_u64 v[50:51], v[50:51], 0, v[62:63]
	v_lshl_add_u64 v[56:57], v[56:57], 0, v[66:67]
	v_or_b32_e32 v74, 10, v60
	v_ashrrev_i32_e32 v75, 31, v74
	v_cmp_gt_i32_e32 vcc, s41, v74
	v_lshlrev_b64 v[78:79], 12, v[74:75]
	v_lshl_add_u64 v[78:79], s[74:75], 0, v[78:79]
	v_lshl_add_u64 v[78:79], v[78:79], 0, s[14:15]
	v_lshl_add_u64 v[78:79], v[78:79], 0, v[66:67]
	s_waitcnt vmcnt(22) lgkmcnt(0)
	v_pk_fma_f32 v[34:35], v[2:3], v[38:39], v[144:145]
	v_pk_fma_f32 v[36:37], v[4:5], v[40:41], v[146:147]
	v_pk_mul_f32 v[38:39], v[64:65], v[34:35]
	v_pk_mul_f32 v[40:41], v[70:71], v[36:37]
	v_cvt_pk_bf16_f32 v38, v38, v39
	v_cvt_pk_bf16_f32 v39, v40, v41
	global_store_dwordx4 v[42:43], v[34:37], off
	global_store_dwordx2 v[44:45], v[38:39], off
	ds_read_b128 v[42:45], v72 offset:8320
	ds_read_b128 v[46:49], v72 offset:9360
	s_waitcnt vmcnt(23) lgkmcnt(1)
	v_pk_fma_f32 v[38:39], v[2:3], v[42:43], v[148:149]
	v_pk_fma_f32 v[40:41], v[4:5], v[44:45], v[150:151]
	v_pk_mul_f32 v[42:43], v[64:65], v[38:39]
	v_pk_mul_f32 v[44:45], v[70:71], v[40:41]
	v_cvt_pk_bf16_f32 v42, v42, v43
	v_cvt_pk_bf16_f32 v43, v44, v45
	global_store_dwordx4 v[54:55], v[38:41], off
	global_store_dwordx2 v[50:51], v[42:43], off
	v_add_u32_e32 v54, 0xffffe00a, v60
	v_lshlrev_b64 v[50:51], 12, v[52:53]
	v_lshlrev_b64 v[52:53], 11, v[52:53]
	v_cndmask_b32_e32 v55, 0, v75, vcc
	v_cndmask_b32_e32 v54, v54, v74, vcc
	v_cndmask_b32_e32 v57, v1, v86, vcc
	v_cndmask_b32_e32 v56, v87, v88, vcc
	v_lshl_add_u64 v[50:51], s[74:75], 0, v[50:51]
	v_lshl_add_u64 v[52:53], s[10:11], 0, v[52:53]
	v_lshlrev_b64 v[54:55], 12, v[54:55]
	v_lshl_add_u64 v[54:55], v[56:57], 0, v[54:55]
	v_lshl_add_u64 v[50:51], v[50:51], 0, s[14:15]
	v_lshl_add_u64 v[52:53], v[52:53], 0, s[16:17]
	v_lshl_add_u64 v[54:55], v[54:55], 0, s[14:15]
	v_lshl_add_u64 v[50:51], v[50:51], 0, v[66:67]
	v_lshl_add_u64 v[52:53], v[52:53], 0, v[62:63]
	v_lshl_add_u64 v[54:55], v[54:55], 0, v[66:67]
	v_cmp_gt_i32_e32 vcc, s41, v76
	v_lshlrev_b64 v[74:75], 11, v[74:75]
	v_lshl_add_u64 v[74:75], s[10:11], 0, v[74:75]
	v_cndmask_b32_e32 v81, 0, v77, vcc
	v_cndmask_b32_e32 v80, v61, v76, vcc
	v_cndmask_b32_e32 v83, v1, v86, vcc
	v_cndmask_b32_e32 v82, v87, v88, vcc
	v_lshlrev_b64 v[80:81], 12, v[80:81]
	v_lshl_add_u64 v[80:81], v[82:83], 0, v[80:81]
	v_lshl_add_u64 v[74:75], v[74:75], 0, s[16:17]
	v_lshl_add_u64 v[80:81], v[80:81], 0, s[14:15]
	v_lshl_add_u64 v[74:75], v[74:75], 0, v[62:63]
	v_lshl_add_u64 v[80:81], v[80:81], 0, v[66:67]
	v_or_b32_e32 v82, 12, v60
	v_add_u32_e32 v61, 0xffffe00c, v60
	v_ashrrev_i32_e32 v83, 31, v82
	v_cmp_gt_i32_e32 vcc, s41, v82
	v_lshlrev_b64 v[98:99], 12, v[82:83]
	v_lshl_add_u64 v[98:99], s[74:75], 0, v[98:99]
	v_lshl_add_u64 v[98:99], v[98:99], 0, s[14:15]
	v_lshl_add_u64 v[98:99], v[98:99], 0, v[66:67]
	s_waitcnt vmcnt(24) lgkmcnt(0)
	v_pk_fma_f32 v[42:43], v[2:3], v[46:47], v[152:153]
	v_pk_fma_f32 v[44:45], v[4:5], v[48:49], v[154:155]
	v_pk_mul_f32 v[46:47], v[64:65], v[42:43]
	v_pk_mul_f32 v[48:49], v[70:71], v[44:45]
	v_cvt_pk_bf16_f32 v46, v46, v47
	v_cvt_pk_bf16_f32 v47, v48, v49
	global_store_dwordx4 v[50:51], v[42:45], off
	global_store_dwordx2 v[52:53], v[46:47], off
	ds_read_b128 v[50:53], v72 offset:10400
	ds_read_b128 v[54:57], v72 offset:11440
	s_waitcnt vmcnt(25) lgkmcnt(1)
	v_pk_fma_f32 v[46:47], v[2:3], v[50:51], v[156:157]
	v_pk_fma_f32 v[48:49], v[4:5], v[52:53], v[158:159]
	v_pk_mul_f32 v[50:51], v[64:65], v[46:47]
	v_pk_mul_f32 v[52:53], v[70:71], v[48:49]
	v_cvt_pk_bf16_f32 v50, v50, v51
	v_cvt_pk_bf16_f32 v51, v52, v53
	global_store_dwordx4 v[78:79], v[46:49], off
	global_store_dwordx2 v[74:75], v[50:51], off
	v_lshlrev_b64 v[74:75], 12, v[76:77]
	v_lshlrev_b64 v[76:77], 11, v[76:77]
	v_cndmask_b32_e32 v79, 0, v83, vcc
	v_cndmask_b32_e32 v78, v61, v82, vcc
	v_cndmask_b32_e32 v81, v1, v86, vcc
	v_cndmask_b32_e32 v80, v87, v88, vcc
	v_lshl_add_u64 v[74:75], s[74:75], 0, v[74:75]
	v_lshl_add_u64 v[76:77], s[10:11], 0, v[76:77]
	v_lshlrev_b64 v[78:79], 12, v[78:79]
	v_lshl_add_u64 v[78:79], v[80:81], 0, v[78:79]
	v_lshl_add_u64 v[74:75], v[74:75], 0, s[14:15]
	v_lshl_add_u64 v[76:77], v[76:77], 0, s[16:17]
	v_lshl_add_u64 v[78:79], v[78:79], 0, s[14:15]
	v_lshl_add_u64 v[74:75], v[74:75], 0, v[66:67]
	v_lshl_add_u64 v[76:77], v[76:77], 0, v[62:63]
	v_lshl_add_u64 v[78:79], v[78:79], 0, v[66:67]
	v_add_u32_e32 v61, 0xffffe00d, v60
	v_cmp_gt_i32_e32 vcc, s41, v84
	v_lshlrev_b64 v[82:83], 11, v[82:83]
	v_lshl_add_u64 v[82:83], s[10:11], 0, v[82:83]
	v_cndmask_b32_e32 v101, 0, v85, vcc
	v_cndmask_b32_e32 v100, v61, v84, vcc
	v_cndmask_b32_e32 v103, v1, v86, vcc
	v_cndmask_b32_e32 v102, v87, v88, vcc
	v_lshlrev_b64 v[100:101], 12, v[100:101]
	v_lshl_add_u64 v[100:101], v[102:103], 0, v[100:101]
	v_lshl_add_u64 v[82:83], v[82:83], 0, s[16:17]
	v_lshl_add_u64 v[100:101], v[100:101], 0, s[14:15]
	v_lshl_add_u64 v[82:83], v[82:83], 0, v[62:63]
	v_lshl_add_u64 v[100:101], v[100:101], 0, v[66:67]
	v_cmp_lt_i32_e32 vcc, v91, v90
	v_or_b32_e32 v102, 14, v60
	v_ashrrev_i32_e32 v103, 31, v102
	v_cndmask_b32_e32 v73, v89, v91, vcc
	v_cmp_gt_i32_e32 vcc, s41, v102
	v_lshlrev_b32_e32 v114, 2, v73
	s_waitcnt vmcnt(26) lgkmcnt(0)
	v_pk_fma_f32 v[50:51], v[2:3], v[54:55], v[160:161]
	v_pk_fma_f32 v[52:53], v[4:5], v[56:57], v[162:163]
	v_pk_mul_f32 v[54:55], v[64:65], v[50:51]
	v_pk_mul_f32 v[56:57], v[70:71], v[52:53]
	v_cvt_pk_bf16_f32 v54, v54, v55
	v_cvt_pk_bf16_f32 v55, v56, v57
	global_store_dwordx4 v[74:75], v[50:53], off
	global_store_dwordx2 v[76:77], v[54:55], off
	ds_read_b128 v[74:77], v72 offset:12480
	ds_read_b128 v[78:81], v72 offset:13520
	s_waitcnt vmcnt(27) lgkmcnt(1)
	v_pk_fma_f32 v[54:55], v[2:3], v[74:75], v[164:165]
	v_pk_fma_f32 v[56:57], v[4:5], v[76:77], v[166:167]
	v_pk_mul_f32 v[74:75], v[64:65], v[54:55]
	v_pk_mul_f32 v[76:77], v[70:71], v[56:57]
	v_cvt_pk_bf16_f32 v74, v74, v75
	v_cvt_pk_bf16_f32 v75, v76, v77
	global_store_dwordx4 v[98:99], v[54:57], off
	global_store_dwordx2 v[82:83], v[74:75], off
	v_add_u32_e32 v98, 0xffffe00e, v60
	v_lshlrev_b64 v[60:61], 12, v[84:85]
	v_lshl_add_u64 v[60:61], s[74:75], 0, v[60:61]
	v_lshlrev_b64 v[82:83], 11, v[84:85]
	v_cndmask_b32_e32 v85, 0, v103, vcc
	v_cndmask_b32_e32 v84, v98, v102, vcc
	v_lshl_add_u64 v[60:61], v[60:61], 0, s[14:15]
	v_cndmask_b32_e32 v99, v1, v86, vcc
	v_cndmask_b32_e32 v98, v87, v88, vcc
	v_lshl_add_u64 v[82:83], s[10:11], 0, v[82:83]
	v_lshlrev_b64 v[84:85], 12, v[84:85]
	v_lshl_add_u64 v[60:61], v[60:61], 0, v[66:67]
	v_lshl_add_u64 v[84:85], v[98:99], 0, v[84:85]
	v_lshl_add_u64 v[82:83], v[82:83], 0, s[16:17]
	v_lshl_add_u64 v[84:85], v[84:85], 0, s[14:15]
	v_lshl_add_u64 v[82:83], v[82:83], 0, v[62:63]
	v_lshl_add_u64 v[84:85], v[84:85], 0, v[66:67]
	v_cmp_lt_i32_e32 vcc, v92, v90
	v_mad_u64_u32 v[98:99], s[4:5], v59, s40, v[66:67]
	v_cmp_eq_u32_e64 s[4:5], 0, v110
	s_waitcnt vmcnt(28) lgkmcnt(0)
	v_pk_fma_f32 v[74:75], v[2:3], v[78:79], v[168:169]
	v_pk_fma_f32 v[76:77], v[4:5], v[80:81], v[170:171]
	global_store_dwordx4 v[60:61], v[74:77], off
	v_pk_mul_f32 v[60:61], v[64:65], v[74:75]
	v_pk_mul_f32 v[78:79], v[70:71], v[76:77]
	v_cvt_pk_bf16_f32 v60, v60, v61
	v_cvt_pk_bf16_f32 v61, v78, v79
	global_store_dwordx2 v[82:83], v[60:61], off
	v_cndmask_b32_e32 v60, v89, v92, vcc
	v_cmp_lt_i32_e32 vcc, v93, v90
	v_lshlrev_b32_e32 v115, 2, v60
	v_add_u32_e32 v60, s12, v59
	v_cndmask_b32_e32 v61, v89, v93, vcc
	v_cmp_lt_i32_e32 vcc, v94, v90
	v_add_u32_e32 v59, 0xffffe000, v60
	v_lshlrev_b32_e32 v116, 2, v61
	v_cndmask_b32_e32 v82, v89, v94, vcc
	v_cmp_lt_i32_e32 vcc, v95, v90
	v_ashrrev_i32_e32 v61, 31, v60
	v_lshlrev_b32_e32 v117, 2, v82
	v_cndmask_b32_e32 v83, v89, v95, vcc
	v_cmp_lt_i32_e32 vcc, v96, v90
	v_lshlrev_b32_e32 v118, 2, v83
	ds_read_b128 v[82:85], v72 offset:14560
	ds_read_b128 v[98:101], v98
	v_cndmask_b32_e32 v113, v89, v96, vcc
	v_cmp_gt_i32_e32 vcc, s41, v60
	v_lshlrev_b64 v[72:73], 12, v[102:103]
	v_lshlrev_b64 v[102:103], 11, v[102:103]
	v_cndmask_b32_e32 v104, v59, v60, vcc
	v_add_f32_e32 v59, v6, v9
	v_pk_mul_f32 v[6:7], v[10:11], v[10:11]
	v_cndmask_b32_e32 v105, 0, v61, vcc
	v_pk_mul_f32 v[8:9], v[12:13], v[12:13]
	v_add_f32_e32 v6, v6, v7
	v_cndmask_b32_e32 v107, v1, v86, vcc
	v_cndmask_b32_e32 v106, v87, v88, vcc
	v_lshlrev_b64 v[104:105], 12, v[104:105]
	v_add_f32_e32 v6, v6, v8
	v_lshl_add_u64 v[104:105], v[106:107], 0, v[104:105]
	v_add_f32_e32 v106, v6, v9
	v_pk_mul_f32 v[6:7], v[14:15], v[14:15]
	v_pk_mul_f32 v[8:9], v[16:17], v[16:17]
	v_add_f32_e32 v6, v6, v7
	v_add_f32_e32 v6, v6, v8
	v_add_f32_e32 v107, v6, v9
	v_pk_mul_f32 v[6:7], v[18:19], v[18:19]
	v_pk_mul_f32 v[8:9], v[20:21], v[20:21]
	v_add_f32_e32 v6, v6, v7
	v_add_f32_e32 v6, v6, v8
	v_add_f32_e32 v20, v6, v9
	v_pk_mul_f32 v[6:7], v[22:23], v[22:23]
	v_pk_mul_f32 v[8:9], v[24:25], v[24:25]
	v_add_f32_e32 v6, v6, v7
	v_add_f32_e32 v6, v6, v8
	v_add_f32_e32 v21, v6, v9
	v_pk_mul_f32 v[6:7], v[26:27], v[26:27]
	v_pk_mul_f32 v[8:9], v[28:29], v[28:29]
	v_add_f32_e32 v6, v6, v7
	v_add_f32_e32 v6, v6, v8
	v_add_f32_e32 v22, v6, v9
	v_pk_mul_f32 v[6:7], v[30:31], v[30:31]
	v_pk_mul_f32 v[8:9], v[32:33], v[32:33]
	v_add_f32_e32 v6, v6, v7
	v_add_f32_e32 v6, v6, v8
	v_lshl_add_u64 v[72:73], s[74:75], 0, v[72:73]
	v_lshl_add_u64 v[102:103], s[10:11], 0, v[102:103]
	v_add_f32_e32 v23, v6, v9
	v_lshl_add_u64 v[72:73], v[72:73], 0, s[14:15]
	v_lshl_add_u64 v[102:103], v[102:103], 0, s[16:17]
	v_lshl_add_u64 v[104:105], v[104:105], 0, s[14:15]
	v_lshl_add_u64 v[72:73], v[72:73], 0, v[66:67]
	v_lshl_add_u64 v[102:103], v[102:103], 0, v[62:63]
	v_lshl_add_u64 v[104:105], v[104:105], 0, v[66:67]
	v_pk_mul_f32 v[14:15], v[34:35], v[34:35]
	v_pk_mul_f32 v[16:17], v[36:37], v[36:37]
	v_add_f32_e32 v14, v14, v15
	v_add_f32_e32 v14, v14, v16
	v_add_f32_e32 v24, v14, v17
	v_pk_mul_f32 v[14:15], v[38:39], v[38:39]
	v_pk_mul_f32 v[16:17], v[40:41], v[40:41]
	v_add_f32_e32 v14, v14, v15
	v_add_f32_e32 v14, v14, v16
	v_add_f32_e32 v14, v14, v17
	v_cmp_eq_u32_e32 vcc, 0, v97
	v_pk_mul_f32 v[16:17], v[44:45], v[44:45]
	v_lshlrev_b64 v[108:109], 12, v[60:61]
	v_cndmask_b32_e32 v18, v14, v59, vcc
	s_waitcnt vmcnt(29) lgkmcnt(1)
	v_pk_fma_f32 v[6:7], v[2:3], v[82:83], v[172:173]
	v_pk_fma_f32 v[8:9], v[4:5], v[84:85], v[174:175]
	v_pk_mul_f32 v[10:11], v[64:65], v[6:7]
	v_pk_mul_f32 v[12:13], v[70:71], v[8:9]
	v_cvt_pk_bf16_f32 v10, v10, v11
	v_cvt_pk_bf16_f32 v11, v12, v13
	global_store_dwordx4 v[72:73], v[6:9], off
	global_store_dwordx2 v[102:103], v[10:11], off
	v_cndmask_b32_e32 v14, v59, v14, vcc
	ds_bpermute_b32 v19, v114, v14
	v_pk_mul_f32 v[14:15], v[42:43], v[42:43]
	v_pk_mul_f32 v[6:7], v[6:7], v[6:7]
	v_add_f32_e32 v14, v14, v15
	v_add_f32_e32 v14, v14, v16
	v_add_f32_e32 v25, v14, v17
	v_cndmask_b32_e32 v14, v106, v25, vcc
	ds_bpermute_b32 v26, v114, v14
	v_pk_mul_f32 v[14:15], v[46:47], v[46:47]
	v_pk_mul_f32 v[16:17], v[48:49], v[48:49]
	v_add_f32_e32 v14, v14, v15
	v_add_f32_e32 v14, v14, v16
	v_add_f32_e32 v14, v14, v17
	v_cndmask_b32_e32 v15, v107, v14, vcc
	ds_bpermute_b32 v15, v114, v15
	v_cndmask_b32_e32 v16, v25, v106, vcc
	v_cndmask_b32_e32 v14, v14, v107, vcc
	s_waitcnt lgkmcnt(1)
	v_add_f32_e32 v25, v16, v26
	v_pk_mul_f32 v[16:17], v[52:53], v[52:53]
	s_waitcnt lgkmcnt(0)
	v_add_f32_e32 v26, v14, v15
	v_pk_mul_f32 v[14:15], v[50:51], v[50:51]
	v_add_f32_e32 v27, v18, v19
	v_add_f32_e32 v14, v14, v15
	v_add_f32_e32 v16, v14, v16
	v_pk_mul_f32 v[14:15], v[54:55], v[54:55]
	v_pk_mul_f32 v[18:19], v[56:57], v[56:57]
	v_add_f32_e32 v14, v14, v15
	v_add_f32_e32 v14, v14, v18
	v_add_f32_e32 v14, v14, v19
	v_cndmask_b32_e32 v15, v21, v14, vcc
	ds_bpermute_b32 v15, v114, v15
	v_cndmask_b32_e32 v14, v14, v21, vcc
	v_add_f32_e32 v18, v16, v17
	v_cndmask_b32_e32 v16, v20, v18, vcc
	v_pk_mul_f32 v[8:9], v[8:9], v[8:9]
	s_waitcnt lgkmcnt(0)
	v_add_f32_e32 v14, v14, v15
	v_cndmask_b32_e64 v21, v14, v27, s[4:5]
	v_cndmask_b32_e64 v14, v27, v14, s[4:5]
	ds_bpermute_b32 v27, v115, v14
	v_pk_mul_f32 v[14:15], v[74:75], v[74:75]
	v_add_f32_e32 v6, v6, v7
	ds_bpermute_b32 v19, v114, v16
	v_pk_mul_f32 v[16:17], v[76:77], v[76:77]
	v_add_f32_e32 v14, v14, v15
	v_add_f32_e32 v6, v6, v8
	v_add_f32_e32 v14, v14, v16
	v_add_f32_e32 v6, v6, v9
	v_add_f32_e32 v14, v14, v17
	v_cndmask_b32_e32 v7, v23, v6, vcc
	v_cndmask_b32_e32 v15, v22, v14, vcc
	ds_bpermute_b32 v7, v114, v7
	ds_bpermute_b32 v15, v114, v15
	v_cndmask_b32_e32 v6, v6, v23, vcc
	v_cndmask_b32_e32 v16, v18, v20, vcc
	v_cndmask_b32_e32 v14, v14, v22, vcc
	s_waitcnt lgkmcnt(1)
	v_add_f32_e32 v18, v6, v7
	s_waitcnt lgkmcnt(0)
	v_add_f32_e32 v14, v14, v15
	v_cndmask_b32_e64 v6, v26, v18, s[4:5]
	v_add_f32_e32 v16, v16, v19
	v_cndmask_b32_e64 v8, v25, v14, s[4:5]
	ds_bpermute_b32 v19, v115, v6
	v_cndmask_b32_e64 v15, v14, v25, s[4:5]
	ds_bpermute_b32 v14, v115, v8
	v_add_f32_e32 v17, v21, v27
	v_lshl_add_u64 v[108:109], s[74:75], 0, v[108:109]
	v_lshlrev_b64 v[60:61], 11, v[60:61]
	s_waitcnt vmcnt(26)
	v_pk_fma_f32 v[2:3], v[2:3], v[98:99], v[120:121]
	v_pk_fma_f32 v[4:5], v[4:5], v[100:101], v[122:123]
	v_pk_mul_f32 v[6:7], v[2:3], v[2:3]
	v_pk_mul_f32 v[8:9], v[4:5], v[4:5]
	v_add_f32_e32 v6, v6, v7
	v_add_f32_e32 v6, v6, v8
	v_add_f32_e32 v6, v6, v9
	v_cndmask_b32_e32 v7, v24, v6, vcc
	ds_bpermute_b32 v7, v114, v7
	v_cndmask_b32_e32 v6, v6, v24, vcc
	v_cndmask_b32_e64 v8, v18, v26, s[4:5]
	s_waitcnt lgkmcnt(1)
	v_add_f32_e32 v10, v15, v14
	v_add_f32_e32 v8, v8, v19
	s_waitcnt lgkmcnt(0)
	v_add_f32_e32 v6, v6, v7
	v_cndmask_b32_e64 v7, v16, v6, s[4:5]
	ds_bpermute_b32 v7, v115, v7
	v_cndmask_b32_e64 v6, v6, v16, s[4:5]
	v_cmp_eq_u32_e32 vcc, 0, v111
	s_waitcnt lgkmcnt(0)
	v_add_f32_e32 v13, v6, v7
	v_cndmask_b32_e32 v11, v8, v17, vcc
	v_cndmask_b32_e32 v8, v17, v8, vcc
	v_cndmask_b32_e32 v6, v10, v13, vcc
	ds_bpermute_b32 v12, v116, v8
	ds_bpermute_b32 v14, v116, v6
	v_cndmask_b32_e32 v10, v13, v10, vcc
	v_cmp_eq_u32_e32 vcc, 0, v112
	v_lshl_add_u64 v[8:9], v[108:109], 0, s[14:15]
	s_waitcnt lgkmcnt(1)
	v_add_f32_e32 v11, v11, v12
	s_waitcnt lgkmcnt(0)
	v_add_f32_e32 v10, v10, v14
	v_cndmask_b32_e32 v12, v11, v10, vcc
	ds_bpermute_b32 v12, v117, v12
	v_lshl_add_u64 v[8:9], v[8:9], 0, v[66:67]
	global_store_dwordx4 v[8:9], v[2:5], off
	v_cndmask_b32_e32 v8, v10, v11, vcc
	v_lshl_add_u64 v[6:7], s[10:11], 0, v[60:61]
	s_waitcnt lgkmcnt(0)
	v_add_f32_e32 v10, v8, v12
	ds_bpermute_b32 v11, v118, v10
	v_pk_mul_f32 v[2:3], v[64:65], v[2:3]
	v_lshl_add_u64 v[6:7], v[6:7], 0, s[16:17]
	v_cvt_pk_bf16_f32 v8, v2, v3
	v_lshlrev_b32_e32 v3, 2, v113
	s_waitcnt lgkmcnt(0)
	v_add_f32_e32 v2, v10, v11
	ds_bpermute_b32 v3, v3, v2
	v_pk_mul_f32 v[4:5], v[70:71], v[4:5]
	s_nop 0
	v_cvt_pk_bf16_f32 v9, v4, v5
	v_lshl_add_u64 v[4:5], v[6:7], 0, v[62:63]
	global_store_dwordx2 v[4:5], v[8:9], off
	v_and_b32_e32 v4, 3, v69
	v_cmp_eq_u32_e32 vcc, 0, v4
	s_and_saveexec_b64 s[4:5], vcc
	s_cbranch_execz .LBB0_625
	s_lshl_b64 s[12:13], s[12:13], 2
	s_add_u32 s12, s23, s12
	s_addc_u32 s13, s24, s13
	v_ashrrev_i32_e32 v59, 31, v58
	s_waitcnt lgkmcnt(0)
	v_add_f32_e32 v4, v2, v3
	v_lshl_add_u64 v[2:3], v[58:59], 2, s[12:13]
	v_mov_b32_e32 v69, v67
	v_lshl_add_u64 v[2:3], v[2:3], 0, v[68:69]
	global_atomic_add_f32 v[2:3], v4, off
	s_branch .LBB0_625

.LBB0_877:
	s_cmp_lt_i32 s64, 10
	s_cselect_b64 s[4:5], -1, 0
	s_and_b64 s[0:1], s[4:5], s[0:1]
	s_and_b64 s[0:1], s[0:1], s[6:7]
	s_andn2_b64 vcc, exec, s[0:1]
	s_cbranch_vccnz .LBB0_884
	s_and_b32 s0, s62, 7
	s_cmp_lg_u32 s0, 0
	s_cselect_b64 s[0:1], -1, 0
	s_ashr_i32 s3, s62, 3
	s_add_u32 s8, s96, 0xda0000
	s_addc_u32 s9, s97, 0
	s_add_u32 s10, s96, 0x13a0000
	s_addc_u32 s11, s97, 0
	s_abs_i32 s12, s62
	v_cvt_f32_u32_e32 v1, s12
	v_cndmask_b32_e64 v0, 0, 1, s[0:1]
	s_sub_i32 s0, 0, s12
	s_lshl_b32 s15, s62, 3
	v_rcp_iflag_f32_e32 v1, v1
	s_ashr_i32 s13, s62, 31
	s_sub_i32 s14, 0, s62
	s_lshl_b32 s16, s2, 3
	v_mul_f32_e32 v1, 0x4f7ffffe, v1
	v_cvt_u32_f32_e32 v1, v1
	s_sub_i32 s17, 0, s15
	v_mov_b32_e32 v65, 0
	s_movk_i32 s19, 0x90
	v_readfirstlane_b32 s1, v1
	s_mul_i32 s0, s0, s1
	s_mul_hi_u32 s0, s1, s0
	s_add_i32 s18, s1, s0
	v_cmp_ne_u32_e64 s[0:1], 1, v0
	s_mov_b32 s20, 0xfffffc0
	s_mov_b32 s21, 0x20000
	s_mov_b32 s22, 0x40000
	s_mov_b32 s23, 0x60000
	s_movk_i32 s24, 0xff00
	s_movk_i32 s25, 0x410
	s_movk_i32 s26, 0x2000
	s_mov_b32 s101, 1
	s_branch .LBB0_880
.LBB0_879:
	s_ashr_i32 s5, s4, 31
	s_lshr_b32 s5, s5, 30
	s_add_i32 s5, s4, s5
	s_and_b32 s5, s5, 0xfffffc
	s_sub_i32 s4, s4, s5
	s_lshl_b32 s6, s4, 8
	s_ashr_i32 s7, s6, 31
	v_mov_b32_e32 v48, v212
	s_lshl_b32 s4, s27, 7
	s_lshl_b64 s[28:29], s[6:7], 11
	s_add_u32 s28, s8, s28
	v_ashrrev_i32_e32 v24, 3, v48
	v_ashrrev_i32_e32 v25, 31, v24
	s_addc_u32 s29, s9, s29
	v_lshlrev_b64 v[0:1], 11, v[24:25]
	v_lshlrev_b32_e32 v4, 4, v48
	v_lshl_add_u64 v[2:3], s[28:29], 0, v[0:1]
	v_and_b32_e32 v64, 0x70, v4
	v_lshl_add_u64 v[70:71], v[2:3], 0, v[64:65]
	v_add_co_u32_e32 v74, vcc, s21, v70
	s_ashr_i32 s5, s4, 31
	s_nop 0
	v_addc_co_u32_e32 v75, vcc, 0, v71, vcc
	s_lshl_b64 s[30:31], s[4:5], 11
	v_add_co_u32_e32 v76, vcc, s22, v70
	s_add_u32 s30, s10, s30
	s_nop 0
	v_addc_co_u32_e32 v77, vcc, 0, v71, vcc
	s_addc_u32 s31, s11, s31
	v_add_co_u32_e32 v78, vcc, s23, v70
	v_lshl_add_u64 v[0:1], s[30:31], 0, v[0:1]
	s_nop 0
	v_addc_co_u32_e32 v79, vcc, 0, v71, vcc
	v_lshl_add_u64 v[72:73], v[0:1], 0, v[64:65]
	global_load_dwordx4 v[0:3], v[70:71], off
	global_load_dwordx4 v[4:7], v[74:75], off
	global_load_dwordx4 v[8:11], v[76:77], off
	global_load_dwordx4 v[12:15], v[78:79], off
	global_load_dwordx4 v[16:19], v[72:73], off
	v_add_co_u32_e32 v80, vcc, s21, v72
	v_mad_u64_u32 v[68:69], s[28:29], v24, s19, v[64:65]
	s_nop 0
	v_addc_co_u32_e32 v81, vcc, 0, v73, vcc
	global_load_dwordx4 v[20:23], v[80:81], off
	global_load_dwordx4 v[24:27], v[70:71], off offset:128
	global_load_dwordx4 v[28:31], v[74:75], off offset:128
	global_load_dwordx4 v[32:35], v[78:79], off offset:128
	global_load_dwordx4 v[84:87], v[74:75], off offset:256
	global_load_dwordx4 v[36:39], v[76:77], off offset:128
	global_load_dwordx4 v[88:91], v[76:77], off offset:256
	global_load_dwordx4 v[92:95], v[70:71], off offset:256
	global_load_dwordx4 v[40:43], v[72:73], off offset:128
	global_load_dwordx4 v[96:99], v[72:73], off offset:256
	global_load_dwordx4 v[100:103], v[78:79], off offset:256
	global_load_dwordx4 v[44:47], v[80:81], off offset:128
	global_load_dwordx4 v[104:107], v[80:81], off offset:256
	s_cmp_eq_u32 s101, 0
	s_cbranch_scc1 .Lskew_done_g5
	s_mov_b32 s101, 0
	s_bitcmp1_b32 s2, 3
	s_cbranch_scc0 .Lskew_done_g5
	s_memrealtime s[98:99]
	s_waitcnt lgkmcnt(0)
	s_add_u32 s100, s98, 400

.Lskew_done_g5:
	v_add_u32_e32 v83, 0x12000, v68
	s_waitcnt vmcnt(17)
	ds_write_b128 v68, v[0:3]
	s_waitcnt vmcnt(16)
	ds_write_b128 v68, v[4:7] offset:9216
	s_waitcnt vmcnt(15)
	ds_write_b128 v68, v[8:11] offset:18432
	s_waitcnt vmcnt(14)
	ds_write_b128 v68, v[12:15] offset:27648
	s_waitcnt vmcnt(13)
	ds_write_b128 v68, v[16:19] offset:36864
	s_waitcnt vmcnt(12)
	ds_write_b128 v68, v[20:23] offset:46080
	s_waitcnt lgkmcnt(0)
	s_barrier
	global_load_dwordx4 v[108:111], v[74:75], off offset:384
	global_load_dwordx4 v[112:115], v[76:77], off offset:384
	global_load_dwordx4 v[116:119], v[70:71], off offset:384
	global_load_dwordx4 v[120:123], v[72:73], off offset:384
	global_load_dwordx4 v[124:127], v[78:79], off offset:384
	global_load_dwordx4 v[128:131], v[80:81], off offset:384
	v_and_b32_e32 v0, 31, v48
	v_lshrrev_b32_e32 v1, 1, v48
	v_and_or_b32 v2, v1, s20, v0
	v_and_b32_e32 v0, 16, v1
	v_and_b32_e32 v1, 0x5f, v48
	v_mad_u32_u24 v69, v1, s19, v0
	v_add_u32_e32 v64, 0x12000, v69
	s_waitcnt vmcnt(17)
	ds_write_b128 v83, v[24:27]
	s_waitcnt vmcnt(16)
	ds_write_b128 v83, v[28:31] offset:9216
	s_waitcnt vmcnt(13)
	ds_write_b128 v83, v[36:39] offset:18432
	ds_write_b128 v83, v[32:35] offset:27648
	s_waitcnt vmcnt(10)
	ds_write_b128 v83, v[40:43] offset:36864
	s_waitcnt vmcnt(7)
	ds_write_b128 v83, v[44:47] offset:46080
	v_mad_u64_u32 v[66:67], s[28:29], v2, s19, v[0:1]
	ds_read_b128 v[0:3], v69 offset:36864
	ds_read_b128 v[132:135], v69 offset:36896
	ds_read_b128 v[4:7], v69 offset:41472
	ds_read_b128 v[136:139], v69 offset:41504
	ds_read_b128 v[8:11], v66
	ds_read_b128 v[140:143], v66 offset:32
	ds_read_b128 v[12:15], v66 offset:4608
	ds_read_b128 v[144:147], v66 offset:4640
	s_setprio 1
	s_waitcnt lgkmcnt(3)
	v_mfma_f32_32x32x16_bf16 v[48:63], v[8:11], v[0:3], 0
	v_mfma_f32_32x32x16_bf16 v[16:31], v[8:11], v[4:7], 0
	s_waitcnt lgkmcnt(1)
	v_mfma_f32_32x32x16_bf16 v[32:47], v[12:15], v[0:3], 0
	v_mfma_f32_32x32x16_bf16 v[0:15], v[12:15], v[4:7], 0
	s_setprio 0
	ds_read_b128 v[148:151], v69 offset:36928
	ds_read_b128 v[152:155], v69 offset:41536
	ds_read_b128 v[156:159], v66 offset:64
	ds_read_b128 v[160:163], v66 offset:4672
	s_setprio 1
	v_mfma_f32_32x32x16_bf16 v[48:63], v[140:143], v[132:135], v[48:63]
	v_mfma_f32_32x32x16_bf16 v[16:31], v[140:143], v[136:139], v[16:31]
	s_waitcnt lgkmcnt(4)
	v_mfma_f32_32x32x16_bf16 v[32:47], v[144:147], v[132:135], v[32:47]
	v_mfma_f32_32x32x16_bf16 v[0:15], v[144:147], v[136:139], v[0:15]
	s_setprio 0
	ds_read_b128 v[132:135], v69 offset:36960
	ds_read_b128 v[136:139], v69 offset:41568
	ds_read_b128 v[140:143], v66 offset:96
	ds_read_b128 v[144:147], v66 offset:4704
	s_setprio 1
	s_waitcnt lgkmcnt(5)
	v_mfma_f32_32x32x16_bf16 v[48:63], v[156:159], v[148:151], v[48:63]
	v_mfma_f32_32x32x16_bf16 v[16:31], v[156:159], v[152:155], v[16:31]
	s_waitcnt lgkmcnt(4)
	v_mfma_f32_32x32x16_bf16 v[32:47], v[160:163], v[148:151], v[32:47]
	v_mfma_f32_32x32x16_bf16 v[0:15], v[160:163], v[152:155], v[0:15]
	s_setprio 0
	s_setprio 1
	s_waitcnt lgkmcnt(1)
	v_mfma_f32_32x32x16_bf16 v[48:63], v[140:143], v[132:135], v[48:63]
	v_mfma_f32_32x32x16_bf16 v[16:31], v[140:143], v[136:139], v[16:31]
	s_waitcnt lgkmcnt(0)
	v_mfma_f32_32x32x16_bf16 v[32:47], v[144:147], v[132:135], v[32:47]
	v_mfma_f32_32x32x16_bf16 v[0:15], v[144:147], v[136:139], v[0:15]
	s_setprio 0
	s_barrier
	global_load_dwordx4 v[132:135], v[74:75], off offset:512
	global_load_dwordx4 v[136:139], v[76:77], off offset:512
	global_load_dwordx4 v[140:143], v[70:71], off offset:512
	global_load_dwordx4 v[144:147], v[72:73], off offset:512
	global_load_dwordx4 v[148:151], v[78:79], off offset:512
	global_load_dwordx4 v[152:155], v[80:81], off offset:512
	ds_write_b128 v68, v[92:95]
	ds_write_b128 v68, v[84:87] offset:9216
	ds_write_b128 v68, v[88:91] offset:18432
	ds_write_b128 v68, v[100:103] offset:27648
	ds_write_b128 v68, v[96:99] offset:36864
	s_waitcnt vmcnt(12)
	ds_write_b128 v68, v[104:107] offset:46080
	v_add_u32_e32 v67, 0x12000, v66
	ds_read_b128 v[84:87], v64 offset:36864
	ds_read_b128 v[88:91], v64 offset:36896
	ds_read_b128 v[92:95], v64 offset:41472
	ds_read_b128 v[96:99], v64 offset:41504
	ds_read_b128 v[100:103], v67
	ds_read_b128 v[104:107], v67 offset:32
	ds_read_b128 v[156:159], v67 offset:4608
	ds_read_b128 v[160:163], v67 offset:4640
	s_setprio 1
	s_waitcnt lgkmcnt(3)
	v_mfma_f32_32x32x16_bf16 v[48:63], v[100:103], v[84:87], v[48:63]
	v_mfma_f32_32x32x16_bf16 v[16:31], v[100:103], v[92:95], v[16:31]
	s_waitcnt lgkmcnt(1)
	v_mfma_f32_32x32x16_bf16 v[32:47], v[156:159], v[84:87], v[32:47]
	v_mfma_f32_32x32x16_bf16 v[0:15], v[156:159], v[92:95], v[0:15]
	s_setprio 0
	ds_read_b128 v[84:87], v64 offset:36928
	ds_read_b128 v[92:95], v64 offset:41536
	ds_read_b128 v[100:103], v67 offset:64
	ds_read_b128 v[156:159], v67 offset:4672
	s_setprio 1
	v_mfma_f32_32x32x16_bf16 v[48:63], v[104:107], v[88:91], v[48:63]
	v_mfma_f32_32x32x16_bf16 v[16:31], v[104:107], v[96:99], v[16:31]
	s_waitcnt lgkmcnt(4)
	v_mfma_f32_32x32x16_bf16 v[32:47], v[160:163], v[88:91], v[32:47]
	v_mfma_f32_32x32x16_bf16 v[0:15], v[160:163], v[96:99], v[0:15]
	s_setprio 0
	ds_read_b128 v[88:91], v64 offset:36960
	ds_read_b128 v[96:99], v64 offset:41568
	ds_read_b128 v[104:107], v67 offset:96
	ds_read_b128 v[160:163], v67 offset:4704
	s_setprio 1
	s_waitcnt lgkmcnt(5)
	v_mfma_f32_32x32x16_bf16 v[48:63], v[100:103], v[84:87], v[48:63]
	v_mfma_f32_32x32x16_bf16 v[16:31], v[100:103], v[92:95], v[16:31]
	s_waitcnt lgkmcnt(4)
	v_mfma_f32_32x32x16_bf16 v[32:47], v[156:159], v[84:87], v[32:47]
	v_mfma_f32_32x32x16_bf16 v[0:15], v[156:159], v[92:95], v[0:15]
	s_setprio 0
	s_setprio 1
	s_waitcnt lgkmcnt(1)
	v_mfma_f32_32x32x16_bf16 v[48:63], v[104:107], v[88:91], v[48:63]
	v_mfma_f32_32x32x16_bf16 v[16:31], v[104:107], v[96:99], v[16:31]
	s_waitcnt lgkmcnt(0)
	v_mfma_f32_32x32x16_bf16 v[32:47], v[160:163], v[88:91], v[32:47]
	v_mfma_f32_32x32x16_bf16 v[0:15], v[160:163], v[96:99], v[0:15]
	s_setprio 0
	s_barrier
	global_load_dwordx4 v[84:87], v[74:75], off offset:640
	global_load_dwordx4 v[88:91], v[76:77], off offset:640
	global_load_dwordx4 v[92:95], v[70:71], off offset:640
	global_load_dwordx4 v[96:99], v[72:73], off offset:640
	global_load_dwordx4 v[100:103], v[78:79], off offset:640
	global_load_dwordx4 v[104:107], v[80:81], off offset:640
	s_waitcnt vmcnt(15)
	ds_write_b128 v83, v[116:119]
	ds_write_b128 v83, v[108:111] offset:9216
	ds_write_b128 v83, v[112:115] offset:18432
	s_waitcnt vmcnt(13)
	ds_write_b128 v83, v[124:127] offset:27648
	ds_write_b128 v83, v[120:123] offset:36864
	s_waitcnt vmcnt(12)
	ds_write_b128 v83, v[128:131] offset:46080
	ds_read_b128 v[108:111], v69 offset:36864
	ds_read_b128 v[112:115], v69 offset:36896
	ds_read_b128 v[116:119], v69 offset:41472
	ds_read_b128 v[120:123], v69 offset:41504
	ds_read_b128 v[124:127], v66
	ds_read_b128 v[128:131], v66 offset:32
	ds_read_b128 v[156:159], v66 offset:4608
	ds_read_b128 v[160:163], v66 offset:4640
	s_setprio 1
	s_waitcnt lgkmcnt(3)
	v_mfma_f32_32x32x16_bf16 v[48:63], v[124:127], v[108:111], v[48:63]
	v_mfma_f32_32x32x16_bf16 v[16:31], v[124:127], v[116:119], v[16:31]
	s_waitcnt lgkmcnt(1)
	v_mfma_f32_32x32x16_bf16 v[32:47], v[156:159], v[108:111], v[32:47]
	v_mfma_f32_32x32x16_bf16 v[0:15], v[156:159], v[116:119], v[0:15]
	s_setprio 0
	ds_read_b128 v[108:111], v69 offset:36928
	ds_read_b128 v[116:119], v69 offset:41536
	ds_read_b128 v[124:127], v66 offset:64
	ds_read_b128 v[156:159], v66 offset:4672
	s_setprio 1
	v_mfma_f32_32x32x16_bf16 v[48:63], v[128:131], v[112:115], v[48:63]
	v_mfma_f32_32x32x16_bf16 v[16:31], v[128:131], v[120:123], v[16:31]
	s_waitcnt lgkmcnt(4)
	v_mfma_f32_32x32x16_bf16 v[32:47], v[160:163], v[112:115], v[32:47]
	v_mfma_f32_32x32x16_bf16 v[0:15], v[160:163], v[120:123], v[0:15]
	s_setprio 0
	ds_read_b128 v[112:115], v69 offset:36960
	ds_read_b128 v[120:123], v69 offset:41568
	ds_read_b128 v[128:131], v66 offset:96
	ds_read_b128 v[160:163], v66 offset:4704
	s_setprio 1
	s_waitcnt lgkmcnt(5)
	v_mfma_f32_32x32x16_bf16 v[48:63], v[124:127], v[108:111], v[48:63]
	v_mfma_f32_32x32x16_bf16 v[16:31], v[124:127], v[116:119], v[16:31]
	s_waitcnt lgkmcnt(4)
	v_mfma_f32_32x32x16_bf16 v[32:47], v[156:159], v[108:111], v[32:47]
	v_mfma_f32_32x32x16_bf16 v[0:15], v[156:159], v[116:119], v[0:15]
	s_setprio 0
	s_setprio 1
	s_waitcnt lgkmcnt(1)
	v_mfma_f32_32x32x16_bf16 v[48:63], v[128:131], v[112:115], v[48:63]
	v_mfma_f32_32x32x16_bf16 v[16:31], v[128:131], v[120:123], v[16:31]
	s_waitcnt lgkmcnt(0)
	v_mfma_f32_32x32x16_bf16 v[32:47], v[160:163], v[112:115], v[32:47]
	v_mfma_f32_32x32x16_bf16 v[0:15], v[160:163], v[120:123], v[0:15]
	s_setprio 0
	s_barrier
	global_load_dwordx4 v[108:111], v[74:75], off offset:768
	global_load_dwordx4 v[112:115], v[76:77], off offset:768
	global_load_dwordx4 v[116:119], v[70:71], off offset:768
	global_load_dwordx4 v[120:123], v[72:73], off offset:768
	global_load_dwordx4 v[124:127], v[78:79], off offset:768
	global_load_dwordx4 v[128:131], v[80:81], off offset:768
	s_waitcnt vmcnt(15)
	ds_write_b128 v68, v[140:143]
	ds_write_b128 v68, v[132:135] offset:9216
	ds_write_b128 v68, v[136:139] offset:18432
	s_waitcnt vmcnt(13)
	ds_write_b128 v68, v[148:151] offset:27648
	ds_write_b128 v68, v[144:147] offset:36864
	s_waitcnt vmcnt(12)
	ds_write_b128 v68, v[152:155] offset:46080
	ds_read_b128 v[132:135], v64 offset:36864
	ds_read_b128 v[136:139], v64 offset:36896
	ds_read_b128 v[140:143], v64 offset:41472
	ds_read_b128 v[144:147], v64 offset:41504
	ds_read_b128 v[148:151], v67
	ds_read_b128 v[152:155], v67 offset:32
	ds_read_b128 v[156:159], v67 offset:4608
	ds_read_b128 v[160:163], v67 offset:4640
	s_setprio 1
	s_waitcnt lgkmcnt(3)
	v_mfma_f32_32x32x16_bf16 v[48:63], v[148:151], v[132:135], v[48:63]
	v_mfma_f32_32x32x16_bf16 v[16:31], v[148:151], v[140:143], v[16:31]
	s_waitcnt lgkmcnt(1)
	v_mfma_f32_32x32x16_bf16 v[32:47], v[156:159], v[132:135], v[32:47]
	v_mfma_f32_32x32x16_bf16 v[0:15], v[156:159], v[140:143], v[0:15]
	s_setprio 0
	ds_read_b128 v[132:135], v64 offset:36928
	ds_read_b128 v[140:143], v64 offset:41536
	ds_read_b128 v[148:151], v67 offset:64
	ds_read_b128 v[156:159], v67 offset:4672
	s_setprio 1
	v_mfma_f32_32x32x16_bf16 v[48:63], v[152:155], v[136:139], v[48:63]
	v_mfma_f32_32x32x16_bf16 v[16:31], v[152:155], v[144:147], v[16:31]
	s_waitcnt lgkmcnt(4)
	v_mfma_f32_32x32x16_bf16 v[32:47], v[160:163], v[136:139], v[32:47]
	v_mfma_f32_32x32x16_bf16 v[0:15], v[160:163], v[144:147], v[0:15]
	s_setprio 0
	ds_read_b128 v[136:139], v64 offset:36960
	ds_read_b128 v[144:147], v64 offset:41568
	ds_read_b128 v[152:155], v67 offset:96
	ds_read_b128 v[160:163], v67 offset:4704
	s_setprio 1
	s_waitcnt lgkmcnt(5)
	v_mfma_f32_32x32x16_bf16 v[48:63], v[148:151], v[132:135], v[48:63]
	v_mfma_f32_32x32x16_bf16 v[16:31], v[148:151], v[140:143], v[16:31]
	s_waitcnt lgkmcnt(4)
	v_mfma_f32_32x32x16_bf16 v[32:47], v[156:159], v[132:135], v[32:47]
	v_mfma_f32_32x32x16_bf16 v[0:15], v[156:159], v[140:143], v[0:15]
	s_setprio 0
	s_setprio 1
	s_waitcnt lgkmcnt(1)
	v_mfma_f32_32x32x16_bf16 v[48:63], v[152:155], v[136:139], v[48:63]
	v_mfma_f32_32x32x16_bf16 v[16:31], v[152:155], v[144:147], v[16:31]
	s_waitcnt lgkmcnt(0)
	v_mfma_f32_32x32x16_bf16 v[32:47], v[160:163], v[136:139], v[32:47]
	v_mfma_f32_32x32x16_bf16 v[0:15], v[160:163], v[144:147], v[0:15]
	s_setprio 0
	s_barrier
	global_load_dwordx4 v[132:135], v[74:75], off offset:896
	global_load_dwordx4 v[136:139], v[76:77], off offset:896
	global_load_dwordx4 v[140:143], v[70:71], off offset:896
	global_load_dwordx4 v[144:147], v[72:73], off offset:896
	global_load_dwordx4 v[148:151], v[78:79], off offset:896
	global_load_dwordx4 v[152:155], v[80:81], off offset:896
	s_waitcnt vmcnt(15)
	ds_write_b128 v83, v[92:95]
	ds_write_b128 v83, v[84:87] offset:9216
	ds_write_b128 v83, v[88:91] offset:18432
	s_waitcnt vmcnt(13)
	ds_write_b128 v83, v[100:103] offset:27648
	ds_write_b128 v83, v[96:99] offset:36864
	s_waitcnt vmcnt(12)
	ds_write_b128 v83, v[104:107] offset:46080
	ds_read_b128 v[84:87], v69 offset:36864
	ds_read_b128 v[88:91], v69 offset:36896
	ds_read_b128 v[92:95], v69 offset:41472
	ds_read_b128 v[96:99], v69 offset:41504
	ds_read_b128 v[100:103], v66
	ds_read_b128 v[104:107], v66 offset:32
	ds_read_b128 v[156:159], v66 offset:4608
	ds_read_b128 v[160:163], v66 offset:4640
	s_setprio 1
	s_waitcnt lgkmcnt(3)
	v_mfma_f32_32x32x16_bf16 v[48:63], v[100:103], v[84:87], v[48:63]
	v_mfma_f32_32x32x16_bf16 v[16:31], v[100:103], v[92:95], v[16:31]
	s_waitcnt lgkmcnt(1)
	v_mfma_f32_32x32x16_bf16 v[32:47], v[156:159], v[84:87], v[32:47]
	v_mfma_f32_32x32x16_bf16 v[0:15], v[156:159], v[92:95], v[0:15]
	s_setprio 0
	ds_read_b128 v[84:87], v69 offset:36928
	ds_read_b128 v[92:95], v69 offset:41536
	ds_read_b128 v[100:103], v66 offset:64
	ds_read_b128 v[156:159], v66 offset:4672
	s_setprio 1
	v_mfma_f32_32x32x16_bf16 v[48:63], v[104:107], v[88:91], v[48:63]
	v_mfma_f32_32x32x16_bf16 v[16:31], v[104:107], v[96:99], v[16:31]
	s_waitcnt lgkmcnt(4)
	v_mfma_f32_32x32x16_bf16 v[32:47], v[160:163], v[88:91], v[32:47]
	v_mfma_f32_32x32x16_bf16 v[0:15], v[160:163], v[96:99], v[0:15]
	s_setprio 0
	ds_read_b128 v[88:91], v69 offset:36960
	ds_read_b128 v[96:99], v69 offset:41568
	ds_read_b128 v[104:107], v66 offset:96
	ds_read_b128 v[160:163], v66 offset:4704
	s_setprio 1
	s_waitcnt lgkmcnt(5)
	v_mfma_f32_32x32x16_bf16 v[48:63], v[100:103], v[84:87], v[48:63]
	v_mfma_f32_32x32x16_bf16 v[16:31], v[100:103], v[92:95], v[16:31]
	s_waitcnt lgkmcnt(4)
	v_mfma_f32_32x32x16_bf16 v[32:47], v[156:159], v[84:87], v[32:47]
	v_mfma_f32_32x32x16_bf16 v[0:15], v[156:159], v[92:95], v[0:15]
	s_setprio 0
	s_setprio 1
	s_waitcnt lgkmcnt(1)
	v_mfma_f32_32x32x16_bf16 v[48:63], v[104:107], v[88:91], v[48:63]
	v_mfma_f32_32x32x16_bf16 v[16:31], v[104:107], v[96:99], v[16:31]
	s_waitcnt lgkmcnt(0)
	v_mfma_f32_32x32x16_bf16 v[32:47], v[160:163], v[88:91], v[32:47]
	v_mfma_f32_32x32x16_bf16 v[0:15], v[160:163], v[96:99], v[0:15]
	s_setprio 0
	s_barrier
	global_load_dwordx4 v[84:87], v[74:75], off offset:1024
	global_load_dwordx4 v[88:91], v[76:77], off offset:1024
	global_load_dwordx4 v[92:95], v[70:71], off offset:1024
	global_load_dwordx4 v[96:99], v[72:73], off offset:1024
	global_load_dwordx4 v[100:103], v[78:79], off offset:1024
	global_load_dwordx4 v[104:107], v[80:81], off offset:1024
	s_waitcnt vmcnt(15)
	ds_write_b128 v68, v[116:119]
	ds_write_b128 v68, v[108:111] offset:9216
	ds_write_b128 v68, v[112:115] offset:18432
	s_waitcnt vmcnt(13)
	ds_write_b128 v68, v[124:127] offset:27648
	ds_write_b128 v68, v[120:123] offset:36864
	s_waitcnt vmcnt(12)
	ds_write_b128 v68, v[128:131] offset:46080
	ds_read_b128 v[108:111], v64 offset:36864
	ds_read_b128 v[112:115], v64 offset:36896
	ds_read_b128 v[116:119], v64 offset:41472
	ds_read_b128 v[120:123], v64 offset:41504
	ds_read_b128 v[124:127], v67
	ds_read_b128 v[128:131], v67 offset:32
	ds_read_b128 v[156:159], v67 offset:4608
	ds_read_b128 v[160:163], v67 offset:4640
	s_setprio 1
	s_waitcnt lgkmcnt(3)
	v_mfma_f32_32x32x16_bf16 v[48:63], v[124:127], v[108:111], v[48:63]
	v_mfma_f32_32x32x16_bf16 v[16:31], v[124:127], v[116:119], v[16:31]
	s_waitcnt lgkmcnt(1)
	v_mfma_f32_32x32x16_bf16 v[32:47], v[156:159], v[108:111], v[32:47]
	v_mfma_f32_32x32x16_bf16 v[0:15], v[156:159], v[116:119], v[0:15]
	s_setprio 0
	ds_read_b128 v[108:111], v64 offset:36928
	ds_read_b128 v[116:119], v64 offset:41536
	ds_read_b128 v[124:127], v67 offset:64
	ds_read_b128 v[156:159], v67 offset:4672
	s_setprio 1
	v_mfma_f32_32x32x16_bf16 v[48:63], v[128:131], v[112:115], v[48:63]
	v_mfma_f32_32x32x16_bf16 v[16:31], v[128:131], v[120:123], v[16:31]
	s_waitcnt lgkmcnt(4)
	v_mfma_f32_32x32x16_bf16 v[32:47], v[160:163], v[112:115], v[32:47]
	v_mfma_f32_32x32x16_bf16 v[0:15], v[160:163], v[120:123], v[0:15]
	s_setprio 0
	ds_read_b128 v[112:115], v64 offset:36960
	ds_read_b128 v[120:123], v64 offset:41568
	ds_read_b128 v[128:131], v67 offset:96
	ds_read_b128 v[160:163], v67 offset:4704
	s_setprio 1
	s_waitcnt lgkmcnt(5)
	v_mfma_f32_32x32x16_bf16 v[48:63], v[124:127], v[108:111], v[48:63]
	v_mfma_f32_32x32x16_bf16 v[16:31], v[124:127], v[116:119], v[16:31]
	s_waitcnt lgkmcnt(4)
	v_mfma_f32_32x32x16_bf16 v[32:47], v[156:159], v[108:111], v[32:47]
	v_mfma_f32_32x32x16_bf16 v[0:15], v[156:159], v[116:119], v[0:15]
	s_setprio 0
	s_setprio 1
	s_waitcnt lgkmcnt(1)
	v_mfma_f32_32x32x16_bf16 v[48:63], v[128:131], v[112:115], v[48:63]
	v_mfma_f32_32x32x16_bf16 v[16:31], v[128:131], v[120:123], v[16:31]
	s_waitcnt lgkmcnt(0)
	v_mfma_f32_32x32x16_bf16 v[32:47], v[160:163], v[112:115], v[32:47]
	v_mfma_f32_32x32x16_bf16 v[0:15], v[160:163], v[120:123], v[0:15]
	s_setprio 0
	s_barrier
	global_load_dwordx4 v[108:111], v[74:75], off offset:1152
	global_load_dwordx4 v[112:115], v[76:77], off offset:1152
	global_load_dwordx4 v[116:119], v[70:71], off offset:1152
	global_load_dwordx4 v[120:123], v[72:73], off offset:1152
	global_load_dwordx4 v[124:127], v[78:79], off offset:1152
	global_load_dwordx4 v[128:131], v[80:81], off offset:1152
	s_waitcnt vmcnt(15)
	ds_write_b128 v83, v[140:143]
	ds_write_b128 v83, v[132:135] offset:9216
	ds_write_b128 v83, v[136:139] offset:18432
	s_waitcnt vmcnt(13)
	ds_write_b128 v83, v[148:151] offset:27648
	ds_write_b128 v83, v[144:147] offset:36864
	s_waitcnt vmcnt(12)
	ds_write_b128 v83, v[152:155] offset:46080
	ds_read_b128 v[132:135], v69 offset:36864
	ds_read_b128 v[136:139], v69 offset:36896
	ds_read_b128 v[140:143], v69 offset:41472
	ds_read_b128 v[144:147], v69 offset:41504
	ds_read_b128 v[148:151], v66
	ds_read_b128 v[152:155], v66 offset:32
	ds_read_b128 v[156:159], v66 offset:4608
	ds_read_b128 v[160:163], v66 offset:4640
	s_setprio 1
	s_waitcnt lgkmcnt(3)
	v_mfma_f32_32x32x16_bf16 v[48:63], v[148:151], v[132:135], v[48:63]
	v_mfma_f32_32x32x16_bf16 v[16:31], v[148:151], v[140:143], v[16:31]
	s_waitcnt lgkmcnt(1)
	v_mfma_f32_32x32x16_bf16 v[32:47], v[156:159], v[132:135], v[32:47]
	v_mfma_f32_32x32x16_bf16 v[0:15], v[156:159], v[140:143], v[0:15]
	s_setprio 0
	ds_read_b128 v[132:135], v69 offset:36928
	ds_read_b128 v[140:143], v69 offset:41536
	ds_read_b128 v[148:151], v66 offset:64
	ds_read_b128 v[156:159], v66 offset:4672
	s_setprio 1
	v_mfma_f32_32x32x16_bf16 v[48:63], v[152:155], v[136:139], v[48:63]
	v_mfma_f32_32x32x16_bf16 v[16:31], v[152:155], v[144:147], v[16:31]
	s_waitcnt lgkmcnt(4)
	v_mfma_f32_32x32x16_bf16 v[32:47], v[160:163], v[136:139], v[32:47]
	v_mfma_f32_32x32x16_bf16 v[0:15], v[160:163], v[144:147], v[0:15]
	s_setprio 0
	ds_read_b128 v[136:139], v69 offset:36960
	ds_read_b128 v[144:147], v69 offset:41568
	ds_read_b128 v[152:155], v66 offset:96
	ds_read_b128 v[160:163], v66 offset:4704
	s_setprio 1
	s_waitcnt lgkmcnt(5)
	v_mfma_f32_32x32x16_bf16 v[48:63], v[148:151], v[132:135], v[48:63]
	v_mfma_f32_32x32x16_bf16 v[16:31], v[148:151], v[140:143], v[16:31]
	s_waitcnt lgkmcnt(4)
	v_mfma_f32_32x32x16_bf16 v[32:47], v[156:159], v[132:135], v[32:47]
	v_mfma_f32_32x32x16_bf16 v[0:15], v[156:159], v[140:143], v[0:15]
	s_setprio 0
	s_setprio 1
	s_waitcnt lgkmcnt(1)
	v_mfma_f32_32x32x16_bf16 v[48:63], v[152:155], v[136:139], v[48:63]
	v_mfma_f32_32x32x16_bf16 v[16:31], v[152:155], v[144:147], v[16:31]
	s_waitcnt lgkmcnt(0)
	v_mfma_f32_32x32x16_bf16 v[32:47], v[160:163], v[136:139], v[32:47]
	v_mfma_f32_32x32x16_bf16 v[0:15], v[160:163], v[144:147], v[0:15]
	s_setprio 0
	s_barrier
	global_load_dwordx4 v[132:135], v[74:75], off offset:1280
	global_load_dwordx4 v[136:139], v[76:77], off offset:1280
	global_load_dwordx4 v[140:143], v[70:71], off offset:1280
	global_load_dwordx4 v[144:147], v[72:73], off offset:1280
	global_load_dwordx4 v[148:151], v[78:79], off offset:1280
	global_load_dwordx4 v[152:155], v[80:81], off offset:1280
	s_waitcnt vmcnt(15)
	ds_write_b128 v68, v[92:95]
	ds_write_b128 v68, v[84:87] offset:9216
	ds_write_b128 v68, v[88:91] offset:18432
	s_waitcnt vmcnt(13)
	ds_write_b128 v68, v[100:103] offset:27648
	ds_write_b128 v68, v[96:99] offset:36864
	s_waitcnt vmcnt(12)
	ds_write_b128 v68, v[104:107] offset:46080
	ds_read_b128 v[84:87], v64 offset:36864
	ds_read_b128 v[88:91], v64 offset:36896
	ds_read_b128 v[92:95], v64 offset:41472
	ds_read_b128 v[96:99], v64 offset:41504
	ds_read_b128 v[100:103], v67
	ds_read_b128 v[104:107], v67 offset:32
	ds_read_b128 v[156:159], v67 offset:4608
	ds_read_b128 v[160:163], v67 offset:4640
	s_setprio 1
	s_waitcnt lgkmcnt(3)
	v_mfma_f32_32x32x16_bf16 v[48:63], v[100:103], v[84:87], v[48:63]
	v_mfma_f32_32x32x16_bf16 v[16:31], v[100:103], v[92:95], v[16:31]
	s_waitcnt lgkmcnt(1)
	v_mfma_f32_32x32x16_bf16 v[32:47], v[156:159], v[84:87], v[32:47]
	v_mfma_f32_32x32x16_bf16 v[0:15], v[156:159], v[92:95], v[0:15]
	s_setprio 0
	ds_read_b128 v[84:87], v64 offset:36928
	ds_read_b128 v[92:95], v64 offset:41536
	ds_read_b128 v[100:103], v67 offset:64
	ds_read_b128 v[156:159], v67 offset:4672
	s_setprio 1
	v_mfma_f32_32x32x16_bf16 v[48:63], v[104:107], v[88:91], v[48:63]
	v_mfma_f32_32x32x16_bf16 v[16:31], v[104:107], v[96:99], v[16:31]
	s_waitcnt lgkmcnt(4)
	v_mfma_f32_32x32x16_bf16 v[32:47], v[160:163], v[88:91], v[32:47]
	v_mfma_f32_32x32x16_bf16 v[0:15], v[160:163], v[96:99], v[0:15]
	s_setprio 0
	ds_read_b128 v[88:91], v64 offset:36960
	ds_read_b128 v[96:99], v64 offset:41568
	ds_read_b128 v[104:107], v67 offset:96
	ds_read_b128 v[160:163], v67 offset:4704
	s_setprio 1
	s_waitcnt lgkmcnt(5)
	v_mfma_f32_32x32x16_bf16 v[48:63], v[100:103], v[84:87], v[48:63]
	v_mfma_f32_32x32x16_bf16 v[16:31], v[100:103], v[92:95], v[16:31]
	s_waitcnt lgkmcnt(4)
	v_mfma_f32_32x32x16_bf16 v[32:47], v[156:159], v[84:87], v[32:47]
	v_mfma_f32_32x32x16_bf16 v[0:15], v[156:159], v[92:95], v[0:15]
	s_setprio 0
	s_setprio 1
	s_waitcnt lgkmcnt(1)
	v_mfma_f32_32x32x16_bf16 v[48:63], v[104:107], v[88:91], v[48:63]
	v_mfma_f32_32x32x16_bf16 v[16:31], v[104:107], v[96:99], v[16:31]
	s_waitcnt lgkmcnt(0)
	v_mfma_f32_32x32x16_bf16 v[32:47], v[160:163], v[88:91], v[32:47]
	v_mfma_f32_32x32x16_bf16 v[0:15], v[160:163], v[96:99], v[0:15]
	s_setprio 0
	s_barrier
	global_load_dwordx4 v[84:87], v[74:75], off offset:1408
	global_load_dwordx4 v[88:91], v[76:77], off offset:1408
	global_load_dwordx4 v[92:95], v[70:71], off offset:1408
	global_load_dwordx4 v[96:99], v[72:73], off offset:1408
	global_load_dwordx4 v[100:103], v[78:79], off offset:1408
	global_load_dwordx4 v[104:107], v[80:81], off offset:1408
	s_waitcnt vmcnt(15)
	ds_write_b128 v83, v[116:119]
	ds_write_b128 v83, v[108:111] offset:9216
	ds_write_b128 v83, v[112:115] offset:18432
	s_waitcnt vmcnt(13)
	ds_write_b128 v83, v[124:127] offset:27648
	ds_write_b128 v83, v[120:123] offset:36864
	s_waitcnt vmcnt(12)
	ds_write_b128 v83, v[128:131] offset:46080
	ds_read_b128 v[108:111], v69 offset:36864
	ds_read_b128 v[112:115], v69 offset:36896
	ds_read_b128 v[116:119], v69 offset:41472
	ds_read_b128 v[120:123], v69 offset:41504
	ds_read_b128 v[124:127], v66
	ds_read_b128 v[128:131], v66 offset:32
	ds_read_b128 v[156:159], v66 offset:4608
	ds_read_b128 v[160:163], v66 offset:4640
	s_setprio 1
	s_waitcnt lgkmcnt(3)
	v_mfma_f32_32x32x16_bf16 v[48:63], v[124:127], v[108:111], v[48:63]
	v_mfma_f32_32x32x16_bf16 v[16:31], v[124:127], v[116:119], v[16:31]
	s_waitcnt lgkmcnt(1)
	v_mfma_f32_32x32x16_bf16 v[32:47], v[156:159], v[108:111], v[32:47]
	v_mfma_f32_32x32x16_bf16 v[0:15], v[156:159], v[116:119], v[0:15]
	s_setprio 0
	ds_read_b128 v[108:111], v69 offset:36928
	ds_read_b128 v[116:119], v69 offset:41536
	ds_read_b128 v[124:127], v66 offset:64
	ds_read_b128 v[156:159], v66 offset:4672
	s_setprio 1
	v_mfma_f32_32x32x16_bf16 v[48:63], v[128:131], v[112:115], v[48:63]
	v_mfma_f32_32x32x16_bf16 v[16:31], v[128:131], v[120:123], v[16:31]
	s_waitcnt lgkmcnt(4)
	v_mfma_f32_32x32x16_bf16 v[32:47], v[160:163], v[112:115], v[32:47]
	v_mfma_f32_32x32x16_bf16 v[0:15], v[160:163], v[120:123], v[0:15]
	s_setprio 0
	ds_read_b128 v[112:115], v69 offset:36960
	ds_read_b128 v[120:123], v69 offset:41568
	ds_read_b128 v[128:131], v66 offset:96
	ds_read_b128 v[160:163], v66 offset:4704
	s_setprio 1
	s_waitcnt lgkmcnt(5)
	v_mfma_f32_32x32x16_bf16 v[48:63], v[124:127], v[108:111], v[48:63]
	v_mfma_f32_32x32x16_bf16 v[16:31], v[124:127], v[116:119], v[16:31]
	s_waitcnt lgkmcnt(4)
	v_mfma_f32_32x32x16_bf16 v[32:47], v[156:159], v[108:111], v[32:47]
	v_mfma_f32_32x32x16_bf16 v[0:15], v[156:159], v[116:119], v[0:15]
	s_setprio 0
	s_setprio 1
	s_waitcnt lgkmcnt(1)
	v_mfma_f32_32x32x16_bf16 v[48:63], v[128:131], v[112:115], v[48:63]
	v_mfma_f32_32x32x16_bf16 v[16:31], v[128:131], v[120:123], v[16:31]
	s_waitcnt lgkmcnt(0)
	v_mfma_f32_32x32x16_bf16 v[32:47], v[160:163], v[112:115], v[32:47]
	v_mfma_f32_32x32x16_bf16 v[0:15], v[160:163], v[120:123], v[0:15]
	s_setprio 0
	s_barrier
	global_load_dwordx4 v[108:111], v[74:75], off offset:1536
	global_load_dwordx4 v[112:115], v[76:77], off offset:1536
	global_load_dwordx4 v[116:119], v[70:71], off offset:1536
	global_load_dwordx4 v[120:123], v[72:73], off offset:1536
	global_load_dwordx4 v[124:127], v[78:79], off offset:1536
	global_load_dwordx4 v[128:131], v[80:81], off offset:1536
	s_waitcnt vmcnt(15)
	ds_write_b128 v68, v[140:143]
	ds_write_b128 v68, v[132:135] offset:9216
	ds_write_b128 v68, v[136:139] offset:18432
	s_waitcnt vmcnt(13)
	ds_write_b128 v68, v[148:151] offset:27648
	ds_write_b128 v68, v[144:147] offset:36864
	s_waitcnt vmcnt(12)
	ds_write_b128 v68, v[152:155] offset:46080
	ds_read_b128 v[132:135], v64 offset:36864
	ds_read_b128 v[136:139], v64 offset:36896
	ds_read_b128 v[140:143], v64 offset:41472
	ds_read_b128 v[144:147], v64 offset:41504
	ds_read_b128 v[148:151], v67
	ds_read_b128 v[152:155], v67 offset:32
	ds_read_b128 v[156:159], v67 offset:4608
	ds_read_b128 v[160:163], v67 offset:4640
	s_setprio 1
	s_waitcnt lgkmcnt(3)
	v_mfma_f32_32x32x16_bf16 v[48:63], v[148:151], v[132:135], v[48:63]
	v_mfma_f32_32x32x16_bf16 v[16:31], v[148:151], v[140:143], v[16:31]
	s_waitcnt lgkmcnt(1)
	v_mfma_f32_32x32x16_bf16 v[32:47], v[156:159], v[132:135], v[32:47]
	v_mfma_f32_32x32x16_bf16 v[0:15], v[156:159], v[140:143], v[0:15]
	s_setprio 0
	ds_read_b128 v[132:135], v64 offset:36928
	ds_read_b128 v[140:143], v64 offset:41536
	ds_read_b128 v[148:151], v67 offset:64
	ds_read_b128 v[156:159], v67 offset:4672
	s_setprio 1
	v_mfma_f32_32x32x16_bf16 v[48:63], v[152:155], v[136:139], v[48:63]
	v_mfma_f32_32x32x16_bf16 v[16:31], v[152:155], v[144:147], v[16:31]
	s_waitcnt lgkmcnt(4)
	v_mfma_f32_32x32x16_bf16 v[32:47], v[160:163], v[136:139], v[32:47]
	v_mfma_f32_32x32x16_bf16 v[0:15], v[160:163], v[144:147], v[0:15]
	s_setprio 0
	ds_read_b128 v[136:139], v64 offset:36960
	ds_read_b128 v[144:147], v64 offset:41568
	ds_read_b128 v[152:155], v67 offset:96
	ds_read_b128 v[160:163], v67 offset:4704
	s_setprio 1
	s_waitcnt lgkmcnt(5)
	v_mfma_f32_32x32x16_bf16 v[48:63], v[148:151], v[132:135], v[48:63]
	v_mfma_f32_32x32x16_bf16 v[16:31], v[148:151], v[140:143], v[16:31]
	s_waitcnt lgkmcnt(4)
	v_mfma_f32_32x32x16_bf16 v[32:47], v[156:159], v[132:135], v[32:47]
	v_mfma_f32_32x32x16_bf16 v[0:15], v[156:159], v[140:143], v[0:15]
	s_setprio 0
	s_setprio 1
	s_waitcnt lgkmcnt(1)
	v_mfma_f32_32x32x16_bf16 v[48:63], v[152:155], v[136:139], v[48:63]
	v_mfma_f32_32x32x16_bf16 v[16:31], v[152:155], v[144:147], v[16:31]
	s_waitcnt lgkmcnt(0)
	v_mfma_f32_32x32x16_bf16 v[32:47], v[160:163], v[136:139], v[32:47]
	v_mfma_f32_32x32x16_bf16 v[0:15], v[160:163], v[144:147], v[0:15]
	s_setprio 0
	s_barrier
	global_load_dwordx4 v[132:135], v[74:75], off offset:1664
	global_load_dwordx4 v[136:139], v[76:77], off offset:1664
	global_load_dwordx4 v[140:143], v[70:71], off offset:1664
	global_load_dwordx4 v[144:147], v[72:73], off offset:1664
	global_load_dwordx4 v[148:151], v[78:79], off offset:1664
	global_load_dwordx4 v[152:155], v[80:81], off offset:1664
	s_waitcnt vmcnt(15)
	ds_write_b128 v83, v[92:95]
	ds_write_b128 v83, v[84:87] offset:9216
	ds_write_b128 v83, v[88:91] offset:18432
	s_waitcnt vmcnt(13)
	ds_write_b128 v83, v[100:103] offset:27648
	ds_write_b128 v83, v[96:99] offset:36864
	s_waitcnt vmcnt(12)
	ds_write_b128 v83, v[104:107] offset:46080
	ds_read_b128 v[84:87], v69 offset:36864
	ds_read_b128 v[88:91], v69 offset:36896
	ds_read_b128 v[92:95], v69 offset:41472
	ds_read_b128 v[96:99], v69 offset:41504
	ds_read_b128 v[100:103], v66
	ds_read_b128 v[104:107], v66 offset:32
	ds_read_b128 v[156:159], v66 offset:4608
	ds_read_b128 v[160:163], v66 offset:4640
	s_setprio 1
	s_waitcnt lgkmcnt(3)
	v_mfma_f32_32x32x16_bf16 v[48:63], v[100:103], v[84:87], v[48:63]
	v_mfma_f32_32x32x16_bf16 v[16:31], v[100:103], v[92:95], v[16:31]
	s_waitcnt lgkmcnt(1)
	v_mfma_f32_32x32x16_bf16 v[32:47], v[156:159], v[84:87], v[32:47]
	v_mfma_f32_32x32x16_bf16 v[0:15], v[156:159], v[92:95], v[0:15]
	s_setprio 0
	ds_read_b128 v[84:87], v69 offset:36928
	ds_read_b128 v[92:95], v69 offset:41536
	ds_read_b128 v[100:103], v66 offset:64
	ds_read_b128 v[156:159], v66 offset:4672
	s_setprio 1
	v_mfma_f32_32x32x16_bf16 v[48:63], v[104:107], v[88:91], v[48:63]
	v_mfma_f32_32x32x16_bf16 v[16:31], v[104:107], v[96:99], v[16:31]
	s_waitcnt lgkmcnt(4)
	v_mfma_f32_32x32x16_bf16 v[32:47], v[160:163], v[88:91], v[32:47]
	v_mfma_f32_32x32x16_bf16 v[0:15], v[160:163], v[96:99], v[0:15]
	s_setprio 0
	ds_read_b128 v[88:91], v69 offset:36960
	ds_read_b128 v[96:99], v69 offset:41568
	ds_read_b128 v[104:107], v66 offset:96
	ds_read_b128 v[160:163], v66 offset:4704
	s_setprio 1
	s_waitcnt lgkmcnt(5)
	v_mfma_f32_32x32x16_bf16 v[48:63], v[100:103], v[84:87], v[48:63]
	v_mfma_f32_32x32x16_bf16 v[16:31], v[100:103], v[92:95], v[16:31]
	s_waitcnt lgkmcnt(4)
	v_mfma_f32_32x32x16_bf16 v[32:47], v[156:159], v[84:87], v[32:47]
	v_mfma_f32_32x32x16_bf16 v[0:15], v[156:159], v[92:95], v[0:15]
	s_setprio 0
	s_setprio 1
	s_waitcnt lgkmcnt(1)
	v_mfma_f32_32x32x16_bf16 v[48:63], v[104:107], v[88:91], v[48:63]
	v_mfma_f32_32x32x16_bf16 v[16:31], v[104:107], v[96:99], v[16:31]
	s_waitcnt lgkmcnt(0)
	v_mfma_f32_32x32x16_bf16 v[32:47], v[160:163], v[88:91], v[32:47]
	v_mfma_f32_32x32x16_bf16 v[0:15], v[160:163], v[96:99], v[0:15]
	s_setprio 0
	s_barrier
	global_load_dwordx4 v[84:87], v[74:75], off offset:1792
	global_load_dwordx4 v[88:91], v[76:77], off offset:1792
	global_load_dwordx4 v[92:95], v[70:71], off offset:1792
	global_load_dwordx4 v[96:99], v[72:73], off offset:1792
	global_load_dwordx4 v[100:103], v[78:79], off offset:1792
	global_load_dwordx4 v[104:107], v[80:81], off offset:1792
	s_waitcnt vmcnt(15)
	ds_write_b128 v68, v[116:119]
	ds_write_b128 v68, v[108:111] offset:9216
	ds_write_b128 v68, v[112:115] offset:18432
	s_waitcnt vmcnt(13)
	ds_write_b128 v68, v[124:127] offset:27648
	ds_write_b128 v68, v[120:123] offset:36864
	s_waitcnt vmcnt(12)
	ds_write_b128 v68, v[128:131] offset:46080
	ds_read_b128 v[108:111], v64 offset:36864
	ds_read_b128 v[112:115], v64 offset:36896
	ds_read_b128 v[116:119], v64 offset:41472
	ds_read_b128 v[120:123], v64 offset:41504
	ds_read_b128 v[124:127], v67
	ds_read_b128 v[128:131], v67 offset:32
	ds_read_b128 v[156:159], v67 offset:4608
	ds_read_b128 v[160:163], v67 offset:4640
	s_setprio 1
	s_waitcnt lgkmcnt(3)
	v_mfma_f32_32x32x16_bf16 v[48:63], v[124:127], v[108:111], v[48:63]
	v_mfma_f32_32x32x16_bf16 v[16:31], v[124:127], v[116:119], v[16:31]
	s_waitcnt lgkmcnt(1)
	v_mfma_f32_32x32x16_bf16 v[32:47], v[156:159], v[108:111], v[32:47]
	v_mfma_f32_32x32x16_bf16 v[0:15], v[156:159], v[116:119], v[0:15]
	s_setprio 0
	ds_read_b128 v[108:111], v64 offset:36928
	ds_read_b128 v[116:119], v64 offset:41536
	ds_read_b128 v[124:127], v67 offset:64
	ds_read_b128 v[156:159], v67 offset:4672
	s_setprio 1
	v_mfma_f32_32x32x16_bf16 v[48:63], v[128:131], v[112:115], v[48:63]
	v_mfma_f32_32x32x16_bf16 v[16:31], v[128:131], v[120:123], v[16:31]
	s_waitcnt lgkmcnt(4)
	v_mfma_f32_32x32x16_bf16 v[32:47], v[160:163], v[112:115], v[32:47]
	v_mfma_f32_32x32x16_bf16 v[0:15], v[160:163], v[120:123], v[0:15]
	s_setprio 0
	ds_read_b128 v[112:115], v64 offset:36960
	ds_read_b128 v[120:123], v64 offset:41568
	ds_read_b128 v[128:131], v67 offset:96
	ds_read_b128 v[160:163], v67 offset:4704
	s_setprio 1
	s_waitcnt lgkmcnt(5)
	v_mfma_f32_32x32x16_bf16 v[48:63], v[124:127], v[108:111], v[48:63]
	v_mfma_f32_32x32x16_bf16 v[16:31], v[124:127], v[116:119], v[16:31]
	s_waitcnt lgkmcnt(4)
	v_mfma_f32_32x32x16_bf16 v[32:47], v[156:159], v[108:111], v[32:47]
	v_mfma_f32_32x32x16_bf16 v[0:15], v[156:159], v[116:119], v[0:15]
	s_setprio 0
	s_setprio 1
	s_waitcnt lgkmcnt(1)
	v_mfma_f32_32x32x16_bf16 v[48:63], v[128:131], v[112:115], v[48:63]
	v_mfma_f32_32x32x16_bf16 v[16:31], v[128:131], v[120:123], v[16:31]
	s_waitcnt lgkmcnt(0)
	v_mfma_f32_32x32x16_bf16 v[32:47], v[160:163], v[112:115], v[32:47]
	v_mfma_f32_32x32x16_bf16 v[0:15], v[160:163], v[120:123], v[0:15]
	s_setprio 0
	s_barrier
	global_load_dwordx4 v[108:111], v[74:75], off offset:1920
	s_nop 0
	global_load_dwordx4 v[74:77], v[76:77], off offset:1920
	s_nop 0
	global_load_dwordx4 v[112:115], v[70:71], off offset:1920
	s_nop 0
	global_load_dwordx4 v[70:73], v[72:73], off offset:1920
	s_nop 0
	global_load_dwordx4 v[116:119], v[78:79], off offset:1920
	s_nop 0
	global_load_dwordx4 v[78:81], v[80:81], off offset:1920
	s_waitcnt vmcnt(15)
	ds_write_b128 v83, v[140:143]
	ds_write_b128 v83, v[132:135] offset:9216
	ds_write_b128 v83, v[136:139] offset:18432
	s_waitcnt vmcnt(13)
	ds_write_b128 v83, v[148:151] offset:27648
	ds_write_b128 v83, v[144:147] offset:36864
	s_waitcnt vmcnt(12)
	ds_write_b128 v83, v[152:155] offset:46080
	ds_read_b128 v[120:123], v69 offset:36864
	ds_read_b128 v[124:127], v69 offset:36896
	ds_read_b128 v[128:131], v69 offset:41472
	ds_read_b128 v[132:135], v69 offset:41504
	ds_read_b128 v[136:139], v66
	ds_read_b128 v[140:143], v66 offset:32
	ds_read_b128 v[144:147], v66 offset:4608
	ds_read_b128 v[148:151], v66 offset:4640
	s_setprio 1
	s_waitcnt lgkmcnt(3)
	v_mfma_f32_32x32x16_bf16 v[48:63], v[136:139], v[120:123], v[48:63]
	v_mfma_f32_32x32x16_bf16 v[16:31], v[136:139], v[128:131], v[16:31]
	s_waitcnt lgkmcnt(1)
	v_mfma_f32_32x32x16_bf16 v[32:47], v[144:147], v[120:123], v[32:47]
	v_mfma_f32_32x32x16_bf16 v[0:15], v[144:147], v[128:131], v[0:15]
	s_setprio 0
	ds_read_b128 v[120:123], v69 offset:36928
	ds_read_b128 v[128:131], v69 offset:41536
	ds_read_b128 v[136:139], v66 offset:64
	ds_read_b128 v[144:147], v66 offset:4672
	s_setprio 1
	v_mfma_f32_32x32x16_bf16 v[48:63], v[140:143], v[124:127], v[48:63]
	v_mfma_f32_32x32x16_bf16 v[16:31], v[140:143], v[132:135], v[16:31]
	s_waitcnt lgkmcnt(4)
	v_mfma_f32_32x32x16_bf16 v[32:47], v[148:151], v[124:127], v[32:47]
	v_mfma_f32_32x32x16_bf16 v[0:15], v[148:151], v[132:135], v[0:15]
	s_setprio 0
	ds_read_b128 v[124:127], v69 offset:36960
	ds_read_b128 v[132:135], v69 offset:41568
	ds_read_b128 v[140:143], v66 offset:96
	ds_read_b128 v[148:151], v66 offset:4704
	s_setprio 1
	s_waitcnt lgkmcnt(5)
	v_mfma_f32_32x32x16_bf16 v[48:63], v[136:139], v[120:123], v[48:63]
	v_mfma_f32_32x32x16_bf16 v[16:31], v[136:139], v[128:131], v[16:31]
	s_waitcnt lgkmcnt(4)
	v_mfma_f32_32x32x16_bf16 v[32:47], v[144:147], v[120:123], v[32:47]
	v_mfma_f32_32x32x16_bf16 v[0:15], v[144:147], v[128:131], v[0:15]
	s_setprio 0
	s_setprio 1
	s_waitcnt lgkmcnt(1)
	v_mfma_f32_32x32x16_bf16 v[48:63], v[140:143], v[124:127], v[48:63]
	v_mfma_f32_32x32x16_bf16 v[16:31], v[140:143], v[132:135], v[16:31]
	s_waitcnt lgkmcnt(0)
	v_mfma_f32_32x32x16_bf16 v[32:47], v[148:151], v[124:127], v[32:47]
	v_mfma_f32_32x32x16_bf16 v[0:15], v[148:151], v[132:135], v[0:15]
	s_setprio 0
	s_barrier
	s_waitcnt vmcnt(9)
	ds_write_b128 v68, v[92:95]
	ds_write_b128 v68, v[84:87] offset:9216
	ds_write_b128 v68, v[88:91] offset:18432
	s_waitcnt vmcnt(7)
	ds_write_b128 v68, v[100:103] offset:27648
	ds_write_b128 v68, v[96:99] offset:36864
	s_waitcnt vmcnt(6)
	ds_write_b128 v68, v[104:107] offset:46080
	ds_read_b128 v[84:87], v64 offset:36864
	ds_read_b128 v[88:91], v64 offset:36896
	ds_read_b128 v[92:95], v64 offset:41472
	ds_read_b128 v[96:99], v64 offset:41504
	ds_read_b128 v[100:103], v67
	ds_read_b128 v[104:107], v67 offset:32
	ds_read_b128 v[120:123], v67 offset:4608
	ds_read_b128 v[124:127], v67 offset:4640
	s_setprio 1
	s_waitcnt lgkmcnt(3)
	v_mfma_f32_32x32x16_bf16 v[48:63], v[100:103], v[84:87], v[48:63]
	v_mfma_f32_32x32x16_bf16 v[16:31], v[100:103], v[92:95], v[16:31]
	s_waitcnt lgkmcnt(1)
	v_mfma_f32_32x32x16_bf16 v[32:47], v[120:123], v[84:87], v[32:47]
	v_mfma_f32_32x32x16_bf16 v[0:15], v[120:123], v[92:95], v[0:15]
	s_setprio 0
	ds_read_b128 v[84:87], v64 offset:36928
	ds_read_b128 v[92:95], v64 offset:41536
	ds_read_b128 v[100:103], v67 offset:64
	ds_read_b128 v[120:123], v67 offset:4672
	s_setprio 1
	v_mfma_f32_32x32x16_bf16 v[48:63], v[104:107], v[88:91], v[48:63]
	v_mfma_f32_32x32x16_bf16 v[16:31], v[104:107], v[96:99], v[16:31]
	s_waitcnt lgkmcnt(4)
	v_mfma_f32_32x32x16_bf16 v[32:47], v[124:127], v[88:91], v[32:47]
	v_mfma_f32_32x32x16_bf16 v[0:15], v[124:127], v[96:99], v[0:15]
	s_setprio 0
	ds_read_b128 v[88:91], v64 offset:36960
	ds_read_b128 v[96:99], v64 offset:41568
	ds_read_b128 v[104:107], v67 offset:96
	ds_read_b128 v[124:127], v67 offset:4704
	s_setprio 1
	s_waitcnt lgkmcnt(5)
	v_mfma_f32_32x32x16_bf16 v[48:63], v[100:103], v[84:87], v[48:63]
	v_mfma_f32_32x32x16_bf16 v[16:31], v[100:103], v[92:95], v[16:31]
	s_waitcnt lgkmcnt(4)
	v_mfma_f32_32x32x16_bf16 v[32:47], v[120:123], v[84:87], v[32:47]
	v_mfma_f32_32x32x16_bf16 v[0:15], v[120:123], v[92:95], v[0:15]
	s_setprio 0
	s_setprio 1
	s_waitcnt lgkmcnt(1)
	v_mfma_f32_32x32x16_bf16 v[48:63], v[104:107], v[88:91], v[48:63]
	v_mfma_f32_32x32x16_bf16 v[16:31], v[104:107], v[96:99], v[16:31]
	s_waitcnt lgkmcnt(0)
	v_mfma_f32_32x32x16_bf16 v[32:47], v[124:127], v[88:91], v[32:47]
	v_mfma_f32_32x32x16_bf16 v[0:15], v[124:127], v[96:99], v[0:15]
	s_setprio 0
	s_barrier
	s_waitcnt vmcnt(3)
	ds_write_b128 v83, v[112:115]
	ds_write_b128 v83, v[108:111] offset:9216
	ds_write_b128 v83, v[74:77] offset:18432
	s_waitcnt vmcnt(1)
	ds_write_b128 v83, v[116:119] offset:27648
	ds_write_b128 v83, v[70:73] offset:36864
	s_waitcnt vmcnt(0)
	ds_write_b128 v83, v[78:81] offset:46080
	ds_read_b128 v[70:73], v69 offset:36864
	ds_read_b128 v[74:77], v69 offset:36896
	ds_read_b128 v[78:81], v69 offset:41472
	ds_read_b128 v[84:87], v69 offset:41504
	ds_read_b128 v[88:91], v66
	ds_read_b128 v[92:95], v66 offset:32
	ds_read_b128 v[96:99], v66 offset:4608
	ds_read_b128 v[100:103], v66 offset:4640
	s_setprio 1
	s_waitcnt lgkmcnt(3)
	v_mfma_f32_32x32x16_bf16 v[48:63], v[88:91], v[70:73], v[48:63]
	v_mfma_f32_32x32x16_bf16 v[16:31], v[88:91], v[78:81], v[16:31]
	s_waitcnt lgkmcnt(1)
	v_mfma_f32_32x32x16_bf16 v[32:47], v[96:99], v[70:73], v[32:47]
	v_mfma_f32_32x32x16_bf16 v[0:15], v[96:99], v[78:81], v[0:15]
	s_setprio 0
	ds_read_b128 v[70:73], v69 offset:36928
	ds_read_b128 v[78:81], v69 offset:41536
	ds_read_b128 v[88:91], v66 offset:64
	ds_read_b128 v[96:99], v66 offset:4672
	s_setprio 1
	v_mfma_f32_32x32x16_bf16 v[48:63], v[92:95], v[74:77], v[48:63]
	v_mfma_f32_32x32x16_bf16 v[16:31], v[92:95], v[84:87], v[16:31]
	s_waitcnt lgkmcnt(4)
	v_mfma_f32_32x32x16_bf16 v[32:47], v[100:103], v[74:77], v[32:47]
	v_mfma_f32_32x32x16_bf16 v[0:15], v[100:103], v[84:87], v[0:15]
	s_setprio 0
	ds_read_b128 v[74:77], v69 offset:36960
	ds_read_b128 v[84:87], v69 offset:41568
	ds_read_b128 v[92:95], v66 offset:96
	ds_read_b128 v[100:103], v66 offset:4704
	s_setprio 1
	s_waitcnt lgkmcnt(5)
	v_mfma_f32_32x32x16_bf16 v[48:63], v[88:91], v[70:73], v[48:63]
	v_mfma_f32_32x32x16_bf16 v[16:31], v[88:91], v[78:81], v[16:31]
	s_waitcnt lgkmcnt(4)
	v_mfma_f32_32x32x16_bf16 v[32:47], v[96:99], v[70:73], v[32:47]
	v_mfma_f32_32x32x16_bf16 v[0:15], v[96:99], v[78:81], v[0:15]
	s_setprio 0
	s_setprio 1
	s_waitcnt lgkmcnt(1)
	v_mfma_f32_32x32x16_bf16 v[48:63], v[92:95], v[74:77], v[48:63]
	v_mfma_f32_32x32x16_bf16 v[16:31], v[92:95], v[84:87], v[16:31]
	s_waitcnt lgkmcnt(0)
	v_mfma_f32_32x32x16_bf16 v[32:47], v[100:103], v[74:77], v[32:47]
	v_mfma_f32_32x32x16_bf16 v[0:15], v[100:103], v[84:87], v[0:15]
	s_setprio 0
	s_barrier
	ds_read_b128 v[68:71], v64 offset:36864
	ds_read_b128 v[72:75], v64 offset:36896
	ds_read_b128 v[76:79], v64 offset:41472
	ds_read_b128 v[84:87], v64 offset:41504
	ds_read_b128 v[88:91], v67
	ds_read_b128 v[92:95], v67 offset:32
	ds_read_b128 v[96:99], v67 offset:4608
	ds_read_b128 v[100:103], v67 offset:4640
	s_setprio 1
	s_waitcnt lgkmcnt(3)
	v_mfma_f32_32x32x16_bf16 v[48:63], v[88:91], v[68:71], v[48:63]
	v_mfma_f32_32x32x16_bf16 v[16:31], v[88:91], v[76:79], v[16:31]
	s_waitcnt lgkmcnt(1)
	v_mfma_f32_32x32x16_bf16 v[32:47], v[96:99], v[68:71], v[32:47]
	v_mfma_f32_32x32x16_bf16 v[0:15], v[96:99], v[76:79], v[0:15]
	s_setprio 0
	ds_read_b128 v[68:71], v64 offset:36928
	ds_read_b128 v[76:79], v64 offset:41536
	ds_read_b128 v[88:91], v67 offset:64
	ds_read_b128 v[96:99], v67 offset:4672
	s_setprio 1
	v_mfma_f32_32x32x16_bf16 v[48:63], v[92:95], v[72:75], v[48:63]
	v_mfma_f32_32x32x16_bf16 v[16:31], v[92:95], v[84:87], v[16:31]
	s_waitcnt lgkmcnt(4)
	v_mfma_f32_32x32x16_bf16 v[32:47], v[100:103], v[72:75], v[32:47]
	v_mfma_f32_32x32x16_bf16 v[0:15], v[100:103], v[84:87], v[0:15]
	s_setprio 0
	ds_read_b128 v[72:75], v64 offset:36960
	ds_read_b128 v[84:87], v64 offset:41568
	ds_read_b128 v[92:95], v67 offset:96
	ds_read_b128 v[100:103], v67 offset:4704
	s_setprio 1
	s_waitcnt lgkmcnt(5)
	v_mfma_f32_32x32x16_bf16 v[48:63], v[88:91], v[68:71], v[48:63]
	v_mfma_f32_32x32x16_bf16 v[16:31], v[88:91], v[76:79], v[16:31]
	s_waitcnt lgkmcnt(4)
	v_mfma_f32_32x32x16_bf16 v[32:47], v[96:99], v[68:71], v[32:47]
	v_mfma_f32_32x32x16_bf16 v[0:15], v[96:99], v[76:79], v[0:15]
	s_setprio 0
	s_setprio 1
	s_waitcnt lgkmcnt(1)
	v_mfma_f32_32x32x16_bf16 v[48:63], v[92:95], v[72:75], v[48:63]
	v_mfma_f32_32x32x16_bf16 v[16:31], v[92:95], v[84:87], v[16:31]
	s_waitcnt lgkmcnt(0)
	v_mfma_f32_32x32x16_bf16 v[32:47], v[100:103], v[72:75], v[32:47]
	v_mfma_f32_32x32x16_bf16 v[0:15], v[100:103], v[84:87], v[0:15]
	s_setprio 0
	s_add_i32 s5, s4, 0xffffe000
	s_lshr_b32 s5, s5, 12
	s_add_i32 s5, s5, 6
	s_cmp_gt_i32 s27, 63
	s_cselect_b32 s5, s5, 5
	v_lshrrev_b32_e32 v66, 1, v82
	s_mul_hi_u32 s27, s5, 0x3000
	s_mulk_i32 s5, 0x3000
	v_lshlrev_b32_e32 v67, 1, v82
	v_and_b32_e32 v66, 16, v66
	s_add_u32 s5, s96, s5
	v_and_b32_e32 v64, 0x5f, v82
	v_and_or_b32 v66, v67, s24, v66
	s_addc_u32 s27, s97, s27
	s_lshl_b64 s[6:7], s[6:7], 2
	v_mad_u32_u24 v64, v64, s25, v66
	s_add_u32 s28, s5, s6
	v_ashrrev_i32_e32 v78, 2, v82
	s_barrier
	ds_write_b128 v64, v[48:51]
	ds_write_b128 v64, v[52:55] offset:32
	ds_write_b128 v64, v[56:59] offset:64
	ds_write_b128 v64, v[60:63] offset:96
	ds_write_b128 v64, v[32:35] offset:128
	ds_write_b128 v64, v[36:39] offset:160
	ds_write_b128 v64, v[40:43] offset:192
	ds_write_b128 v64, v[44:47] offset:224
	ds_write_b128 v64, v[16:19] offset:33280
	ds_write_b128 v64, v[20:23] offset:33312
	ds_write_b128 v64, v[24:27] offset:33344
	ds_write_b128 v64, v[28:31] offset:33376
	ds_write_b128 v64, v[0:3] offset:33408
	ds_write_b128 v64, v[4:7] offset:33440
	ds_write_b128 v64, v[8:11] offset:33472
	ds_write_b128 v64, v[12:15] offset:33504
	s_addc_u32 s29, s27, s7
	v_lshlrev_b32_e32 v0, 4, v82
	v_and_b32_e32 v82, -16, v78
	s_add_u32 s6, s74, s6
	v_add_u32_e32 v16, s4, v82
	v_and_b32_e32 v64, 0x3f0, v0
	s_addc_u32 s7, s75, s7
	v_ashrrev_i32_e32 v17, 31, v16
	v_lshl_add_u64 v[14:15], s[6:7], 0, v[64:65]
	v_lshlrev_b64 v[2:3], 12, v[16:17]
	v_lshl_add_u64 v[4:5], v[14:15], 0, v[2:3]
	v_or_b32_e32 v2, 1, v16
	v_ashrrev_i32_e32 v3, 31, v2
	v_lshlrev_b64 v[2:3], 12, v[2:3]
	v_lshl_add_u64 v[6:7], v[14:15], 0, v[2:3]
	v_or_b32_e32 v2, 2, v16
	v_ashrrev_i32_e32 v3, 31, v2
	v_lshlrev_b64 v[2:3], 12, v[2:3]
	v_lshl_add_u64 v[8:9], v[14:15], 0, v[2:3]
	v_or_b32_e32 v2, 3, v16
	v_ashrrev_i32_e32 v3, 31, v2
	v_lshlrev_b64 v[2:3], 12, v[2:3]
	v_lshl_add_u64 v[0:1], s[28:29], 0, v[64:65]
	v_lshl_add_u64 v[10:11], v[14:15], 0, v[2:3]
	v_or_b32_e32 v2, 4, v16
	v_ashrrev_i32_e32 v3, 31, v2
	v_add_co_u32_e32 v0, vcc, s26, v0
	v_lshlrev_b64 v[2:3], 12, v[2:3]
	s_nop 0
	v_addc_co_u32_e32 v1, vcc, 0, v1, vcc
	s_waitcnt lgkmcnt(0)
	s_barrier
	v_lshl_add_u64 v[12:13], v[14:15], 0, v[2:3]
	global_load_dwordx4 v[0:3], v[0:1], off
	s_nop 0
	global_load_dwordx4 v[20:23], v[4:5], off
	v_or_b32_e32 v28, 6, v16
	global_load_dwordx4 v[24:27], v[6:7], off
	v_ashrrev_i32_e32 v29, 31, v28
	v_lshlrev_b64 v[32:33], 12, v[28:29]
	global_load_dwordx4 v[28:31], v[8:9], off
	v_or_b32_e32 v36, 7, v16
	v_ashrrev_i32_e32 v37, 31, v36
	v_lshl_add_u64 v[90:91], v[14:15], 0, v[32:33]
	global_load_dwordx4 v[32:35], v[10:11], off
	v_lshlrev_b64 v[36:37], 12, v[36:37]
	v_lshl_add_u64 v[92:93], v[14:15], 0, v[36:37]
	global_load_dwordx4 v[36:39], v[12:13], off
	v_or_b32_e32 v18, 5, v16
	v_ashrrev_i32_e32 v19, 31, v18
	v_or_b32_e32 v40, 8, v16
	v_lshlrev_b64 v[18:19], 12, v[18:19]
	v_ashrrev_i32_e32 v41, 31, v40
	v_lshl_add_u64 v[18:19], v[14:15], 0, v[18:19]
	v_lshlrev_b64 v[40:41], 12, v[40:41]
	v_or_b32_e32 v44, 9, v16
	v_lshl_add_u64 v[94:95], v[14:15], 0, v[40:41]
	global_load_dwordx4 v[40:43], v[18:19], off
	v_ashrrev_i32_e32 v45, 31, v44
	v_lshlrev_b64 v[48:49], 12, v[44:45]
	global_load_dwordx4 v[44:47], v[90:91], off
	v_or_b32_e32 v52, 10, v16
	v_ashrrev_i32_e32 v53, 31, v52
	v_lshl_add_u64 v[96:97], v[14:15], 0, v[48:49]
	global_load_dwordx4 v[48:51], v[92:93], off
	v_lshlrev_b64 v[52:53], 12, v[52:53]
	v_lshl_add_u64 v[98:99], v[14:15], 0, v[52:53]
	global_load_dwordx4 v[52:55], v[94:95], off
	v_or_b32_e32 v56, 11, v16
	v_ashrrev_i32_e32 v57, 31, v56
	v_lshlrev_b64 v[56:57], 12, v[56:57]
	v_or_b32_e32 v60, 12, v16
	v_lshl_add_u64 v[100:101], v[14:15], 0, v[56:57]
	global_load_dwordx4 v[56:59], v[96:97], off
	v_ashrrev_i32_e32 v61, 31, v60
	v_lshlrev_b64 v[66:67], 12, v[60:61]
	global_load_dwordx4 v[60:63], v[98:99], off
	v_or_b32_e32 v70, 13, v16
	v_ashrrev_i32_e32 v71, 31, v70
	v_lshl_add_u64 v[102:103], v[14:15], 0, v[66:67]
	global_load_dwordx4 v[66:69], v[100:101], off
	v_lshlrev_b64 v[70:71], 12, v[70:71]
	v_or_b32_e32 v16, 14, v16
	v_lshl_add_u64 v[104:105], v[14:15], 0, v[70:71]
	global_load_dwordx4 v[70:73], v[102:103], off
	v_ashrrev_i32_e32 v17, 31, v16
	v_lshlrev_b64 v[16:17], 12, v[16:17]
	v_or_b32_e32 v86, 15, v78
	v_lshl_add_u64 v[106:107], v[14:15], 0, v[16:17]
	v_add_u32_e32 v16, s4, v86
	v_ashrrev_i32_e32 v17, 31, v16
	v_lshlrev_b64 v[16:17], 12, v[16:17]
	global_load_dwordx4 v[74:77], v[104:105], off
	global_load_dwordx4 v[78:81], v[106:107], off
	v_lshl_add_u64 v[108:109], v[14:15], 0, v[16:17]
	global_load_dwordx4 v[14:17], v[108:109], off
	v_mad_u64_u32 v[110:111], s[4:5], v82, s25, v[64:65]
	ds_read_b128 v[82:85], v110
	v_mad_u64_u32 v[112:113], s[4:5], v86, s25, v[64:65]
	ds_read_b128 v[86:89], v110 offset:1040
	s_add_i32 s2, s2, s62
	s_add_i32 s16, s16, s15
	s_cmpk_lt_i32 s2, 0x300
	s_waitcnt vmcnt(15) lgkmcnt(1)
	v_pk_fma_f32 v[20:21], v[0:1], v[82:83], v[20:21]
	v_pk_fma_f32 v[22:23], v[2:3], v[84:85], v[22:23]
	global_store_dwordx4 v[4:5], v[20:23], off
	ds_read_b128 v[20:23], v110 offset:2080
	s_waitcnt vmcnt(15) lgkmcnt(1)
	v_pk_fma_f32 v[24:25], v[0:1], v[86:87], v[24:25]
	v_pk_fma_f32 v[26:27], v[2:3], v[88:89], v[26:27]
	global_store_dwordx4 v[6:7], v[24:27], off
	ds_read_b128 v[4:7], v110 offset:3120
	s_waitcnt vmcnt(15) lgkmcnt(1)
	v_pk_fma_f32 v[20:21], v[0:1], v[20:21], v[28:29]
	v_pk_fma_f32 v[22:23], v[2:3], v[22:23], v[30:31]
	global_store_dwordx4 v[8:9], v[20:23], off
	ds_read_b128 v[20:23], v110 offset:4160
	s_waitcnt vmcnt(15) lgkmcnt(1)
	v_pk_fma_f32 v[4:5], v[0:1], v[4:5], v[32:33]
	v_pk_fma_f32 v[6:7], v[2:3], v[6:7], v[34:35]
	global_store_dwordx4 v[10:11], v[4:7], off
	ds_read_b128 v[4:7], v110 offset:5200
	s_waitcnt vmcnt(15) lgkmcnt(1)
	v_pk_fma_f32 v[8:9], v[0:1], v[20:21], v[36:37]
	v_pk_fma_f32 v[10:11], v[2:3], v[22:23], v[38:39]
	global_store_dwordx4 v[12:13], v[8:11], off
	ds_read_b128 v[8:11], v110 offset:6240
	s_waitcnt vmcnt(15) lgkmcnt(1)
	v_pk_fma_f32 v[4:5], v[0:1], v[4:5], v[40:41]
	v_pk_fma_f32 v[6:7], v[2:3], v[6:7], v[42:43]
	global_store_dwordx4 v[18:19], v[4:7], off
	ds_read_b128 v[4:7], v110 offset:7280
	s_waitcnt vmcnt(15) lgkmcnt(1)
	v_pk_fma_f32 v[8:9], v[0:1], v[8:9], v[44:45]
	v_pk_fma_f32 v[10:11], v[2:3], v[10:11], v[46:47]
	global_store_dwordx4 v[90:91], v[8:11], off
	ds_read_b128 v[8:11], v110 offset:8320
	s_waitcnt vmcnt(15) lgkmcnt(1)
	v_pk_fma_f32 v[4:5], v[0:1], v[4:5], v[48:49]
	v_pk_fma_f32 v[6:7], v[2:3], v[6:7], v[50:51]
	global_store_dwordx4 v[92:93], v[4:7], off
	ds_read_b128 v[4:7], v110 offset:9360
	s_waitcnt vmcnt(15) lgkmcnt(1)
	v_pk_fma_f32 v[8:9], v[0:1], v[8:9], v[52:53]
	v_pk_fma_f32 v[10:11], v[2:3], v[10:11], v[54:55]
	global_store_dwordx4 v[94:95], v[8:11], off
	ds_read_b128 v[8:11], v110 offset:10400
	s_waitcnt vmcnt(15) lgkmcnt(1)
	v_pk_fma_f32 v[4:5], v[0:1], v[4:5], v[56:57]
	v_pk_fma_f32 v[6:7], v[2:3], v[6:7], v[58:59]
	global_store_dwordx4 v[96:97], v[4:7], off
	ds_read_b128 v[4:7], v110 offset:11440
	s_waitcnt vmcnt(15) lgkmcnt(1)
	v_pk_fma_f32 v[8:9], v[0:1], v[8:9], v[60:61]
	v_pk_fma_f32 v[10:11], v[2:3], v[10:11], v[62:63]
	global_store_dwordx4 v[98:99], v[8:11], off
	ds_read_b128 v[8:11], v110 offset:12480
	s_waitcnt vmcnt(15) lgkmcnt(1)
	v_pk_fma_f32 v[4:5], v[0:1], v[4:5], v[66:67]
	v_pk_fma_f32 v[6:7], v[2:3], v[6:7], v[68:69]
	global_store_dwordx4 v[100:101], v[4:7], off
	ds_read_b128 v[4:7], v110 offset:13520
	s_waitcnt vmcnt(15) lgkmcnt(1)
	v_pk_fma_f32 v[8:9], v[0:1], v[8:9], v[70:71]
	v_pk_fma_f32 v[10:11], v[2:3], v[10:11], v[72:73]
	global_store_dwordx4 v[102:103], v[8:11], off
	ds_read_b128 v[8:11], v110 offset:14560
	ds_read_b128 v[18:21], v112
	s_waitcnt vmcnt(15) lgkmcnt(2)
	v_pk_fma_f32 v[4:5], v[0:1], v[4:5], v[74:75]
	v_pk_fma_f32 v[6:7], v[2:3], v[6:7], v[76:77]
	global_store_dwordx4 v[104:105], v[4:7], off
	s_waitcnt vmcnt(15) lgkmcnt(1)
	s_nop 0
	v_pk_fma_f32 v[4:5], v[0:1], v[8:9], v[78:79]
	v_pk_fma_f32 v[6:7], v[2:3], v[10:11], v[80:81]
	s_waitcnt vmcnt(14) lgkmcnt(0)
	v_pk_fma_f32 v[0:1], v[0:1], v[18:19], v[14:15]
	v_pk_fma_f32 v[2:3], v[2:3], v[20:21], v[16:17]
	global_store_dwordx4 v[106:107], v[4:7], off
	global_store_dwordx4 v[108:109], v[0:3], off
	s_cbranch_scc0 .LBB0_884
